# rename-safe N=1 + activation-major snake MFMA order: src1 (activation fragment) held for 4 consecutive MFMAs, one operand changes per step
# baseline (speedup 1.0000x reference)
; #define PG8_STAGE(bufoff, gbase, voff) do { _Pragma("unroll") for (int _i = 0; _i < 2; ++_i) \
;         asm volatile("s_mov_b32 m0, %2\n\ts_nop 0\n\tglobal_load_lds_dwordx4 %0, %1" :: "v"((voff)[_i]), "s"((const char*)(gbase)), "s"(ldsbase + (unsigned)(bufoff) + ldsw + (unsigned)_i * 8192u) : "memory", "m0"); } while (0)
; #define PG8_LDA(dst, b, h) do { _Pragma("unroll") for (int m = 0; m < 4; ++m) _Pragma("unroll") for (int k = 0; k < 2; ++k) dst[m][k] = *(const PG8_LAS bf16x8*)(lds + PG8_SA(b, h) + aoff + m * 2048 + k * 1024); } while (0)
; #define PG8_LDB(dst, b, h) do { _Pragma("unroll") for (int n = 0; n < 2; ++n) _Pragma("unroll") for (int k = 0; k < 2; ++k) dst[n][k] = *(const PG8_LAS bf16x8*)(lds + PG8_SB(b, h) + boff + n * 2048 + k * 1024); } while (0)
; #define PG8_MMA(ai, bj, At, Bt) do { __builtin_amdgcn_s_setprio(1); _Pragma("unroll") for (int m = 0; m < 4; ++m) _Pragma("unroll") for (int n = 0; n < 2; ++n) _Pragma("unroll") for (int k = 0; k < 2; ++k) \
;         acc[ai][bj][m][n] = __builtin_amdgcn_mfma_f32_16x16x32_bf16(Bt[n][k], At[m][k], acc[ai][bj][m][n], 0, 0, 0); __builtin_amdgcn_s_setprio(0); } while (0)
; template <class Epi, class Sched, bool ALIGN_EPI = false, bool SP2 = false>
; __device__ __forceinline__ void gemm_phase(PG8_LAS unsigned char* lds, const Gemm g, const Sched& S, const Epi& E) {
;     ...
;             const bool last = (t == nt - 2);
;             const char* a1 = cA + (size_t)(t + 1) * kstep;
;             const char* a2 = last ? nA : cA + (size_t)(t + 2) * kstep; const char* b2 = last ? nB : cB + (size_t)(t + 2) * kstep;
;             const char* a3 = a2 + kstep; const char* b3 = b2 + kstep;
;             if (last && has_next) S.a_ready(nxt);
;             if constexpr (epi_has_mid<Epi>::value) { if (t == Epi::MID_T) E.mid(acc, cur, wr, wc, fr, fq); }
;             if constexpr (SP2) {
;             PG8_LDB(B0, 0, 0); PG8_LDB(B1, 0, 1); PG8_SCHED; PG8_LDA(At, 0, 0); PG8_STAGE(PG8_SA(1, 1), a1 + hstep, voffA);
;             PG8_WAIT_V(8); PG8_WAIT_L(0); PG8_BAR; PG8_MMA(0, 0, At, B0); PG8_MMA(0, 1, At, B1); PG8_BAR; PG8_SCHED;
;             PG8_LDA(At, 0, 1); PG8_STAGE(PG8_SB(0, 0), b2, voffB); PG8_STAGE(PG8_SB(0, 1), b2 + hstep, voffB); PG8_STAGE(PG8_SA(0, 0), a2, voffA);
;             PG8_WAIT_V(8); PG8_WAIT_L(0); PG8_BAR; PG8_MMA(1, 0, At, B0); PG8_MMA(1, 1, At, B1); PG8_BAR; PG8_SCHED;
.LBB0_138:
	ds_read_b128 v[148:151], v142
	ds_read_b128 v[152:155], v142 offset:1024
	ds_read_b128 v[156:159], v142 offset:2048
	ds_read_b128 v[160:163], v142 offset:3072
	ds_read_b128 v[164:167], v143
	ds_read_b128 v[168:171], v143 offset:1024
	ds_read_b128 v[172:175], v143 offset:2048
	ds_read_b128 v[176:179], v143 offset:3072
	s_add_u32 s62, s66, 0x100
	s_addc_u32 s63, s67, 0
	s_cmp_eq_u32 s96, 60
	s_cselect_b32 s86, s92, s62
	s_cselect_b32 s87, s13, s63
	s_cselect_b32 s84, s93, s94
	s_cselect_b32 s85, s11, s95
	s_add_u32 s76, s86, 0x80
	s_addc_u32 s77, s87, 0
	ds_read_b128 v[180:183], v144
	ds_read_b128 v[184:187], v144 offset:1024
	ds_read_b128 v[188:191], v144 offset:2048
	ds_read_b128 v[192:195], v144 offset:3072
	ds_read_b128 v[196:199], v144 offset:4096
	ds_read_b128 v[200:203], v144 offset:5120
	ds_read_b128 v[204:207], v144 offset:6144
	ds_read_b128 v[208:211], v144 offset:7168
	s_add_u32 s66, s66, 0x100080
	s_addc_u32 s67, s67, 0
	s_mov_b32 m0, s83
	s_nop 0
	global_load_lds_dwordx4 v136, s[66:67]
	s_nop 0
	s_mov_b32 m0, s88
	s_nop 0
	global_load_lds_dwordx4 v138, s[66:67]
	s_waitcnt vmcnt(8)
	s_waitcnt lgkmcnt(0)
	s_barrier
	s_setprio 1
	s_waitcnt lgkmcnt(7)
	v_mfma_f32_16x16x32_bf16 v[126:129], v[148:151], v[180:183], v[126:129]
	v_mfma_f32_16x16x32_bf16 v[122:125], v[156:159], v[180:183], v[122:125]
	s_waitcnt lgkmcnt(5)
	v_mfma_f32_16x16x32_bf16 v[118:121], v[164:167], v[180:183], v[118:121]
	v_mfma_f32_16x16x32_bf16 v[114:117], v[172:175], v[180:183], v[114:117]
	s_waitcnt lgkmcnt(3)
	v_mfma_f32_16x16x32_bf16 v[98:101], v[172:175], v[188:191], v[98:101]
	v_mfma_f32_16x16x32_bf16 v[102:105], v[164:167], v[188:191], v[102:105]
	s_waitcnt lgkmcnt(1)
	v_mfma_f32_16x16x32_bf16 v[106:109], v[156:159], v[188:191], v[106:109]
	v_mfma_f32_16x16x32_bf16 v[110:113], v[148:151], v[188:191], v[110:113]
	v_mfma_f32_16x16x32_bf16 v[94:97], v[148:151], v[196:199], v[94:97]
	v_mfma_f32_16x16x32_bf16 v[90:93], v[156:159], v[196:199], v[90:93]
	v_mfma_f32_16x16x32_bf16 v[86:89], v[164:167], v[196:199], v[86:89]
	v_mfma_f32_16x16x32_bf16 v[82:85], v[172:175], v[196:199], v[82:85]
	v_mfma_f32_16x16x32_bf16 v[66:69], v[172:175], v[204:207], v[66:69]
	v_mfma_f32_16x16x32_bf16 v[70:73], v[164:167], v[204:207], v[70:73]
	s_waitcnt lgkmcnt(0)
	v_mfma_f32_16x16x32_bf16 v[74:77], v[156:159], v[204:207], v[74:77]
	v_mfma_f32_16x16x32_bf16 v[78:81], v[148:151], v[204:207], v[78:81]
	s_setprio 0
	s_setprio 1
	v_mfma_f32_16x16x32_bf16 v[126:129], v[152:155], v[184:187], v[126:129]
	v_mfma_f32_16x16x32_bf16 v[122:125], v[160:163], v[184:187], v[122:125]
	v_mfma_f32_16x16x32_bf16 v[118:121], v[168:171], v[184:187], v[118:121]
	v_mfma_f32_16x16x32_bf16 v[114:117], v[176:179], v[184:187], v[114:117]
	v_mfma_f32_16x16x32_bf16 v[98:101], v[176:179], v[192:195], v[98:101]
	v_mfma_f32_16x16x32_bf16 v[102:105], v[168:171], v[192:195], v[102:105]
	v_mfma_f32_16x16x32_bf16 v[106:109], v[160:163], v[192:195], v[106:109]
	v_mfma_f32_16x16x32_bf16 v[110:113], v[152:155], v[192:195], v[110:113]
	v_mfma_f32_16x16x32_bf16 v[94:97], v[152:155], v[200:203], v[94:97]
	v_mfma_f32_16x16x32_bf16 v[90:93], v[160:163], v[200:203], v[90:93]
	v_mfma_f32_16x16x32_bf16 v[86:89], v[168:171], v[200:203], v[86:89]
	v_mfma_f32_16x16x32_bf16 v[82:85], v[176:179], v[200:203], v[82:85]
	v_mfma_f32_16x16x32_bf16 v[66:69], v[176:179], v[208:211], v[66:69]
	v_mfma_f32_16x16x32_bf16 v[70:73], v[168:171], v[208:211], v[70:73]
	v_mfma_f32_16x16x32_bf16 v[74:77], v[160:163], v[208:211], v[74:77]
	s_setprio 2
	s_barrier
	v_mfma_f32_16x16x32_bf16 v[78:81], v[152:155], v[208:211], v[78:81]
	s_setprio 0
	ds_read_b128 v[180:183], v144 offset:16384
	ds_read_b128 v[184:187], v144 offset:17408
	ds_read_b128 v[188:191], v144 offset:18432
	ds_read_b128 v[192:195], v144 offset:19456
	ds_read_b128 v[196:199], v144 offset:20480
	ds_read_b128 v[200:203], v144 offset:21504
	ds_read_b128 v[204:207], v144 offset:22528
	ds_read_b128 v[252:255], v144 offset:23552
	s_mov_b32 m0, s55
	s_nop 0
	global_load_lds_dwordx4 v137, s[84:85]
	s_add_u32 s66, s84, 0x100000
	s_mov_b32 m0, s56
	s_nop 0
	global_load_lds_dwordx4 v139, s[84:85]
	s_addc_u32 s67, s85, 0
	s_mov_b32 m0, s57
	s_nop 0
	global_load_lds_dwordx4 v137, s[66:67]
	s_nop 0
	s_mov_b32 m0, s58
	s_nop 0
	global_load_lds_dwordx4 v139, s[66:67]
	s_nop 0
	s_mov_b32 m0, s54
	s_nop 0
	global_load_lds_dwordx4 v136, s[86:87]
	s_nop 0
	s_mov_b32 m0, s59
	s_nop 0
	global_load_lds_dwordx4 v138, s[86:87]
	s_waitcnt vmcnt(8)
	s_waitcnt lgkmcnt(0)
	s_barrier
; #define PG8_STAGE(bufoff, gbase, voff) do { _Pragma("unroll") for (int _i = 0; _i < 2; ++_i) \
;         asm volatile("s_mov_b32 m0, %2\n\ts_nop 0\n\tglobal_load_lds_dwordx4 %0, %1" :: "v"((voff)[_i]), "s"((const char*)(gbase)), "s"(ldsbase + (unsigned)(bufoff) + ldsw + (unsigned)_i * 8192u) : "memory", "m0"); } while (0)
; #define PG8_LDA(dst, b, h) do { _Pragma("unroll") for (int m = 0; m < 4; ++m) _Pragma("unroll") for (int k = 0; k < 2; ++k) dst[m][k] = *(const PG8_LAS bf16x8*)(lds + PG8_SA(b, h) + aoff + m * 2048 + k * 1024); } while (0)
; #define PG8_LDB(dst, b, h) do { _Pragma("unroll") for (int n = 0; n < 2; ++n) _Pragma("unroll") for (int k = 0; k < 2; ++k) dst[n][k] = *(const PG8_LAS bf16x8*)(lds + PG8_SB(b, h) + boff + n * 2048 + k * 1024); } while (0)
; #define PG8_MMA(ai, bj, At, Bt) do { __builtin_amdgcn_s_setprio(1); _Pragma("unroll") for (int m = 0; m < 4; ++m) _Pragma("unroll") for (int n = 0; n < 2; ++n) _Pragma("unroll") for (int k = 0; k < 2; ++k) \
;         acc[ai][bj][m][n] = __builtin_amdgcn_mfma_f32_16x16x32_bf16(Bt[n][k], At[m][k], acc[ai][bj][m][n], 0, 0, 0); __builtin_amdgcn_s_setprio(0); } while (0)
; #define PG8_WAIT_V(n) asm volatile("s_waitcnt vmcnt(" #n ")" ::: "memory")
; #define PG8_WAIT_L(n) asm volatile("s_waitcnt lgkmcnt(" #n ")" ::: "memory")
; #define PG8_BAR __builtin_amdgcn_s_barrier()
; #define PG8_SCHED __builtin_amdgcn_sched_barrier(0)
; template <class Epi, class Sched, bool ALIGN_EPI = false, bool SP2 = false>
; __device__ __forceinline__ void gemm_phase(PG8_LAS unsigned char* lds, const Gemm g, const Sched& S, const Epi& E) {
;     ...
;             PG8_WAIT_V(8); PG8_WAIT_L(0); PG8_BAR; PG8_MMA(1, 0, At, B0); PG8_MMA(1, 1, At, B1); PG8_BAR; PG8_SCHED;
;             PG8_LDB(B0, 1, 0); PG8_LDB(B1, 1, 1); PG8_SCHED; PG8_LDA(At, 1, 0); PG8_STAGE(PG8_SA(0, 1), a2 + hstep, voffA);
;             PG8_WAIT_V(8); PG8_WAIT_L(0); PG8_BAR; PG8_MMA(0, 0, At, B0); PG8_MMA(0, 1, At, B1); PG8_BAR; PG8_SCHED;
	s_setprio 1
	s_waitcnt lgkmcnt(7)
	v_mfma_f32_16x16x32_bf16 v[62:65], v[148:151], v[180:183], v[62:65]
	v_mfma_f32_16x16x32_bf16 v[58:61], v[156:159], v[180:183], v[58:61]
	s_waitcnt lgkmcnt(5)
	v_mfma_f32_16x16x32_bf16 v[54:57], v[164:167], v[180:183], v[54:57]
	v_mfma_f32_16x16x32_bf16 v[50:53], v[172:175], v[180:183], v[50:53]
	s_waitcnt lgkmcnt(3)
	v_mfma_f32_16x16x32_bf16 v[34:37], v[172:175], v[188:191], v[34:37]
	v_mfma_f32_16x16x32_bf16 v[38:41], v[164:167], v[188:191], v[38:41]
	s_waitcnt lgkmcnt(1)
	v_mfma_f32_16x16x32_bf16 v[42:45], v[156:159], v[188:191], v[42:45]
	v_mfma_f32_16x16x32_bf16 v[46:49], v[148:151], v[188:191], v[46:49]
	v_mfma_f32_16x16x32_bf16 v[30:33], v[148:151], v[196:199], v[30:33]
	v_mfma_f32_16x16x32_bf16 v[26:29], v[156:159], v[196:199], v[26:29]
	v_mfma_f32_16x16x32_bf16 v[22:25], v[164:167], v[196:199], v[22:25]
	v_mfma_f32_16x16x32_bf16 v[18:21], v[172:175], v[196:199], v[18:21]
	v_mfma_f32_16x16x32_bf16 v[2:5], v[172:175], v[204:207], v[2:5]
	v_mfma_f32_16x16x32_bf16 v[6:9], v[164:167], v[204:207], v[6:9]
	s_waitcnt lgkmcnt(0)
	v_mfma_f32_16x16x32_bf16 v[10:13], v[156:159], v[204:207], v[10:13]
	v_mfma_f32_16x16x32_bf16 v[14:17], v[148:151], v[204:207], v[14:17]
	s_setprio 0
	s_setprio 1
	v_mfma_f32_16x16x32_bf16 v[62:65], v[152:155], v[184:187], v[62:65]
	v_mfma_f32_16x16x32_bf16 v[58:61], v[160:163], v[184:187], v[58:61]
	v_mfma_f32_16x16x32_bf16 v[54:57], v[168:171], v[184:187], v[54:57]
	v_mfma_f32_16x16x32_bf16 v[50:53], v[176:179], v[184:187], v[50:53]
	v_mfma_f32_16x16x32_bf16 v[34:37], v[176:179], v[192:195], v[34:37]
	v_mfma_f32_16x16x32_bf16 v[38:41], v[168:171], v[192:195], v[38:41]
	v_mfma_f32_16x16x32_bf16 v[42:45], v[160:163], v[192:195], v[42:45]
	v_mfma_f32_16x16x32_bf16 v[46:49], v[152:155], v[192:195], v[46:49]
	v_mfma_f32_16x16x32_bf16 v[30:33], v[152:155], v[200:203], v[30:33]
	v_mfma_f32_16x16x32_bf16 v[26:29], v[160:163], v[200:203], v[26:29]
	v_mfma_f32_16x16x32_bf16 v[22:25], v[168:171], v[200:203], v[22:25]
	v_mfma_f32_16x16x32_bf16 v[18:21], v[176:179], v[200:203], v[18:21]
	v_mfma_f32_16x16x32_bf16 v[2:5], v[176:179], v[252:255], v[2:5]
	v_mfma_f32_16x16x32_bf16 v[6:9], v[168:171], v[252:255], v[6:9]
	v_mfma_f32_16x16x32_bf16 v[10:13], v[160:163], v[252:255], v[10:13]
	s_setprio 2
	s_barrier
	v_mfma_f32_16x16x32_bf16 v[14:17], v[152:155], v[252:255], v[14:17]
	s_setprio 0
	ds_read_b128 v[148:151], v145
	ds_read_b128 v[248:251], v145 offset:1024
	ds_read_b128 v[156:159], v145 offset:2048
	ds_read_b128 v[160:163], v145 offset:3072
	ds_read_b128 v[164:167], v146
	ds_read_b128 v[168:171], v146 offset:1024
	ds_read_b128 v[172:175], v146 offset:2048
	ds_read_b128 v[176:179], v146 offset:3072
	ds_read_b128 v[180:183], v144 offset:32768
	ds_read_b128 v[184:187], v144 offset:33792
	ds_read_b128 v[188:191], v144 offset:34816
	ds_read_b128 v[192:195], v144 offset:35840
	ds_read_b128 v[196:199], v144 offset:36864
	ds_read_b128 v[200:203], v144 offset:37888
	ds_read_b128 v[204:207], v144 offset:38912
	ds_read_b128 v[208:211], v144 offset:39936
	s_add_u32 s66, s86, 0x100000
	s_addc_u32 s67, s87, 0
	s_mov_b32 m0, s60
	s_nop 0
	global_load_lds_dwordx4 v136, s[66:67]
	s_nop 0
	s_mov_b32 m0, s61
	s_nop 0
	global_load_lds_dwordx4 v138, s[66:67]
	s_waitcnt vmcnt(8)
	s_waitcnt lgkmcnt(0)
	s_barrier
	s_setprio 1
	s_waitcnt lgkmcnt(7)
	v_mfma_f32_16x16x32_bf16 v[126:129], v[148:151], v[180:183], v[126:129]
	v_mfma_f32_16x16x32_bf16 v[122:125], v[156:159], v[180:183], v[122:125]
	s_waitcnt lgkmcnt(5)
	v_mfma_f32_16x16x32_bf16 v[118:121], v[164:167], v[180:183], v[118:121]
	v_mfma_f32_16x16x32_bf16 v[114:117], v[172:175], v[180:183], v[114:117]
	s_waitcnt lgkmcnt(3)
	v_mfma_f32_16x16x32_bf16 v[98:101], v[172:175], v[188:191], v[98:101]
	v_mfma_f32_16x16x32_bf16 v[102:105], v[164:167], v[188:191], v[102:105]
	s_waitcnt lgkmcnt(1)
	v_mfma_f32_16x16x32_bf16 v[106:109], v[156:159], v[188:191], v[106:109]
	v_mfma_f32_16x16x32_bf16 v[110:113], v[148:151], v[188:191], v[110:113]
	v_mfma_f32_16x16x32_bf16 v[94:97], v[148:151], v[196:199], v[94:97]
	v_mfma_f32_16x16x32_bf16 v[90:93], v[156:159], v[196:199], v[90:93]
	v_mfma_f32_16x16x32_bf16 v[86:89], v[164:167], v[196:199], v[86:89]
	v_mfma_f32_16x16x32_bf16 v[82:85], v[172:175], v[196:199], v[82:85]
	v_mfma_f32_16x16x32_bf16 v[66:69], v[172:175], v[204:207], v[66:69]
	v_mfma_f32_16x16x32_bf16 v[70:73], v[164:167], v[204:207], v[70:73]
	s_waitcnt lgkmcnt(0)
	v_mfma_f32_16x16x32_bf16 v[74:77], v[156:159], v[204:207], v[74:77]
	v_mfma_f32_16x16x32_bf16 v[78:81], v[148:151], v[204:207], v[78:81]
	s_setprio 0
	s_setprio 1
	v_mfma_f32_16x16x32_bf16 v[126:129], v[248:251], v[184:187], v[126:129]
	v_mfma_f32_16x16x32_bf16 v[122:125], v[160:163], v[184:187], v[122:125]
	v_mfma_f32_16x16x32_bf16 v[118:121], v[168:171], v[184:187], v[118:121]
	v_mfma_f32_16x16x32_bf16 v[114:117], v[176:179], v[184:187], v[114:117]
	v_mfma_f32_16x16x32_bf16 v[98:101], v[176:179], v[192:195], v[98:101]
	v_mfma_f32_16x16x32_bf16 v[102:105], v[168:171], v[192:195], v[102:105]
	v_mfma_f32_16x16x32_bf16 v[106:109], v[160:163], v[192:195], v[106:109]
	v_mfma_f32_16x16x32_bf16 v[110:113], v[248:251], v[192:195], v[110:113]
	v_mfma_f32_16x16x32_bf16 v[94:97], v[248:251], v[200:203], v[94:97]
	v_mfma_f32_16x16x32_bf16 v[90:93], v[160:163], v[200:203], v[90:93]
	v_mfma_f32_16x16x32_bf16 v[86:89], v[168:171], v[200:203], v[86:89]
	v_mfma_f32_16x16x32_bf16 v[82:85], v[176:179], v[200:203], v[82:85]
	v_mfma_f32_16x16x32_bf16 v[66:69], v[176:179], v[208:211], v[66:69]
	v_mfma_f32_16x16x32_bf16 v[70:73], v[168:171], v[208:211], v[70:73]
	v_mfma_f32_16x16x32_bf16 v[74:77], v[160:163], v[208:211], v[74:77]
	s_setprio 2
	s_barrier
; __device__ __forceinline__ unsigned cvt_pk_bf16(float lo, float hi) { unsigned r; asm volatile("v_cvt_pk_bf16_f32 %0, %1, %2" : "=v"(r) : "v"(lo), "v"(hi)); return r; }
; __device__ __forceinline__ float silu_f(float x) { return x * sigmoid_f(x); }
; #define PG8_STAGE(bufoff, gbase, voff) do { _Pragma("unroll") for (int _i = 0; _i < 2; ++_i) \
;         asm volatile("s_mov_b32 m0, %2\n\ts_nop 0\n\tglobal_load_lds_dwordx4 %0, %1" :: "v"((voff)[_i]), "s"((const char*)(gbase)), "s"(ldsbase + (unsigned)(bufoff) + ldsw + (unsigned)_i * 8192u) : "memory", "m0"); } while (0)
; #define PG8_LDA(dst, b, h) do { _Pragma("unroll") for (int m = 0; m < 4; ++m) _Pragma("unroll") for (int k = 0; k < 2; ++k) dst[m][k] = *(const PG8_LAS bf16x8*)(lds + PG8_SA(b, h) + aoff + m * 2048 + k * 1024); } while (0)
; #define PG8_WAIT_V(n) asm volatile("s_waitcnt vmcnt(" #n ")" ::: "memory")
; #define PG8_WAIT_L(n) asm volatile("s_waitcnt lgkmcnt(" #n ")" ::: "memory")
; #define PG8_BAR __builtin_amdgcn_s_barrier()
;     __device__ __forceinline__ void operator()(const f32x4 (&acc)[2][2][4][2], const Unit& u, int wr, int wc, int fr, int fq) const {
;         const int row0 = u.pm * BM + wr * 64 + fr, col0 = u.pn * HALF + wc * 32 + 8 * fq;
; #pragma unroll
;         for (int ai = 0; ai < 2; ++ai)
; #pragma unroll
;             for (int m = 0; m < 4; ++m) { bf16_t* rowp = O + (size_t)(row0 + ai * HALF + m * 16) * ldc + col0;
;                 const f32x4 g0 = acc[ai][0][m][0], g1 = acc[ai][0][m][1], u0 = acc[ai][1][m][0], u1 = acc[ai][1][m][1];
;                 f32x4 v0, v1;
; #pragma unroll
;                 for (int j = 0; j < 4; ++j) { v0[j] = silu_f(g0[j]) * u0[j]; v1[j] = silu_f(g1[j]) * u1[j]; }
;                 u32x4 w; w.x = cvt_pk_bf16(v0[0], v0[1]); w.y = cvt_pk_bf16(v0[2], v0[3]); w.z = cvt_pk_bf16(v1[0], v1[1]); w.w = cvt_pk_bf16(v1[2], v1[3]);
;                 *(u32x4*)rowp = w; }
; template <class Epi, class Sched, bool ALIGN_EPI = false, bool SP2 = false>
; __device__ __forceinline__ void gemm_phase(PG8_LAS unsigned char* lds, const Gemm g, const Sched& S, const Epi& E) {
;     ...
;             PG8_LDA(At, 1, 1); PG8_STAGE(PG8_SB(1, 0), b3, voffB); PG8_STAGE(PG8_SB(1, 1), b3 + hstep, voffB); PG8_STAGE(PG8_SA(1, 0), a3, voffA);
;             PG8_WAIT_V(8); PG8_WAIT_L(0); PG8_BAR; PG8_MMA(1, 0, At, B0); PG8_MMA(1, 1, At, B1); PG8_BAR; PG8_SCHED;
	v_mfma_f32_16x16x32_bf16 v[78:81], v[248:251], v[208:211], v[78:81]
	s_setprio 0
	ds_read_b128 v[180:183], v144 offset:49152
	ds_read_b128 v[184:187], v144 offset:50176
	ds_read_b128 v[188:191], v144 offset:51200
	ds_read_b128 v[192:195], v144 offset:52224
	ds_read_b128 v[196:199], v144 offset:53248
	ds_read_b128 v[200:203], v144 offset:54272
	ds_read_b128 v[204:207], v144 offset:55296
	ds_read_b128 v[252:255], v144 offset:56320
	s_add_u32 s66, s84, 0x80
	s_addc_u32 s67, s85, 0
	s_mov_b32 m0, s64
	s_nop 0
	global_load_lds_dwordx4 v137, s[66:67]
	s_nop 0
	s_mov_b32 m0, s65
	s_nop 0
	global_load_lds_dwordx4 v139, s[66:67]
	s_add_u32 s66, s84, 0x100080
	s_addc_u32 s67, s85, 0
	s_mov_b32 m0, s70
	s_nop 0
	global_load_lds_dwordx4 v137, s[66:67]
	s_nop 0
	s_mov_b32 m0, s71
	s_nop 0
	global_load_lds_dwordx4 v139, s[66:67]
	s_nop 0
	s_mov_b32 m0, s68
	s_nop 0
	global_load_lds_dwordx4 v136, s[76:77]
	s_nop 0
	s_mov_b32 m0, s69
	s_nop 0
	global_load_lds_dwordx4 v138, s[76:77]
	s_waitcnt vmcnt(8)
	s_waitcnt lgkmcnt(0)
	s_barrier
	s_setprio 1
	s_waitcnt lgkmcnt(7)
	v_mfma_f32_16x16x32_bf16 v[62:65], v[148:151], v[180:183], v[62:65]
	v_mfma_f32_16x16x32_bf16 v[58:61], v[156:159], v[180:183], v[58:61]
	s_waitcnt lgkmcnt(5)
	v_mfma_f32_16x16x32_bf16 v[54:57], v[164:167], v[180:183], v[54:57]
	v_mfma_f32_16x16x32_bf16 v[50:53], v[172:175], v[180:183], v[50:53]
	s_waitcnt lgkmcnt(3)
	v_mfma_f32_16x16x32_bf16 v[34:37], v[172:175], v[188:191], v[34:37]
	v_mfma_f32_16x16x32_bf16 v[38:41], v[164:167], v[188:191], v[38:41]
	s_waitcnt lgkmcnt(1)
	v_mfma_f32_16x16x32_bf16 v[42:45], v[156:159], v[188:191], v[42:45]
	v_mfma_f32_16x16x32_bf16 v[46:49], v[148:151], v[188:191], v[46:49]
	v_mfma_f32_16x16x32_bf16 v[30:33], v[148:151], v[196:199], v[30:33]
	v_mfma_f32_16x16x32_bf16 v[26:29], v[156:159], v[196:199], v[26:29]
	v_mfma_f32_16x16x32_bf16 v[22:25], v[164:167], v[196:199], v[22:25]
	v_mfma_f32_16x16x32_bf16 v[18:21], v[172:175], v[196:199], v[18:21]
	v_mfma_f32_16x16x32_bf16 v[2:5], v[172:175], v[204:207], v[2:5]
	v_mfma_f32_16x16x32_bf16 v[6:9], v[164:167], v[204:207], v[6:9]
	s_waitcnt lgkmcnt(0)
	v_mfma_f32_16x16x32_bf16 v[10:13], v[156:159], v[204:207], v[10:13]
	v_mfma_f32_16x16x32_bf16 v[14:17], v[148:151], v[204:207], v[14:17]
	s_setprio 0
	s_setprio 1
	v_mfma_f32_16x16x32_bf16 v[62:65], v[248:251], v[184:187], v[62:65]
	v_mfma_f32_16x16x32_bf16 v[58:61], v[160:163], v[184:187], v[58:61]
	v_mfma_f32_16x16x32_bf16 v[54:57], v[168:171], v[184:187], v[54:57]
	v_mfma_f32_16x16x32_bf16 v[50:53], v[176:179], v[184:187], v[50:53]
	v_mfma_f32_16x16x32_bf16 v[34:37], v[176:179], v[192:195], v[34:37]
	v_mfma_f32_16x16x32_bf16 v[38:41], v[168:171], v[192:195], v[38:41]
	v_mfma_f32_16x16x32_bf16 v[42:45], v[160:163], v[192:195], v[42:45]
	v_mfma_f32_16x16x32_bf16 v[46:49], v[248:251], v[192:195], v[46:49]
	v_mfma_f32_16x16x32_bf16 v[30:33], v[248:251], v[200:203], v[30:33]
	v_mfma_f32_16x16x32_bf16 v[26:29], v[160:163], v[200:203], v[26:29]
	v_mfma_f32_16x16x32_bf16 v[22:25], v[168:171], v[200:203], v[22:25]
	v_mfma_f32_16x16x32_bf16 v[18:21], v[176:179], v[200:203], v[18:21]
	v_mfma_f32_16x16x32_bf16 v[2:5], v[176:179], v[252:255], v[2:5]
	v_mfma_f32_16x16x32_bf16 v[6:9], v[168:171], v[252:255], v[6:9]
	v_mfma_f32_16x16x32_bf16 v[10:13], v[160:163], v[252:255], v[10:13]
	s_setprio 2
	s_barrier
	v_mfma_f32_16x16x32_bf16 v[14:17], v[248:251], v[252:255], v[14:17]
	s_setprio 0
	s_add_i32 s96, s96, 2
	s_add_u32 s94, s94, 0x100
	s_addc_u32 s95, s95, 0
	s_cmp_gt_u32 s96, 61
	s_mov_b64 s[66:67], s[62:63]
	s_cbranch_scc0 .LBB0_138
	v_mul_f32_e32 v134, 0xbfb8aa3b, v126
	v_exp_f32_e32 v150, v134
	v_mul_f32_e32 v134, 0xbfb8aa3b, v122
	v_exp_f32_e32 v151, v134
	v_lshl_or_b32 v148, s91, 7, v141
	v_add_f32_e32 v150, 1.0, v150
	v_rcp_f32_e32 v152, v150
	v_add_f32_e32 v150, 1.0, v151
	v_rcp_f32_e32 v153, v150
	v_lshl_add_u32 v147, s82, 8, v140
	v_mul_f32_e32 v126, v126, v152
	v_mul_f32_e32 v118, v126, v118
	v_mul_f32_e32 v126, 0xbfb8aa3b, v127
	v_exp_f32_e32 v126, v126
	v_mul_f32_e32 v152, 0xbfb8aa3b, v123
	v_exp_f32_e32 v152, v152
	v_mul_f32_e32 v122, v122, v153
	v_mul_f32_e32 v122, v122, v114
	v_add_f32_e32 v114, 1.0, v126
	v_rcp_f32_e32 v114, v114
	v_add_f32_e32 v126, 1.0, v152
	v_mul_f32_e32 v152, 0xbfb8aa3b, v128
	v_rcp_f32_e32 v126, v126
	v_exp_f32_e32 v152, v152
	v_mul_f32_e32 v114, v127, v114
	v_mul_f32_e32 v119, v114, v119
	v_mul_f32_e32 v114, v123, v126
	v_add_f32_e32 v123, 1.0, v152
	v_rcp_f32_e32 v123, v123
	v_mul_f32_e32 v126, 0xbfb8aa3b, v124
	v_exp_f32_e32 v126, v126
	v_mul_f32_e32 v127, v114, v115
	v_mul_f32_e32 v114, v128, v123
	v_mul_f32_e32 v115, 0xbfb8aa3b, v129
	v_mul_f32_e32 v123, v114, v120
	v_exp_f32_e32 v115, v115
	v_mul_f32_e32 v120, 0xbfb8aa3b, v125
	v_exp_f32_e32 v120, v120
	v_add_f32_e32 v114, 1.0, v126
	v_rcp_f32_e32 v114, v114
	v_add_f32_e32 v115, 1.0, v115
	v_rcp_f32_e32 v115, v115
	v_add_f32_e32 v120, 1.0, v120
	v_rcp_f32_e32 v120, v120
	v_mul_f32_e32 v114, v124, v114
	v_mul_f32_e32 v124, v114, v116
	v_mul_f32_e32 v114, v129, v115
	v_ashrrev_i32_e32 v149, 31, v148
	v_mov_b64_e32 v[134:135], s[72:73]
	v_mul_f32_e32 v126, v114, v121
	v_mul_f32_e32 v114, v125, v120
	v_mad_i64_i32 v[150:151], s[62:63], v147, s90, v[134:135]
	v_mul_f32_e32 v125, v114, v117
	v_lshlrev_b64 v[114:115], 1, v[148:149]
	v_lshl_add_u64 v[120:121], v[150:151], 0, v[114:115]
	v_cvt_pk_bf16_f32 v116, v118, v119
	v_cvt_pk_bf16_f32 v117, v123, v126
	v_cvt_pk_bf16_f32 v118, v122, v127
	v_cvt_pk_bf16_f32 v119, v124, v125
	global_store_dwordx4 v[120:121], v[116:119], off
	s_and_b64 vcc, exec, s[0:1]
	s_mov_b32 s91, s10
	v_mul_f32_e32 v116, 0xbfb8aa3b, v110
	v_exp_f32_e32 v116, v116
; __device__ __forceinline__ unsigned cvt_pk_bf16(float lo, float hi) { unsigned r; asm volatile("v_cvt_pk_bf16_f32 %0, %1, %2" : "=v"(r) : "v"(lo), "v"(hi)); return r; }
; __device__ __forceinline__ float silu_f(float x) { return x * sigmoid_f(x); }
;     __device__ __forceinline__ void operator()(const f32x4 (&acc)[2][2][4][2], const Unit& u, int wr, int wc, int fr, int fq) const {
;         const int row0 = u.pm * BM + wr * 64 + fr, col0 = u.pn * HALF + wc * 32 + 8 * fq;
; #pragma unroll
;         for (int ai = 0; ai < 2; ++ai)
; #pragma unroll
;             for (int m = 0; m < 4; ++m) { bf16_t* rowp = O + (size_t)(row0 + ai * HALF + m * 16) * ldc + col0;
;                 const f32x4 g0 = acc[ai][0][m][0], g1 = acc[ai][0][m][1], u0 = acc[ai][1][m][0], u1 = acc[ai][1][m][1];
;                 f32x4 v0, v1;
; #pragma unroll
;                 for (int j = 0; j < 4; ++j) { v0[j] = silu_f(g0[j]) * u0[j]; v1[j] = silu_f(g1[j]) * u1[j]; }
;                 u32x4 w; w.x = cvt_pk_bf16(v0[0], v0[1]); w.y = cvt_pk_bf16(v0[2], v0[3]); w.z = cvt_pk_bf16(v1[0], v1[1]); w.w = cvt_pk_bf16(v1[2], v1[3]);
;                 *(u32x4*)rowp = w; }
	v_mul_f32_e32 v117, 0xbfb8aa3b, v106
	v_exp_f32_e32 v117, v117
	v_or_b32_e32 v118, 16, v147
	v_add_f32_e32 v116, 1.0, v116
	v_rcp_f32_e32 v119, v116
	v_add_f32_e32 v116, 1.0, v117
	v_rcp_f32_e32 v120, v116
	v_mad_i64_i32 v[116:117], s[62:63], v118, s90, v[134:135]
	v_mul_f32_e32 v110, v110, v119
	v_mul_f32_e32 v110, v110, v102
	v_mul_f32_e32 v102, v106, v120
	v_mul_f32_e32 v106, 0xbfb8aa3b, v111
	v_exp_f32_e32 v106, v106
	v_mul_f32_e32 v118, 0xbfb8aa3b, v107
	v_mul_f32_e32 v119, v102, v98
	v_exp_f32_e32 v118, v118
	v_add_f32_e32 v98, 1.0, v106
	v_rcp_f32_e32 v98, v98
	v_mul_f32_e32 v106, 0xbfb8aa3b, v112
	v_exp_f32_e32 v106, v106
	v_add_f32_e32 v102, 1.0, v118
	v_mul_f32_e32 v98, v111, v98
	v_rcp_f32_e32 v102, v102
	v_mul_f32_e32 v98, v98, v103
	v_add_f32_e32 v103, 1.0, v106
	v_rcp_f32_e32 v103, v103
	v_mul_f32_e32 v102, v107, v102
	v_mul_f32_e32 v106, 0xbfb8aa3b, v108
	v_mul_f32_e32 v107, v102, v99
	v_mul_f32_e32 v99, v112, v103
	v_exp_f32_e32 v106, v106
	v_mul_f32_e32 v99, v99, v104
	v_mul_f32_e32 v103, 0xbfb8aa3b, v113
	v_mul_f32_e32 v104, 0xbfb8aa3b, v109
	v_exp_f32_e32 v103, v103
	v_exp_f32_e32 v104, v104
	v_add_f32_e32 v102, 1.0, v106
	v_rcp_f32_e32 v102, v102
	v_add_f32_e32 v103, 1.0, v103
	v_add_f32_e32 v104, 1.0, v104
	v_rcp_f32_e32 v103, v103
	v_rcp_f32_e32 v104, v104
	v_mul_f32_e32 v102, v108, v102
	v_mul_f32_e32 v106, v102, v100
	v_mul_f32_e32 v100, v113, v103
	v_mul_f32_e32 v102, v109, v104
	v_mul_f32_e32 v100, v100, v105
	v_mul_f32_e32 v101, v102, v101
	v_lshl_add_u64 v[102:103], v[116:117], 0, v[114:115]
	v_cvt_pk_bf16_f32 v98, v110, v98
	v_cvt_pk_bf16_f32 v99, v99, v100
	v_cvt_pk_bf16_f32 v100, v119, v107
	v_cvt_pk_bf16_f32 v101, v106, v101
	global_store_dwordx4 v[102:103], v[98:101], off
	s_mov_b32 s82, s12
	s_mov_b64 s[66:67], s[14:15]
	v_mul_f32_e32 v98, 0xbfb8aa3b, v94
	v_exp_f32_e32 v98, v98
	v_mul_f32_e32 v99, 0xbfb8aa3b, v90
	v_exp_f32_e32 v99, v99
	v_or_b32_e32 v100, 32, v147
	v_add_f32_e32 v98, 1.0, v98
	v_rcp_f32_e32 v101, v98
	v_add_f32_e32 v98, 1.0, v99
	v_rcp_f32_e32 v102, v98
	v_mad_i64_i32 v[98:99], s[62:63], v100, s90, v[134:135]
	v_mul_f32_e32 v94, v94, v101
	v_mul_f32_e32 v94, v94, v86
	v_mul_f32_e32 v86, v90, v102
	v_mul_f32_e32 v90, 0xbfb8aa3b, v95
	v_exp_f32_e32 v90, v90
	v_mul_f32_e32 v100, 0xbfb8aa3b, v91
	v_mul_f32_e32 v101, v86, v82
	v_exp_f32_e32 v100, v100
	v_add_f32_e32 v82, 1.0, v90
	v_rcp_f32_e32 v82, v82
	v_mul_f32_e32 v90, 0xbfb8aa3b, v96
	v_exp_f32_e32 v90, v90
	v_add_f32_e32 v86, 1.0, v100
	v_mul_f32_e32 v82, v95, v82
	v_rcp_f32_e32 v86, v86
	v_mul_f32_e32 v82, v82, v87
	v_add_f32_e32 v87, 1.0, v90
	v_rcp_f32_e32 v87, v87
	v_mul_f32_e32 v86, v91, v86
	v_mul_f32_e32 v90, 0xbfb8aa3b, v92
	v_mul_f32_e32 v91, v86, v83
	v_mul_f32_e32 v83, v96, v87
	v_exp_f32_e32 v90, v90
	v_mul_f32_e32 v83, v83, v88
	v_mul_f32_e32 v87, 0xbfb8aa3b, v97
	v_mul_f32_e32 v88, 0xbfb8aa3b, v93
	v_exp_f32_e32 v87, v87
	v_exp_f32_e32 v88, v88
	v_add_f32_e32 v86, 1.0, v90
	v_rcp_f32_e32 v86, v86
	v_add_f32_e32 v87, 1.0, v87
	v_add_f32_e32 v88, 1.0, v88
	v_rcp_f32_e32 v87, v87
	v_rcp_f32_e32 v88, v88
	v_mul_f32_e32 v86, v92, v86
	v_mul_f32_e32 v90, v86, v84
	v_mul_f32_e32 v84, v97, v87
	v_mul_f32_e32 v86, v93, v88
	v_mul_f32_e32 v84, v84, v89
	v_mul_f32_e32 v85, v86, v85
	v_lshl_add_u64 v[86:87], v[98:99], 0, v[114:115]
	v_cvt_pk_bf16_f32 v82, v94, v82
	v_cvt_pk_bf16_f32 v83, v83, v84
	v_cvt_pk_bf16_f32 v84, v101, v91
	v_cvt_pk_bf16_f32 v85, v90, v85
	global_store_dwordx4 v[86:87], v[82:85], off
	s_nop 1
	v_mul_f32_e32 v82, 0xbfb8aa3b, v78
	v_exp_f32_e32 v82, v82
	v_mul_f32_e32 v83, 0xbfb8aa3b, v74
	v_exp_f32_e32 v83, v83
	v_or_b32_e32 v84, 48, v147
	v_add_f32_e32 v82, 1.0, v82
	v_rcp_f32_e32 v85, v82
	v_add_f32_e32 v82, 1.0, v83
	v_rcp_f32_e32 v86, v82
	v_mad_i64_i32 v[82:83], s[62:63], v84, s90, v[134:135]
	v_mul_f32_e32 v78, v78, v85
	v_mul_f32_e32 v78, v78, v70
	v_mul_f32_e32 v70, v74, v86
	v_mul_f32_e32 v74, 0xbfb8aa3b, v79
	v_exp_f32_e32 v74, v74
	v_mul_f32_e32 v84, 0xbfb8aa3b, v75
	v_mul_f32_e32 v85, v70, v66
	v_exp_f32_e32 v84, v84
	v_add_f32_e32 v66, 1.0, v74
	v_rcp_f32_e32 v66, v66
	v_mul_f32_e32 v74, 0xbfb8aa3b, v80
	v_exp_f32_e32 v74, v74
	v_add_f32_e32 v70, 1.0, v84
	v_mul_f32_e32 v66, v79, v66
	v_rcp_f32_e32 v70, v70
	v_mul_f32_e32 v66, v66, v71
	v_add_f32_e32 v71, 1.0, v74
	v_rcp_f32_e32 v71, v71
	v_mul_f32_e32 v70, v75, v70
	v_mul_f32_e32 v74, 0xbfb8aa3b, v76
	v_mul_f32_e32 v75, v70, v67
	v_mul_f32_e32 v67, v80, v71
	v_exp_f32_e32 v74, v74
	v_mul_f32_e32 v67, v67, v72
	v_mul_f32_e32 v71, 0xbfb8aa3b, v81
	v_mul_f32_e32 v72, 0xbfb8aa3b, v77
	v_exp_f32_e32 v71, v71
	v_exp_f32_e32 v72, v72
	v_add_f32_e32 v70, 1.0, v74
	v_rcp_f32_e32 v70, v70
	v_add_f32_e32 v71, 1.0, v71
	v_add_f32_e32 v72, 1.0, v72
	v_rcp_f32_e32 v71, v71
	v_rcp_f32_e32 v72, v72
	v_mul_f32_e32 v70, v76, v70
	v_mul_f32_e32 v74, v70, v68
	v_mul_f32_e32 v68, v81, v71
	v_mul_f32_e32 v70, v77, v72
	v_mul_f32_e32 v68, v68, v73
	v_mul_f32_e32 v69, v70, v69
	v_lshl_add_u64 v[70:71], v[82:83], 0, v[114:115]
	v_cvt_pk_bf16_f32 v66, v78, v66
	v_cvt_pk_bf16_f32 v67, v67, v68
	v_cvt_pk_bf16_f32 v68, v85, v75
	v_cvt_pk_bf16_f32 v69, v74, v69
	global_store_dwordx4 v[70:71], v[66:69], off
	s_nop 1
	v_mul_f32_e32 v66, 0xbfb8aa3b, v62
	v_exp_f32_e32 v66, v66
	v_mul_f32_e32 v67, 0xbfb8aa3b, v58
	v_exp_f32_e32 v67, v67
	v_add_u32_e32 v68, 0x80, v147
	v_add_f32_e32 v66, 1.0, v66
	v_rcp_f32_e32 v69, v66
	v_add_f32_e32 v66, 1.0, v67
	v_rcp_f32_e32 v70, v66
	v_mad_i64_i32 v[66:67], s[62:63], v68, s90, v[134:135]
	v_mul_f32_e32 v62, v62, v69
	v_mul_f32_e32 v62, v62, v54
	v_mul_f32_e32 v54, v58, v70
	v_mul_f32_e32 v58, 0xbfb8aa3b, v63
	v_exp_f32_e32 v58, v58
; __device__ __forceinline__ unsigned cvt_pk_bf16(float lo, float hi) { unsigned r; asm volatile("v_cvt_pk_bf16_f32 %0, %1, %2" : "=v"(r) : "v"(lo), "v"(hi)); return r; }
; __device__ __forceinline__ float silu_f(float x) { return x * sigmoid_f(x); }
; #define PG8_WAIT_V(n) asm volatile("s_waitcnt vmcnt(" #n ")" ::: "memory")
; #define PG8_BAR __builtin_amdgcn_s_barrier()
;     __device__ __forceinline__ void operator()(const f32x4 (&acc)[2][2][4][2], const Unit& u, int wr, int wc, int fr, int fq) const {
;         const int row0 = u.pm * BM + wr * 64 + fr, col0 = u.pn * HALF + wc * 32 + 8 * fq;
; #pragma unroll
;         for (int ai = 0; ai < 2; ++ai)
; #pragma unroll
;             for (int m = 0; m < 4; ++m) { bf16_t* rowp = O + (size_t)(row0 + ai * HALF + m * 16) * ldc + col0;
;                 const f32x4 g0 = acc[ai][0][m][0], g1 = acc[ai][0][m][1], u0 = acc[ai][1][m][0], u1 = acc[ai][1][m][1];
;                 f32x4 v0, v1;
; #pragma unroll
;                 for (int j = 0; j < 4; ++j) { v0[j] = silu_f(g0[j]) * u0[j]; v1[j] = silu_f(g1[j]) * u1[j]; }
;                 u32x4 w; w.x = cvt_pk_bf16(v0[0], v0[1]); w.y = cvt_pk_bf16(v0[2], v0[3]); w.z = cvt_pk_bf16(v1[0], v1[1]); w.w = cvt_pk_bf16(v1[2], v1[3]);
;                 *(u32x4*)rowp = w; }
; template <class Epi, class Sched, bool ALIGN_EPI = false, bool SP2 = false>
; __device__ __forceinline__ void gemm_phase(PG8_LAS unsigned char* lds, const Gemm g, const Sched& S, const Epi& E) {
;     ...
;         if (!has_next) break;
; #pragma unroll
;         for (int a = 0; a < 2; ++a)
; #pragma unroll
;             for (int b = 0; b < 2; ++b)
; #pragma unroll
;                 for (int m = 0; m < 4; ++m)
; #pragma unroll
;                     for (int n = 0; n < 2; ++n) acc[a][b][m][n] = (f32x4){0.f, 0.f, 0.f, 0.f};
;         cur = nxt; cA = nA; cB = nB; ++ui;
;         if constexpr (ALIGN_EPI) { if (wr == 1) PG8_BAR; }
;     }
;     PG8_WAIT_V(0);
;     if constexpr (!ALIGN_EPI) { if (wr == 0) PG8_BAR; }
	v_mul_f32_e32 v68, 0xbfb8aa3b, v59
	v_mul_f32_e32 v69, v54, v50
	v_exp_f32_e32 v68, v68
	v_add_f32_e32 v50, 1.0, v58
	v_rcp_f32_e32 v50, v50
	v_mul_f32_e32 v58, 0xbfb8aa3b, v64
	v_exp_f32_e32 v58, v58
	v_add_f32_e32 v54, 1.0, v68
	v_mul_f32_e32 v50, v63, v50
	v_rcp_f32_e32 v54, v54
	v_mul_f32_e32 v50, v50, v55
	v_add_f32_e32 v55, 1.0, v58
	v_rcp_f32_e32 v55, v55
	v_mul_f32_e32 v54, v59, v54
	v_mul_f32_e32 v58, 0xbfb8aa3b, v60
	v_mul_f32_e32 v59, v54, v51
	v_mul_f32_e32 v51, v64, v55
	v_exp_f32_e32 v58, v58
	v_mul_f32_e32 v51, v51, v56
	v_mul_f32_e32 v55, 0xbfb8aa3b, v65
	v_mul_f32_e32 v56, 0xbfb8aa3b, v61
	v_exp_f32_e32 v55, v55
	v_exp_f32_e32 v56, v56
	v_add_f32_e32 v54, 1.0, v58
	v_rcp_f32_e32 v54, v54
	v_add_f32_e32 v55, 1.0, v55
	v_add_f32_e32 v56, 1.0, v56
	v_rcp_f32_e32 v55, v55
	v_rcp_f32_e32 v56, v56
	v_mul_f32_e32 v54, v60, v54
	v_mul_f32_e32 v58, v54, v52
	v_mul_f32_e32 v52, v65, v55
	v_mul_f32_e32 v54, v61, v56
	v_mul_f32_e32 v52, v52, v57
	v_mul_f32_e32 v53, v54, v53
	v_lshl_add_u64 v[54:55], v[66:67], 0, v[114:115]
	v_cvt_pk_bf16_f32 v50, v62, v50
	v_cvt_pk_bf16_f32 v51, v51, v52
	v_cvt_pk_bf16_f32 v52, v69, v59
	v_cvt_pk_bf16_f32 v53, v58, v53
	global_store_dwordx4 v[54:55], v[50:53], off
	s_nop 1
	v_mul_f32_e32 v50, 0xbfb8aa3b, v46
	v_exp_f32_e32 v50, v50
	v_mul_f32_e32 v51, 0xbfb8aa3b, v42
	v_exp_f32_e32 v51, v51
	v_add_u32_e32 v52, 0x90, v147
	v_add_f32_e32 v50, 1.0, v50
	v_rcp_f32_e32 v53, v50
	v_add_f32_e32 v50, 1.0, v51
	v_rcp_f32_e32 v54, v50
	v_mad_i64_i32 v[50:51], s[62:63], v52, s90, v[134:135]
	v_mul_f32_e32 v46, v46, v53
	v_mul_f32_e32 v46, v46, v38
	v_mul_f32_e32 v38, v42, v54
	v_mul_f32_e32 v42, 0xbfb8aa3b, v47
	v_exp_f32_e32 v42, v42
	v_mul_f32_e32 v52, 0xbfb8aa3b, v43
	v_mul_f32_e32 v53, v38, v34
	v_exp_f32_e32 v52, v52
	v_add_f32_e32 v34, 1.0, v42
	v_rcp_f32_e32 v34, v34
	v_mul_f32_e32 v42, 0xbfb8aa3b, v48
	v_exp_f32_e32 v42, v42
	v_add_f32_e32 v38, 1.0, v52
	v_mul_f32_e32 v34, v47, v34
	v_rcp_f32_e32 v38, v38
	v_mul_f32_e32 v34, v34, v39
	v_add_f32_e32 v39, 1.0, v42
	v_rcp_f32_e32 v39, v39
	v_mul_f32_e32 v38, v43, v38
	v_mul_f32_e32 v42, 0xbfb8aa3b, v44
	v_mul_f32_e32 v43, v38, v35
	v_mul_f32_e32 v35, v48, v39
	v_exp_f32_e32 v42, v42
	v_mul_f32_e32 v35, v35, v40
	v_mul_f32_e32 v39, 0xbfb8aa3b, v49
	v_mul_f32_e32 v40, 0xbfb8aa3b, v45
	v_exp_f32_e32 v39, v39
	v_exp_f32_e32 v40, v40
	v_add_f32_e32 v38, 1.0, v42
	v_rcp_f32_e32 v38, v38
	v_add_f32_e32 v39, 1.0, v39
	v_add_f32_e32 v40, 1.0, v40
	v_rcp_f32_e32 v39, v39
	v_rcp_f32_e32 v40, v40
	v_mul_f32_e32 v38, v44, v38
	v_mul_f32_e32 v42, v38, v36
	v_mul_f32_e32 v36, v49, v39
	v_mul_f32_e32 v38, v45, v40
	v_mul_f32_e32 v36, v36, v41
	v_mul_f32_e32 v37, v38, v37
	v_lshl_add_u64 v[38:39], v[50:51], 0, v[114:115]
	v_cvt_pk_bf16_f32 v34, v46, v34
	v_cvt_pk_bf16_f32 v35, v35, v36
	v_cvt_pk_bf16_f32 v36, v53, v43
	v_cvt_pk_bf16_f32 v37, v42, v37
	global_store_dwordx4 v[38:39], v[34:37], off
	s_nop 1
	v_mul_f32_e32 v34, 0xbfb8aa3b, v30
	v_exp_f32_e32 v34, v34
	v_mul_f32_e32 v35, 0xbfb8aa3b, v26
	v_exp_f32_e32 v35, v35
	v_add_u32_e32 v36, 0xa0, v147
	v_add_f32_e32 v34, 1.0, v34
	v_rcp_f32_e32 v37, v34
	v_add_f32_e32 v34, 1.0, v35
	v_rcp_f32_e32 v38, v34
	v_mad_i64_i32 v[34:35], s[62:63], v36, s90, v[134:135]
	v_mul_f32_e32 v30, v30, v37
	v_mul_f32_e32 v30, v30, v22
	v_mul_f32_e32 v22, v26, v38
	v_mul_f32_e32 v26, 0xbfb8aa3b, v31
	v_exp_f32_e32 v26, v26
	v_mul_f32_e32 v36, 0xbfb8aa3b, v27
	v_mul_f32_e32 v37, v22, v18
	v_exp_f32_e32 v36, v36
	v_add_f32_e32 v18, 1.0, v26
	v_rcp_f32_e32 v18, v18
	v_mul_f32_e32 v26, 0xbfb8aa3b, v32
	v_exp_f32_e32 v26, v26
	v_add_f32_e32 v22, 1.0, v36
	v_mul_f32_e32 v18, v31, v18
	v_rcp_f32_e32 v22, v22
	v_mul_f32_e32 v18, v18, v23
	v_add_f32_e32 v23, 1.0, v26
	v_rcp_f32_e32 v23, v23
	v_mul_f32_e32 v22, v27, v22
	v_mul_f32_e32 v26, 0xbfb8aa3b, v28
	v_mul_f32_e32 v27, v22, v19
	v_mul_f32_e32 v19, v32, v23
	v_exp_f32_e32 v26, v26
	v_mul_f32_e32 v19, v19, v24
	v_mul_f32_e32 v23, 0xbfb8aa3b, v33
	v_mul_f32_e32 v24, 0xbfb8aa3b, v29
	v_exp_f32_e32 v23, v23
	v_exp_f32_e32 v24, v24
	v_add_f32_e32 v22, 1.0, v26
	v_rcp_f32_e32 v22, v22
	v_add_f32_e32 v23, 1.0, v23
	v_add_f32_e32 v24, 1.0, v24
	v_rcp_f32_e32 v23, v23
	v_rcp_f32_e32 v24, v24
	v_mul_f32_e32 v22, v28, v22
	v_mul_f32_e32 v26, v22, v20
	v_mul_f32_e32 v20, v33, v23
	v_mul_f32_e32 v22, v29, v24
	v_mul_f32_e32 v20, v20, v25
	v_mul_f32_e32 v21, v22, v21
	v_lshl_add_u64 v[22:23], v[34:35], 0, v[114:115]
	v_cvt_pk_bf16_f32 v18, v30, v18
	v_cvt_pk_bf16_f32 v19, v19, v20
	v_cvt_pk_bf16_f32 v20, v37, v27
	v_cvt_pk_bf16_f32 v21, v26, v21
	global_store_dwordx4 v[22:23], v[18:21], off
	s_nop 1
	v_mul_f32_e32 v18, 0xbfb8aa3b, v14
	v_exp_f32_e32 v18, v18
	v_mul_f32_e32 v19, 0xbfb8aa3b, v10
	v_exp_f32_e32 v19, v19
	v_add_u32_e32 v20, 0xb0, v147
	v_add_f32_e32 v18, 1.0, v18
	v_rcp_f32_e32 v21, v18
	v_add_f32_e32 v18, 1.0, v19
	v_rcp_f32_e32 v22, v18
	v_mad_i64_i32 v[18:19], s[62:63], v20, s90, v[134:135]
	v_mul_f32_e32 v14, v14, v21
	v_mul_f32_e32 v14, v14, v6
	v_mul_f32_e32 v6, v10, v22
	v_mul_f32_e32 v10, 0xbfb8aa3b, v15
	v_exp_f32_e32 v10, v10
	v_mul_f32_e32 v20, 0xbfb8aa3b, v11
	v_mul_f32_e32 v21, v6, v2
	v_exp_f32_e32 v20, v20
	v_add_f32_e32 v2, 1.0, v10
	v_rcp_f32_e32 v2, v2
	v_mul_f32_e32 v10, 0xbfb8aa3b, v16
	v_exp_f32_e32 v10, v10
	v_add_f32_e32 v6, 1.0, v20
	v_mul_f32_e32 v2, v15, v2
	v_rcp_f32_e32 v6, v6
	v_mul_f32_e32 v2, v2, v7
	v_add_f32_e32 v7, 1.0, v10
	v_rcp_f32_e32 v7, v7
	v_mul_f32_e32 v6, v11, v6
	v_mul_f32_e32 v10, 0xbfb8aa3b, v12
	v_mul_f32_e32 v11, v6, v3
	v_mul_f32_e32 v3, v16, v7
	v_exp_f32_e32 v10, v10
	v_mul_f32_e32 v3, v3, v8
	v_mul_f32_e32 v7, 0xbfb8aa3b, v17
	v_mul_f32_e32 v8, 0xbfb8aa3b, v13
	v_exp_f32_e32 v7, v7
	v_exp_f32_e32 v8, v8
	v_add_f32_e32 v6, 1.0, v10
	v_rcp_f32_e32 v6, v6
	v_add_f32_e32 v7, 1.0, v7
	v_add_f32_e32 v8, 1.0, v8
	v_rcp_f32_e32 v7, v7
	v_rcp_f32_e32 v8, v8
	v_mul_f32_e32 v6, v12, v6
	v_mul_f32_e32 v10, v6, v4
	v_mul_f32_e32 v4, v17, v7
	v_mul_f32_e32 v6, v13, v8
	v_mul_f32_e32 v4, v4, v9
	v_mul_f32_e32 v5, v6, v5
	v_lshl_add_u64 v[6:7], v[18:19], 0, v[114:115]
	s_mov_b64 s[62:63], s[16:17]
	v_cvt_pk_bf16_f32 v2, v14, v2
	v_cvt_pk_bf16_f32 v3, v3, v4
	v_cvt_pk_bf16_f32 v4, v21, v11
	v_cvt_pk_bf16_f32 v5, v10, v5
	global_store_dwordx4 v[6:7], v[2:5], off
	s_cbranch_vccz .LBB0_135
	s_waitcnt vmcnt(0)
	s_cmpk_gt_u32 s3, 0xff
	s_cbranch_scc1 .LBB0_142
	s_barrier

; #define PG8_STAGE(bufoff, gbase, voff) do { _Pragma("unroll") for (int _i = 0; _i < 2; ++_i) \
;         asm volatile("s_mov_b32 m0, %2\n\ts_nop 0\n\tglobal_load_lds_dwordx4 %0, %1" :: "v"((voff)[_i]), "s"((const char*)(gbase)), "s"(ldsbase + (unsigned)(bufoff) + ldsw + (unsigned)_i * 8192u) : "memory", "m0"); } while (0)
; #define PG8_LDA(dst, b, h) do { _Pragma("unroll") for (int m = 0; m < 4; ++m) _Pragma("unroll") for (int k = 0; k < 2; ++k) dst[m][k] = *(const PG8_LAS bf16x8*)(lds + PG8_SA(b, h) + aoff + m * 2048 + k * 1024); } while (0)
; #define PG8_WAIT_V(n) asm volatile("s_waitcnt vmcnt(" #n ")" ::: "memory")
; template <class Epi, class Sched, bool ALIGN_EPI = false, bool SP2 = false>
; __device__ __forceinline__ void gemm_phase(PG8_LAS unsigned char* lds, const Gemm g, const Sched& S, const Epi& E) {
;     ...
;             const bool last = (t == nt - 2);
;             const char* a1 = cA + (size_t)(t + 1) * kstep;
;             const char* a2 = last ? nA : cA + (size_t)(t + 2) * kstep; const char* b2 = last ? nB : cB + (size_t)(t + 2) * kstep;
;             const char* a3 = a2 + kstep; const char* b3 = b2 + kstep;
;             if (last && has_next) S.a_ready(nxt);
;             if constexpr (epi_has_mid<Epi>::value) { if (t == Epi::MID_T) E.mid(acc, cur, wr, wc, fr, fq); }
;             if constexpr (SP2) {
;             PG8_LDB(B0, 0, 0); PG8_LDB(B1, 0, 1); PG8_SCHED; PG8_LDA(At, 0, 0); PG8_STAGE(PG8_SA(1, 1), a1 + hstep, voffA);
;             PG8_WAIT_V(8); PG8_WAIT_L(0); PG8_BAR; PG8_MMA(0, 0, At, B0); PG8_MMA(0, 1, At, B1); PG8_BAR; PG8_SCHED;
;             PG8_LDA(At, 0, 1); PG8_STAGE(PG8_SB(0, 0), b2, voffB); PG8_STAGE(PG8_SB(0, 1), b2 + hstep, voffB); PG8_STAGE(PG8_SA(0, 0), a2, voffA);
;             PG8_WAIT_V(8); PG8_WAIT_L(0); PG8_BAR; PG8_MMA(1, 0, At, B0); PG8_MMA(1, 1, At, B1); PG8_BAR; PG8_SCHED;
;             PG8_LDB(B0, 1, 0); PG8_LDB(B1, 1, 1); PG8_SCHED; PG8_LDA(At, 1, 0); PG8_STAGE(PG8_SA(0, 1), a2 + hstep, voffA);
;             PG8_WAIT_V(8); PG8_WAIT_L(0); PG8_BAR; PG8_MMA(0, 0, At, B0); PG8_MMA(0, 1, At, B1); PG8_BAR; PG8_SCHED;
;             PG8_LDA(At, 1, 1); PG8_STAGE(PG8_SB(1, 0), b3, voffB); PG8_STAGE(PG8_SB(1, 1), b3 + hstep, voffB); PG8_STAGE(PG8_SA(1, 0), a3, voffA);
;             PG8_WAIT_V(8); PG8_WAIT_L(0); PG8_BAR; PG8_MMA(1, 0, At, B0); PG8_MMA(1, 1, At, B1); PG8_BAR; PG8_SCHED;
.LBB0_234:
	ds_read_b128 v[134:137], v145
	ds_read_b128 v[152:155], v145 offset:1024
	ds_read_b128 v[156:159], v145 offset:2048
	ds_read_b128 v[160:163], v145 offset:3072
	ds_read_b128 v[164:167], v146
	ds_read_b128 v[168:171], v146 offset:1024
	ds_read_b128 v[172:175], v146 offset:2048
	ds_read_b128 v[176:179], v146 offset:3072
	s_cmpk_eq_i32 s57, 0xa8
	s_cselect_b32 s76, s4, s53
	s_cselect_b32 s77, s5, s54
	s_cselect_b32 s66, s46, s55
	s_cselect_b32 s67, s47, s56
	s_add_u32 s62, s76, 0x80
	s_addc_u32 s63, s77, 0
	ds_read_b128 v[180:183], v147
	ds_read_b128 v[184:187], v147 offset:1024
	ds_read_b128 v[188:191], v147 offset:2048
	ds_read_b128 v[192:195], v147 offset:3072
	ds_read_b128 v[196:199], v147 offset:4096
	ds_read_b128 v[200:203], v147 offset:5120
	ds_read_b128 v[204:207], v147 offset:6144
	ds_read_b128 v[208:211], v147 offset:7168
	s_mov_b32 m0, s94
	s_nop 0
	global_load_lds_dwordx4 v1, s[50:51]
	s_nop 0
	s_mov_b32 m0, s95
	s_nop 0
	global_load_lds_dwordx4 v141, s[50:51]
	s_waitcnt vmcnt(8)
	s_waitcnt lgkmcnt(0)
	s_barrier
	s_setprio 1
	s_waitcnt lgkmcnt(7)
	v_mfma_f32_16x16x32_bf16 v[126:129], v[134:137], v[180:183], v[126:129]
	v_mfma_f32_16x16x32_bf16 v[122:125], v[156:159], v[180:183], v[122:125]
	s_waitcnt lgkmcnt(5)
	v_mfma_f32_16x16x32_bf16 v[118:121], v[164:167], v[180:183], v[118:121]
	v_mfma_f32_16x16x32_bf16 v[114:117], v[172:175], v[180:183], v[114:117]
	s_waitcnt lgkmcnt(3)
	v_mfma_f32_16x16x32_bf16 v[98:101], v[172:175], v[188:191], v[98:101]
	v_mfma_f32_16x16x32_bf16 v[102:105], v[164:167], v[188:191], v[102:105]
	s_waitcnt lgkmcnt(1)
	v_mfma_f32_16x16x32_bf16 v[106:109], v[156:159], v[188:191], v[106:109]
	v_mfma_f32_16x16x32_bf16 v[110:113], v[134:137], v[188:191], v[110:113]
	v_mfma_f32_16x16x32_bf16 v[94:97], v[134:137], v[196:199], v[94:97]
	v_mfma_f32_16x16x32_bf16 v[90:93], v[156:159], v[196:199], v[90:93]
	v_mfma_f32_16x16x32_bf16 v[86:89], v[164:167], v[196:199], v[86:89]
	v_mfma_f32_16x16x32_bf16 v[82:85], v[172:175], v[196:199], v[82:85]
	v_mfma_f32_16x16x32_bf16 v[66:69], v[172:175], v[204:207], v[66:69]
	v_mfma_f32_16x16x32_bf16 v[70:73], v[164:167], v[204:207], v[70:73]
	s_waitcnt lgkmcnt(0)
	v_mfma_f32_16x16x32_bf16 v[74:77], v[156:159], v[204:207], v[74:77]
	v_mfma_f32_16x16x32_bf16 v[78:81], v[134:137], v[204:207], v[78:81]
	s_setprio 0
	s_setprio 1
	v_mfma_f32_16x16x32_bf16 v[126:129], v[152:155], v[184:187], v[126:129]
	v_mfma_f32_16x16x32_bf16 v[122:125], v[160:163], v[184:187], v[122:125]
	v_mfma_f32_16x16x32_bf16 v[118:121], v[168:171], v[184:187], v[118:121]
	v_mfma_f32_16x16x32_bf16 v[114:117], v[176:179], v[184:187], v[114:117]
	v_mfma_f32_16x16x32_bf16 v[98:101], v[176:179], v[192:195], v[98:101]
	v_mfma_f32_16x16x32_bf16 v[102:105], v[168:171], v[192:195], v[102:105]
	v_mfma_f32_16x16x32_bf16 v[106:109], v[160:163], v[192:195], v[106:109]
	v_mfma_f32_16x16x32_bf16 v[110:113], v[152:155], v[192:195], v[110:113]
	v_mfma_f32_16x16x32_bf16 v[94:97], v[152:155], v[200:203], v[94:97]
	v_mfma_f32_16x16x32_bf16 v[90:93], v[160:163], v[200:203], v[90:93]
	v_mfma_f32_16x16x32_bf16 v[86:89], v[168:171], v[200:203], v[86:89]
	v_mfma_f32_16x16x32_bf16 v[82:85], v[176:179], v[200:203], v[82:85]
	v_mfma_f32_16x16x32_bf16 v[66:69], v[176:179], v[208:211], v[66:69]
	v_mfma_f32_16x16x32_bf16 v[70:73], v[168:171], v[208:211], v[70:73]
	v_mfma_f32_16x16x32_bf16 v[74:77], v[160:163], v[208:211], v[74:77]
	s_setprio 2
	s_barrier
	v_mfma_f32_16x16x32_bf16 v[78:81], v[152:155], v[208:211], v[78:81]
	s_setprio 0
	ds_read_b128 v[180:183], v147 offset:16384
	ds_read_b128 v[184:187], v147 offset:17408
	ds_read_b128 v[188:191], v147 offset:18432
	ds_read_b128 v[192:195], v147 offset:19456
	ds_read_b128 v[196:199], v147 offset:20480
	ds_read_b128 v[200:203], v147 offset:21504
	ds_read_b128 v[204:207], v147 offset:22528
	ds_read_b128 v[252:255], v147 offset:23552
	s_mov_b32 m0, s64
	s_nop 0
	global_load_lds_dwordx4 v140, s[66:67]
	s_add_u32 s58, s66, 0x2b0000
	s_mov_b32 m0, s65
	s_nop 0
	global_load_lds_dwordx4 v142, s[66:67]
	s_addc_u32 s59, s67, 0
	s_mov_b32 m0, s82
	s_nop 0
	global_load_lds_dwordx4 v140, s[58:59]
	s_nop 0
	s_mov_b32 m0, s83
	s_nop 0
	global_load_lds_dwordx4 v142, s[58:59]
	s_nop 0
	s_mov_b32 m0, s35
	s_nop 0
	global_load_lds_dwordx4 v1, s[76:77]
	s_nop 0
	s_mov_b32 m0, s84
	s_nop 0
	global_load_lds_dwordx4 v141, s[76:77]
	s_waitcnt vmcnt(8)
	s_waitcnt lgkmcnt(0)
	s_barrier
	s_setprio 1
	s_waitcnt lgkmcnt(7)
	v_mfma_f32_16x16x32_bf16 v[62:65], v[134:137], v[180:183], v[62:65]
	v_mfma_f32_16x16x32_bf16 v[58:61], v[156:159], v[180:183], v[58:61]
	s_waitcnt lgkmcnt(5)
	v_mfma_f32_16x16x32_bf16 v[54:57], v[164:167], v[180:183], v[54:57]
	v_mfma_f32_16x16x32_bf16 v[50:53], v[172:175], v[180:183], v[50:53]
	s_waitcnt lgkmcnt(3)
	v_mfma_f32_16x16x32_bf16 v[34:37], v[172:175], v[188:191], v[34:37]
	v_mfma_f32_16x16x32_bf16 v[38:41], v[164:167], v[188:191], v[38:41]
	s_waitcnt lgkmcnt(1)
	v_mfma_f32_16x16x32_bf16 v[42:45], v[156:159], v[188:191], v[42:45]
	v_mfma_f32_16x16x32_bf16 v[46:49], v[134:137], v[188:191], v[46:49]
	v_mfma_f32_16x16x32_bf16 v[30:33], v[134:137], v[196:199], v[30:33]
	v_mfma_f32_16x16x32_bf16 v[26:29], v[156:159], v[196:199], v[26:29]
	v_mfma_f32_16x16x32_bf16 v[22:25], v[164:167], v[196:199], v[22:25]
	v_mfma_f32_16x16x32_bf16 v[18:21], v[172:175], v[196:199], v[18:21]
	v_mfma_f32_16x16x32_bf16 v[2:5], v[172:175], v[204:207], v[2:5]
	v_mfma_f32_16x16x32_bf16 v[6:9], v[164:167], v[204:207], v[6:9]
	s_waitcnt lgkmcnt(0)
	v_mfma_f32_16x16x32_bf16 v[10:13], v[156:159], v[204:207], v[10:13]
	v_mfma_f32_16x16x32_bf16 v[14:17], v[134:137], v[204:207], v[14:17]
	s_setprio 0
	s_setprio 1
	v_mfma_f32_16x16x32_bf16 v[62:65], v[152:155], v[184:187], v[62:65]
	v_mfma_f32_16x16x32_bf16 v[58:61], v[160:163], v[184:187], v[58:61]
	v_mfma_f32_16x16x32_bf16 v[54:57], v[168:171], v[184:187], v[54:57]
	v_mfma_f32_16x16x32_bf16 v[50:53], v[176:179], v[184:187], v[50:53]
	v_mfma_f32_16x16x32_bf16 v[34:37], v[176:179], v[192:195], v[34:37]
	v_mfma_f32_16x16x32_bf16 v[38:41], v[168:171], v[192:195], v[38:41]
	v_mfma_f32_16x16x32_bf16 v[42:45], v[160:163], v[192:195], v[42:45]
	v_mfma_f32_16x16x32_bf16 v[46:49], v[152:155], v[192:195], v[46:49]
	v_mfma_f32_16x16x32_bf16 v[30:33], v[152:155], v[200:203], v[30:33]
	v_mfma_f32_16x16x32_bf16 v[26:29], v[160:163], v[200:203], v[26:29]
	v_mfma_f32_16x16x32_bf16 v[22:25], v[168:171], v[200:203], v[22:25]
	v_mfma_f32_16x16x32_bf16 v[18:21], v[176:179], v[200:203], v[18:21]
	v_mfma_f32_16x16x32_bf16 v[2:5], v[176:179], v[252:255], v[2:5]
	v_mfma_f32_16x16x32_bf16 v[6:9], v[168:171], v[252:255], v[6:9]
	v_mfma_f32_16x16x32_bf16 v[10:13], v[160:163], v[252:255], v[10:13]
	s_setprio 2
	s_barrier
; #define PG8_STAGE(bufoff, gbase, voff) do { _Pragma("unroll") for (int _i = 0; _i < 2; ++_i) \
;         asm volatile("s_mov_b32 m0, %2\n\ts_nop 0\n\tglobal_load_lds_dwordx4 %0, %1" :: "v"((voff)[_i]), "s"((const char*)(gbase)), "s"(ldsbase + (unsigned)(bufoff) + ldsw + (unsigned)_i * 8192u) : "memory", "m0"); } while (0)
; #define PG8_LDA(dst, b, h) do { _Pragma("unroll") for (int m = 0; m < 4; ++m) _Pragma("unroll") for (int k = 0; k < 2; ++k) dst[m][k] = *(const PG8_LAS bf16x8*)(lds + PG8_SA(b, h) + aoff + m * 2048 + k * 1024); } while (0)
; #define PG8_LDB(dst, b, h) do { _Pragma("unroll") for (int n = 0; n < 2; ++n) _Pragma("unroll") for (int k = 0; k < 2; ++k) dst[n][k] = *(const PG8_LAS bf16x8*)(lds + PG8_SB(b, h) + boff + n * 2048 + k * 1024); } while (0)
; #define PG8_MMA(ai, bj, At, Bt) do { __builtin_amdgcn_s_setprio(1); _Pragma("unroll") for (int m = 0; m < 4; ++m) _Pragma("unroll") for (int n = 0; n < 2; ++n) _Pragma("unroll") for (int k = 0; k < 2; ++k) \
;         acc[ai][bj][m][n] = __builtin_amdgcn_mfma_f32_16x16x32_bf16(Bt[n][k], At[m][k], acc[ai][bj][m][n], 0, 0, 0); __builtin_amdgcn_s_setprio(0); } while (0)
; template <class Epi, class Sched, bool ALIGN_EPI = false, bool SP2 = false>
; __device__ __forceinline__ void gemm_phase(PG8_LAS unsigned char* lds, const Gemm g, const Sched& S, const Epi& E) {
;     ...
;             PG8_LDB(B0, 0, 0); PG8_LDB(B1, 0, 1); PG8_SCHED; PG8_LDA(At, 0, 0); PG8_STAGE(PG8_SA(1, 1), a1 + hstep, voffA);
;             PG8_WAIT_V(8); PG8_WAIT_L(0); PG8_BAR; PG8_MMA(0, 0, At, B0); PG8_MMA(0, 1, At, B1); PG8_BAR; PG8_SCHED;
;             PG8_LDA(At, 0, 1); PG8_STAGE(PG8_SB(0, 0), b2, voffB); PG8_STAGE(PG8_SB(0, 1), b2 + hstep, voffB); PG8_STAGE(PG8_SA(0, 0), a2, voffA);
;             PG8_WAIT_V(8); PG8_WAIT_L(0); PG8_BAR; PG8_MMA(1, 0, At, B0); PG8_MMA(1, 1, At, B1); PG8_BAR; PG8_SCHED;
;             PG8_LDB(B0, 1, 0); PG8_LDB(B1, 1, 1); PG8_SCHED; PG8_LDA(At, 1, 0); PG8_STAGE(PG8_SA(0, 1), a2 + hstep, voffA);
;             PG8_WAIT_V(8); PG8_WAIT_L(0); PG8_BAR; PG8_MMA(0, 0, At, B0); PG8_MMA(0, 1, At, B1); PG8_BAR; PG8_SCHED;
;             PG8_LDA(At, 1, 1); PG8_STAGE(PG8_SB(1, 0), b3, voffB); PG8_STAGE(PG8_SB(1, 1), b3 + hstep, voffB); PG8_STAGE(PG8_SA(1, 0), a3, voffA);
;             PG8_WAIT_V(8); PG8_WAIT_L(0); PG8_BAR; PG8_MMA(1, 0, At, B0); PG8_MMA(1, 1, At, B1); PG8_BAR; PG8_SCHED;
	v_mfma_f32_16x16x32_bf16 v[14:17], v[152:155], v[252:255], v[14:17]
	s_setprio 0
	ds_read_b128 v[134:137], v148
	ds_read_b128 v[248:251], v148 offset:1024
	ds_read_b128 v[156:159], v148 offset:2048
	ds_read_b128 v[160:163], v148 offset:3072
	ds_read_b128 v[164:167], v149
	ds_read_b128 v[168:171], v149 offset:1024
	ds_read_b128 v[172:175], v149 offset:2048
	ds_read_b128 v[176:179], v149 offset:3072
	ds_read_b128 v[180:183], v147 offset:32768
	ds_read_b128 v[184:187], v147 offset:33792
	ds_read_b128 v[188:191], v147 offset:34816
	ds_read_b128 v[192:195], v147 offset:35840
	ds_read_b128 v[196:199], v147 offset:36864
	ds_read_b128 v[200:203], v147 offset:37888
	ds_read_b128 v[204:207], v147 offset:38912
	ds_read_b128 v[208:211], v147 offset:39936
	s_add_u32 s58, s76, 0x2b0000
	s_addc_u32 s59, s77, 0
	s_mov_b32 m0, s85
	s_nop 0
	global_load_lds_dwordx4 v1, s[58:59]
	s_nop 0
	s_mov_b32 m0, s86
	s_nop 0
	global_load_lds_dwordx4 v141, s[58:59]
	s_waitcnt vmcnt(8)
	s_waitcnt lgkmcnt(0)
	s_barrier
	s_setprio 1
	s_waitcnt lgkmcnt(7)
	v_mfma_f32_16x16x32_bf16 v[126:129], v[134:137], v[180:183], v[126:129]
	v_mfma_f32_16x16x32_bf16 v[122:125], v[156:159], v[180:183], v[122:125]
	s_waitcnt lgkmcnt(5)
	v_mfma_f32_16x16x32_bf16 v[118:121], v[164:167], v[180:183], v[118:121]
	v_mfma_f32_16x16x32_bf16 v[114:117], v[172:175], v[180:183], v[114:117]
	s_waitcnt lgkmcnt(3)
	v_mfma_f32_16x16x32_bf16 v[98:101], v[172:175], v[188:191], v[98:101]
	v_mfma_f32_16x16x32_bf16 v[102:105], v[164:167], v[188:191], v[102:105]
	s_waitcnt lgkmcnt(1)
	v_mfma_f32_16x16x32_bf16 v[106:109], v[156:159], v[188:191], v[106:109]
	v_mfma_f32_16x16x32_bf16 v[110:113], v[134:137], v[188:191], v[110:113]
	v_mfma_f32_16x16x32_bf16 v[94:97], v[134:137], v[196:199], v[94:97]
	v_mfma_f32_16x16x32_bf16 v[90:93], v[156:159], v[196:199], v[90:93]
	v_mfma_f32_16x16x32_bf16 v[86:89], v[164:167], v[196:199], v[86:89]
	v_mfma_f32_16x16x32_bf16 v[82:85], v[172:175], v[196:199], v[82:85]
	v_mfma_f32_16x16x32_bf16 v[66:69], v[172:175], v[204:207], v[66:69]
	v_mfma_f32_16x16x32_bf16 v[70:73], v[164:167], v[204:207], v[70:73]
	s_waitcnt lgkmcnt(0)
	v_mfma_f32_16x16x32_bf16 v[74:77], v[156:159], v[204:207], v[74:77]
	v_mfma_f32_16x16x32_bf16 v[78:81], v[134:137], v[204:207], v[78:81]
	s_setprio 0
	s_setprio 1
	v_mfma_f32_16x16x32_bf16 v[126:129], v[248:251], v[184:187], v[126:129]
	v_mfma_f32_16x16x32_bf16 v[122:125], v[160:163], v[184:187], v[122:125]
	v_mfma_f32_16x16x32_bf16 v[118:121], v[168:171], v[184:187], v[118:121]
	v_mfma_f32_16x16x32_bf16 v[114:117], v[176:179], v[184:187], v[114:117]
	v_mfma_f32_16x16x32_bf16 v[98:101], v[176:179], v[192:195], v[98:101]
	v_mfma_f32_16x16x32_bf16 v[102:105], v[168:171], v[192:195], v[102:105]
	v_mfma_f32_16x16x32_bf16 v[106:109], v[160:163], v[192:195], v[106:109]
	v_mfma_f32_16x16x32_bf16 v[110:113], v[248:251], v[192:195], v[110:113]
	v_mfma_f32_16x16x32_bf16 v[94:97], v[248:251], v[200:203], v[94:97]
	v_mfma_f32_16x16x32_bf16 v[90:93], v[160:163], v[200:203], v[90:93]
	v_mfma_f32_16x16x32_bf16 v[86:89], v[168:171], v[200:203], v[86:89]
	v_mfma_f32_16x16x32_bf16 v[82:85], v[176:179], v[200:203], v[82:85]
	v_mfma_f32_16x16x32_bf16 v[66:69], v[176:179], v[208:211], v[66:69]
	v_mfma_f32_16x16x32_bf16 v[70:73], v[168:171], v[208:211], v[70:73]
	v_mfma_f32_16x16x32_bf16 v[74:77], v[160:163], v[208:211], v[74:77]
	s_setprio 2
	s_barrier
; #define PG8_STAGE(bufoff, gbase, voff) do { _Pragma("unroll") for (int _i = 0; _i < 2; ++_i) \
;         asm volatile("s_mov_b32 m0, %2\n\ts_nop 0\n\tglobal_load_lds_dwordx4 %0, %1" :: "v"((voff)[_i]), "s"((const char*)(gbase)), "s"(ldsbase + (unsigned)(bufoff) + ldsw + (unsigned)_i * 8192u) : "memory", "m0"); } while (0)
; #define PG8_LDA(dst, b, h) do { _Pragma("unroll") for (int m = 0; m < 4; ++m) _Pragma("unroll") for (int k = 0; k < 2; ++k) dst[m][k] = *(const PG8_LAS bf16x8*)(lds + PG8_SA(b, h) + aoff + m * 2048 + k * 1024); } while (0)
; #define PG8_BAR __builtin_amdgcn_s_barrier()
; template <class Epi, class Sched, bool ALIGN_EPI = false, bool SP2 = false>
; __device__ __forceinline__ void gemm_phase(PG8_LAS unsigned char* lds, const Gemm g, const Sched& S, const Epi& E) {
;     ...
;         for (int t = 0; t < nt; t += 2) {
;             const bool last = (t == nt - 2);
;             const char* a1 = cA + (size_t)(t + 1) * kstep;
;             const char* a2 = last ? nA : cA + (size_t)(t + 2) * kstep; const char* b2 = last ? nB : cB + (size_t)(t + 2) * kstep;
;             const char* a3 = a2 + kstep; const char* b3 = b2 + kstep;
;             if (last && has_next) S.a_ready(nxt);
;             if constexpr (epi_has_mid<Epi>::value) { if (t == Epi::MID_T) E.mid(acc, cur, wr, wc, fr, fq); }
;             if constexpr (SP2) {
;             PG8_LDB(B0, 0, 0); PG8_LDB(B1, 0, 1); PG8_SCHED; PG8_LDA(At, 0, 0); PG8_STAGE(PG8_SA(1, 1), a1 + hstep, voffA);
;             PG8_WAIT_V(8); PG8_WAIT_L(0); PG8_BAR; PG8_MMA(0, 0, At, B0); PG8_MMA(0, 1, At, B1); PG8_BAR; PG8_SCHED;
;             PG8_LDA(At, 0, 1); PG8_STAGE(PG8_SB(0, 0), b2, voffB); PG8_STAGE(PG8_SB(0, 1), b2 + hstep, voffB); PG8_STAGE(PG8_SA(0, 0), a2, voffA);
;             PG8_WAIT_V(8); PG8_WAIT_L(0); PG8_BAR; PG8_MMA(1, 0, At, B0); PG8_MMA(1, 1, At, B1); PG8_BAR; PG8_SCHED;
;             PG8_LDB(B0, 1, 0); PG8_LDB(B1, 1, 1); PG8_SCHED; PG8_LDA(At, 1, 0); PG8_STAGE(PG8_SA(0, 1), a2 + hstep, voffA);
;             PG8_WAIT_V(8); PG8_WAIT_L(0); PG8_BAR; PG8_MMA(0, 0, At, B0); PG8_MMA(0, 1, At, B1); PG8_BAR; PG8_SCHED;
;             PG8_LDA(At, 1, 1); PG8_STAGE(PG8_SB(1, 0), b3, voffB); PG8_STAGE(PG8_SB(1, 1), b3 + hstep, voffB); PG8_STAGE(PG8_SA(1, 0), a3, voffA);
;             PG8_WAIT_V(8); PG8_WAIT_L(0); PG8_BAR; PG8_MMA(1, 0, At, B0); PG8_MMA(1, 1, At, B1); PG8_BAR; PG8_SCHED;
	v_mfma_f32_16x16x32_bf16 v[78:81], v[248:251], v[208:211], v[78:81]
	s_setprio 0
	ds_read_b128 v[180:183], v147 offset:49152
	ds_read_b128 v[184:187], v147 offset:50176
	ds_read_b128 v[188:191], v147 offset:51200
	ds_read_b128 v[192:195], v147 offset:52224
	ds_read_b128 v[196:199], v147 offset:53248
	ds_read_b128 v[200:203], v147 offset:54272
	ds_read_b128 v[204:207], v147 offset:55296
	ds_read_b128 v[252:255], v147 offset:56320
	s_add_u32 s58, s66, 0x80
	s_addc_u32 s59, s67, 0
	s_mov_b32 m0, s88
	s_nop 0
	global_load_lds_dwordx4 v140, s[58:59]
	s_nop 0
	s_mov_b32 m0, s89
	s_nop 0
	global_load_lds_dwordx4 v142, s[58:59]
	s_add_u32 s58, s66, 0x2b0080
	s_addc_u32 s59, s67, 0
	s_mov_b32 m0, s92
	s_nop 0
	global_load_lds_dwordx4 v140, s[58:59]
	s_nop 0
	s_mov_b32 m0, s93
	s_nop 0
	global_load_lds_dwordx4 v142, s[58:59]
	s_nop 0
	s_mov_b32 m0, s90
	s_nop 0
	global_load_lds_dwordx4 v1, s[62:63]
	s_nop 0
	s_mov_b32 m0, s91
	s_nop 0
	global_load_lds_dwordx4 v141, s[62:63]
	s_waitcnt vmcnt(8)
	s_waitcnt lgkmcnt(0)
	s_barrier
	s_setprio 1
	s_waitcnt lgkmcnt(7)
	v_mfma_f32_16x16x32_bf16 v[62:65], v[134:137], v[180:183], v[62:65]
	v_mfma_f32_16x16x32_bf16 v[58:61], v[156:159], v[180:183], v[58:61]
	s_waitcnt lgkmcnt(5)
	v_mfma_f32_16x16x32_bf16 v[54:57], v[164:167], v[180:183], v[54:57]
	v_mfma_f32_16x16x32_bf16 v[50:53], v[172:175], v[180:183], v[50:53]
	s_waitcnt lgkmcnt(3)
	v_mfma_f32_16x16x32_bf16 v[34:37], v[172:175], v[188:191], v[34:37]
	v_mfma_f32_16x16x32_bf16 v[38:41], v[164:167], v[188:191], v[38:41]
	s_waitcnt lgkmcnt(1)
	v_mfma_f32_16x16x32_bf16 v[42:45], v[156:159], v[188:191], v[42:45]
	v_mfma_f32_16x16x32_bf16 v[46:49], v[134:137], v[188:191], v[46:49]
	v_mfma_f32_16x16x32_bf16 v[30:33], v[134:137], v[196:199], v[30:33]
	v_mfma_f32_16x16x32_bf16 v[26:29], v[156:159], v[196:199], v[26:29]
	v_mfma_f32_16x16x32_bf16 v[22:25], v[164:167], v[196:199], v[22:25]
	v_mfma_f32_16x16x32_bf16 v[18:21], v[172:175], v[196:199], v[18:21]
	v_mfma_f32_16x16x32_bf16 v[2:5], v[172:175], v[204:207], v[2:5]
	v_mfma_f32_16x16x32_bf16 v[6:9], v[164:167], v[204:207], v[6:9]
	s_waitcnt lgkmcnt(0)
	v_mfma_f32_16x16x32_bf16 v[10:13], v[156:159], v[204:207], v[10:13]
	v_mfma_f32_16x16x32_bf16 v[14:17], v[134:137], v[204:207], v[14:17]
	s_setprio 0
	s_setprio 1
	v_mfma_f32_16x16x32_bf16 v[62:65], v[248:251], v[184:187], v[62:65]
	v_mfma_f32_16x16x32_bf16 v[58:61], v[160:163], v[184:187], v[58:61]
	v_mfma_f32_16x16x32_bf16 v[54:57], v[168:171], v[184:187], v[54:57]
	v_mfma_f32_16x16x32_bf16 v[50:53], v[176:179], v[184:187], v[50:53]
	v_mfma_f32_16x16x32_bf16 v[34:37], v[176:179], v[192:195], v[34:37]
	v_mfma_f32_16x16x32_bf16 v[38:41], v[168:171], v[192:195], v[38:41]
	v_mfma_f32_16x16x32_bf16 v[42:45], v[160:163], v[192:195], v[42:45]
	v_mfma_f32_16x16x32_bf16 v[46:49], v[248:251], v[192:195], v[46:49]
	v_mfma_f32_16x16x32_bf16 v[30:33], v[248:251], v[200:203], v[30:33]
	v_mfma_f32_16x16x32_bf16 v[26:29], v[160:163], v[200:203], v[26:29]
	v_mfma_f32_16x16x32_bf16 v[22:25], v[168:171], v[200:203], v[22:25]
	v_mfma_f32_16x16x32_bf16 v[18:21], v[176:179], v[200:203], v[18:21]
	v_mfma_f32_16x16x32_bf16 v[2:5], v[176:179], v[252:255], v[2:5]
	v_mfma_f32_16x16x32_bf16 v[6:9], v[168:171], v[252:255], v[6:9]
	v_mfma_f32_16x16x32_bf16 v[10:13], v[160:163], v[252:255], v[10:13]
	s_setprio 2
	s_barrier
	v_mfma_f32_16x16x32_bf16 v[14:17], v[248:251], v[252:255], v[14:17]
	s_setprio 0
	s_add_i32 s57, s57, 2
	s_add_u32 s53, s53, 0x100
	s_addc_u32 s54, s54, 0
	s_add_u32 s55, s55, 0x100
	s_addc_u32 s56, s56, 0
	s_add_u32 s50, s50, 0x100
	s_addc_u32 s51, s51, 0
	s_cmpk_gt_u32 s57, 0xa9
	s_cbranch_scc0 .LBB0_234
	s_and_b64 vcc, exec, s[16:17]
	s_cbranch_vccz .LBB0_237
	s_barrier

; #define PG8_STAGE(bufoff, gbase, voff) do { _Pragma("unroll") for (int _i = 0; _i < 2; ++_i) \
;         asm volatile("s_mov_b32 m0, %2\n\ts_nop 0\n\tglobal_load_lds_dwordx4 %0, %1" :: "v"((voff)[_i]), "s"((const char*)(gbase)), "s"(ldsbase + (unsigned)(bufoff) + ldsw + (unsigned)_i * 8192u) : "memory", "m0"); } while (0)
; #define PG8_LDA(dst, b, h) do { _Pragma("unroll") for (int m = 0; m < 4; ++m) _Pragma("unroll") for (int k = 0; k < 2; ++k) dst[m][k] = *(const PG8_LAS bf16x8*)(lds + PG8_SA(b, h) + aoff + m * 2048 + k * 1024); } while (0)
; #define PG8_WAIT_V(n) asm volatile("s_waitcnt vmcnt(" #n ")" ::: "memory")
; template <class Epi, class Sched, bool ALIGN_EPI = false, bool SP2 = false>
; __device__ __forceinline__ void gemm_phase(PG8_LAS unsigned char* lds, const Gemm g, const Sched& S, const Epi& E) {
;     ...
;             const bool last = (t == nt - 2);
;             const char* a1 = cA + (size_t)(t + 1) * kstep;
;             const char* a2 = last ? nA : cA + (size_t)(t + 2) * kstep; const char* b2 = last ? nB : cB + (size_t)(t + 2) * kstep;
;             const char* a3 = a2 + kstep; const char* b3 = b2 + kstep;
;             if (last && has_next) S.a_ready(nxt);
;             if constexpr (epi_has_mid<Epi>::value) { if (t == Epi::MID_T) E.mid(acc, cur, wr, wc, fr, fq); }
;             if constexpr (SP2) {
;             PG8_LDB(B0, 0, 0); PG8_LDB(B1, 0, 1); PG8_SCHED; PG8_LDA(At, 0, 0); PG8_STAGE(PG8_SA(1, 1), a1 + hstep, voffA);
;             PG8_WAIT_V(8); PG8_WAIT_L(0); PG8_BAR; PG8_MMA(0, 0, At, B0); PG8_MMA(0, 1, At, B1); PG8_BAR; PG8_SCHED;
;             PG8_LDA(At, 0, 1); PG8_STAGE(PG8_SB(0, 0), b2, voffB); PG8_STAGE(PG8_SB(0, 1), b2 + hstep, voffB); PG8_STAGE(PG8_SA(0, 0), a2, voffA);
;             PG8_WAIT_V(8); PG8_WAIT_L(0); PG8_BAR; PG8_MMA(1, 0, At, B0); PG8_MMA(1, 1, At, B1); PG8_BAR; PG8_SCHED;
;             PG8_LDB(B0, 1, 0); PG8_LDB(B1, 1, 1); PG8_SCHED; PG8_LDA(At, 1, 0); PG8_STAGE(PG8_SA(0, 1), a2 + hstep, voffA);
;             PG8_WAIT_V(8); PG8_WAIT_L(0); PG8_BAR; PG8_MMA(0, 0, At, B0); PG8_MMA(0, 1, At, B1); PG8_BAR; PG8_SCHED;
;             PG8_LDA(At, 1, 1); PG8_STAGE(PG8_SB(1, 0), b3, voffB); PG8_STAGE(PG8_SB(1, 1), b3 + hstep, voffB); PG8_STAGE(PG8_SA(1, 0), a3, voffA);
;             PG8_WAIT_V(8); PG8_WAIT_L(0); PG8_BAR; PG8_MMA(1, 0, At, B0); PG8_MMA(1, 1, At, B1); PG8_BAR; PG8_SCHED;
.LBB0_325:
	v_add_u32_e32 v138, 0x10000, v151
	ds_read_b128 v[154:157], v138
	ds_read_b128 v[158:161], v138 offset:1024
	ds_read_b128 v[162:165], v138 offset:2048
	ds_read_b128 v[166:169], v138 offset:3072
	v_add_u32_e32 v138, 0x14000, v151
	s_add_u32 s8, s82, 0x100
	ds_read_b128 v[170:173], v138
	ds_read_b128 v[174:177], v138 offset:1024
	ds_read_b128 v[178:181], v138 offset:2048
	ds_read_b128 v[182:185], v138 offset:3072
	s_addc_u32 s9, s83, 0
	s_and_b64 s[60:61], s[62:63], exec
	s_cselect_b32 s84, s54, s8
	s_cselect_b32 s85, s19, s9
	s_cselect_b32 s63, s17, s57
	s_cselect_b32 s62, s55, s56
	s_add_u32 s66, s84, 0x80
	s_addc_u32 s67, s85, 0
	s_add_u32 s76, s62, 0x80
	s_addc_u32 s77, s63, 0
	ds_read_b128 v[186:189], v152
	ds_read_b128 v[190:193], v152 offset:1024
	ds_read_b128 v[194:197], v152 offset:2048
	ds_read_b128 v[198:201], v152 offset:3072
	ds_read_b128 v[202:205], v152 offset:4096
	ds_read_b128 v[206:209], v152 offset:5120
	ds_read_b128 v[210:213], v152 offset:6144
	ds_read_b128 v[214:217], v152 offset:7168
	s_add_u32 s60, s82, 0x100080
	s_addc_u32 s61, s83, 0
	s_mov_b32 m0, s97
	s_nop 0
	global_load_lds_dwordx4 v141, s[60:61]
	s_nop 0
	s_mov_b32 m0, s70
	s_nop 0
	global_load_lds_dwordx4 v143, s[60:61]
	s_waitcnt vmcnt(8)
	s_waitcnt lgkmcnt(0)
	s_barrier
	s_setprio 1
	s_waitcnt lgkmcnt(7)
	v_mfma_f32_16x16x32_bf16 v[126:129], v[154:157], v[186:189], v[126:129]
	v_mfma_f32_16x16x32_bf16 v[122:125], v[162:165], v[186:189], v[122:125]
	s_waitcnt lgkmcnt(5)
	v_mfma_f32_16x16x32_bf16 v[118:121], v[170:173], v[186:189], v[118:121]
	v_mfma_f32_16x16x32_bf16 v[114:117], v[178:181], v[186:189], v[114:117]
	s_waitcnt lgkmcnt(3)
	v_mfma_f32_16x16x32_bf16 v[98:101], v[178:181], v[194:197], v[98:101]
	v_mfma_f32_16x16x32_bf16 v[102:105], v[170:173], v[194:197], v[102:105]
	s_waitcnt lgkmcnt(1)
	v_mfma_f32_16x16x32_bf16 v[106:109], v[162:165], v[194:197], v[106:109]
	v_mfma_f32_16x16x32_bf16 v[110:113], v[154:157], v[194:197], v[110:113]
	v_mfma_f32_16x16x32_bf16 v[94:97], v[154:157], v[202:205], v[94:97]
	v_mfma_f32_16x16x32_bf16 v[90:93], v[162:165], v[202:205], v[90:93]
	v_mfma_f32_16x16x32_bf16 v[86:89], v[170:173], v[202:205], v[86:89]
	v_mfma_f32_16x16x32_bf16 v[82:85], v[178:181], v[202:205], v[82:85]
	v_mfma_f32_16x16x32_bf16 v[66:69], v[178:181], v[210:213], v[66:69]
	v_mfma_f32_16x16x32_bf16 v[70:73], v[170:173], v[210:213], v[70:73]
	s_waitcnt lgkmcnt(0)
	v_mfma_f32_16x16x32_bf16 v[74:77], v[162:165], v[210:213], v[74:77]
	v_mfma_f32_16x16x32_bf16 v[78:81], v[154:157], v[210:213], v[78:81]
	s_setprio 0
	s_setprio 1
	v_mfma_f32_16x16x32_bf16 v[126:129], v[158:161], v[190:193], v[126:129]
	v_mfma_f32_16x16x32_bf16 v[122:125], v[166:169], v[190:193], v[122:125]
	v_mfma_f32_16x16x32_bf16 v[118:121], v[174:177], v[190:193], v[118:121]
	v_mfma_f32_16x16x32_bf16 v[114:117], v[182:185], v[190:193], v[114:117]
	v_mfma_f32_16x16x32_bf16 v[98:101], v[182:185], v[198:201], v[98:101]
	v_mfma_f32_16x16x32_bf16 v[102:105], v[174:177], v[198:201], v[102:105]
	v_mfma_f32_16x16x32_bf16 v[106:109], v[166:169], v[198:201], v[106:109]
	v_mfma_f32_16x16x32_bf16 v[110:113], v[158:161], v[198:201], v[110:113]
	v_mfma_f32_16x16x32_bf16 v[94:97], v[158:161], v[206:209], v[94:97]
	v_mfma_f32_16x16x32_bf16 v[90:93], v[166:169], v[206:209], v[90:93]
	v_mfma_f32_16x16x32_bf16 v[86:89], v[174:177], v[206:209], v[86:89]
	v_mfma_f32_16x16x32_bf16 v[82:85], v[182:185], v[206:209], v[82:85]
	v_mfma_f32_16x16x32_bf16 v[66:69], v[182:185], v[214:217], v[66:69]
	v_mfma_f32_16x16x32_bf16 v[70:73], v[174:177], v[214:217], v[70:73]
	v_mfma_f32_16x16x32_bf16 v[74:77], v[166:169], v[214:217], v[74:77]
	s_setprio 2
	s_barrier
	v_mfma_f32_16x16x32_bf16 v[78:81], v[158:161], v[214:217], v[78:81]
	s_setprio 0
	ds_read_b128 v[186:189], v152 offset:16384
	ds_read_b128 v[190:193], v152 offset:17408
	ds_read_b128 v[194:197], v152 offset:18432
	ds_read_b128 v[198:201], v152 offset:19456
	ds_read_b128 v[202:205], v152 offset:20480
	ds_read_b128 v[206:209], v152 offset:21504
	ds_read_b128 v[210:213], v152 offset:22528
	ds_read_b128 v[252:255], v152 offset:23552
	s_mov_b32 m0, s68
	s_nop 0
	global_load_lds_dwordx4 v142, s[62:63]
	s_add_u32 s60, s62, 0x100000
	s_mov_b32 m0, s69
	s_nop 0
	global_load_lds_dwordx4 v144, s[62:63]
	s_addc_u32 s61, s63, 0
	s_mov_b32 m0, s81
	s_nop 0
	global_load_lds_dwordx4 v142, s[60:61]
	s_nop 0
	s_mov_b32 m0, s86
	s_nop 0
	global_load_lds_dwordx4 v144, s[60:61]
	s_nop 0
	s_mov_b32 m0, s65
	s_nop 0
	global_load_lds_dwordx4 v141, s[84:85]
	s_nop 0
	s_mov_b32 m0, s87
	s_nop 0
	global_load_lds_dwordx4 v143, s[84:85]
	s_waitcnt vmcnt(8)
	s_waitcnt lgkmcnt(0)
	s_barrier
; #define PG8_STAGE(bufoff, gbase, voff) do { _Pragma("unroll") for (int _i = 0; _i < 2; ++_i) \
;         asm volatile("s_mov_b32 m0, %2\n\ts_nop 0\n\tglobal_load_lds_dwordx4 %0, %1" :: "v"((voff)[_i]), "s"((const char*)(gbase)), "s"(ldsbase + (unsigned)(bufoff) + ldsw + (unsigned)_i * 8192u) : "memory", "m0"); } while (0)
; #define PG8_LDA(dst, b, h) do { _Pragma("unroll") for (int m = 0; m < 4; ++m) _Pragma("unroll") for (int k = 0; k < 2; ++k) dst[m][k] = *(const PG8_LAS bf16x8*)(lds + PG8_SA(b, h) + aoff + m * 2048 + k * 1024); } while (0)
; #define PG8_LDB(dst, b, h) do { _Pragma("unroll") for (int n = 0; n < 2; ++n) _Pragma("unroll") for (int k = 0; k < 2; ++k) dst[n][k] = *(const PG8_LAS bf16x8*)(lds + PG8_SB(b, h) + boff + n * 2048 + k * 1024); } while (0)
; #define PG8_MMA(ai, bj, At, Bt) do { __builtin_amdgcn_s_setprio(1); _Pragma("unroll") for (int m = 0; m < 4; ++m) _Pragma("unroll") for (int n = 0; n < 2; ++n) _Pragma("unroll") for (int k = 0; k < 2; ++k) \
;         acc[ai][bj][m][n] = __builtin_amdgcn_mfma_f32_16x16x32_bf16(Bt[n][k], At[m][k], acc[ai][bj][m][n], 0, 0, 0); __builtin_amdgcn_s_setprio(0); } while (0)
; template <class Epi, class Sched, bool ALIGN_EPI = false, bool SP2 = false>
; __device__ __forceinline__ void gemm_phase(PG8_LAS unsigned char* lds, const Gemm g, const Sched& S, const Epi& E) {
;     ...
;             PG8_LDB(B0, 0, 0); PG8_LDB(B1, 0, 1); PG8_SCHED; PG8_LDA(At, 0, 0); PG8_STAGE(PG8_SA(1, 1), a1 + hstep, voffA);
;             PG8_WAIT_V(8); PG8_WAIT_L(0); PG8_BAR; PG8_MMA(0, 0, At, B0); PG8_MMA(0, 1, At, B1); PG8_BAR; PG8_SCHED;
;             PG8_LDA(At, 0, 1); PG8_STAGE(PG8_SB(0, 0), b2, voffB); PG8_STAGE(PG8_SB(0, 1), b2 + hstep, voffB); PG8_STAGE(PG8_SA(0, 0), a2, voffA);
;             PG8_WAIT_V(8); PG8_WAIT_L(0); PG8_BAR; PG8_MMA(1, 0, At, B0); PG8_MMA(1, 1, At, B1); PG8_BAR; PG8_SCHED;
;             PG8_LDB(B0, 1, 0); PG8_LDB(B1, 1, 1); PG8_SCHED; PG8_LDA(At, 1, 0); PG8_STAGE(PG8_SA(0, 1), a2 + hstep, voffA);
;             PG8_WAIT_V(8); PG8_WAIT_L(0); PG8_BAR; PG8_MMA(0, 0, At, B0); PG8_MMA(0, 1, At, B1); PG8_BAR; PG8_SCHED;
;             PG8_LDA(At, 1, 1); PG8_STAGE(PG8_SB(1, 0), b3, voffB); PG8_STAGE(PG8_SB(1, 1), b3 + hstep, voffB); PG8_STAGE(PG8_SA(1, 0), a3, voffA);
;             PG8_WAIT_V(8); PG8_WAIT_L(0); PG8_BAR; PG8_MMA(1, 0, At, B0); PG8_MMA(1, 1, At, B1); PG8_BAR; PG8_SCHED;
	s_setprio 1
	s_waitcnt lgkmcnt(7)
	v_mfma_f32_16x16x32_bf16 v[62:65], v[154:157], v[186:189], v[62:65]
	v_mfma_f32_16x16x32_bf16 v[58:61], v[162:165], v[186:189], v[58:61]
	s_waitcnt lgkmcnt(5)
	v_mfma_f32_16x16x32_bf16 v[54:57], v[170:173], v[186:189], v[54:57]
	v_mfma_f32_16x16x32_bf16 v[50:53], v[178:181], v[186:189], v[50:53]
	s_waitcnt lgkmcnt(3)
	v_mfma_f32_16x16x32_bf16 v[34:37], v[178:181], v[194:197], v[34:37]
	v_mfma_f32_16x16x32_bf16 v[38:41], v[170:173], v[194:197], v[38:41]
	s_waitcnt lgkmcnt(1)
	v_mfma_f32_16x16x32_bf16 v[42:45], v[162:165], v[194:197], v[42:45]
	v_mfma_f32_16x16x32_bf16 v[46:49], v[154:157], v[194:197], v[46:49]
	v_mfma_f32_16x16x32_bf16 v[30:33], v[154:157], v[202:205], v[30:33]
	v_mfma_f32_16x16x32_bf16 v[26:29], v[162:165], v[202:205], v[26:29]
	v_mfma_f32_16x16x32_bf16 v[22:25], v[170:173], v[202:205], v[22:25]
	v_mfma_f32_16x16x32_bf16 v[18:21], v[178:181], v[202:205], v[18:21]
	v_mfma_f32_16x16x32_bf16 v[2:5], v[178:181], v[210:213], v[2:5]
	v_mfma_f32_16x16x32_bf16 v[6:9], v[170:173], v[210:213], v[6:9]
	s_waitcnt lgkmcnt(0)
	v_mfma_f32_16x16x32_bf16 v[10:13], v[162:165], v[210:213], v[10:13]
	v_mfma_f32_16x16x32_bf16 v[14:17], v[154:157], v[210:213], v[14:17]
	s_setprio 0
	s_setprio 1
	v_mfma_f32_16x16x32_bf16 v[62:65], v[158:161], v[190:193], v[62:65]
	v_mfma_f32_16x16x32_bf16 v[58:61], v[166:169], v[190:193], v[58:61]
	v_mfma_f32_16x16x32_bf16 v[54:57], v[174:177], v[190:193], v[54:57]
	v_mfma_f32_16x16x32_bf16 v[50:53], v[182:185], v[190:193], v[50:53]
	v_mfma_f32_16x16x32_bf16 v[34:37], v[182:185], v[198:201], v[34:37]
	v_mfma_f32_16x16x32_bf16 v[38:41], v[174:177], v[198:201], v[38:41]
	v_mfma_f32_16x16x32_bf16 v[42:45], v[166:169], v[198:201], v[42:45]
	v_mfma_f32_16x16x32_bf16 v[46:49], v[158:161], v[198:201], v[46:49]
	v_mfma_f32_16x16x32_bf16 v[30:33], v[158:161], v[206:209], v[30:33]
	v_mfma_f32_16x16x32_bf16 v[26:29], v[166:169], v[206:209], v[26:29]
	v_mfma_f32_16x16x32_bf16 v[22:25], v[174:177], v[206:209], v[22:25]
	v_mfma_f32_16x16x32_bf16 v[18:21], v[182:185], v[206:209], v[18:21]
	v_mfma_f32_16x16x32_bf16 v[2:5], v[182:185], v[252:255], v[2:5]
	v_mfma_f32_16x16x32_bf16 v[6:9], v[174:177], v[252:255], v[6:9]
	v_mfma_f32_16x16x32_bf16 v[10:13], v[166:169], v[252:255], v[10:13]
	s_setprio 2
	s_barrier
	v_mfma_f32_16x16x32_bf16 v[14:17], v[158:161], v[252:255], v[14:17]
	s_setprio 0
	v_add_u32_e32 v138, 0x18000, v151
	ds_read_b128 v[154:157], v138
	ds_read_b128 v[248:251], v138 offset:1024
	ds_read_b128 v[162:165], v138 offset:2048
	ds_read_b128 v[166:169], v138 offset:3072
	v_add_u32_e32 v138, 0x1c000, v151
	ds_read_b128 v[170:173], v138
	ds_read_b128 v[174:177], v138 offset:1024
	ds_read_b128 v[178:181], v138 offset:2048
	ds_read_b128 v[182:185], v138 offset:3072
	ds_read_b128 v[186:189], v152 offset:32768
	ds_read_b128 v[190:193], v152 offset:33792
	ds_read_b128 v[194:197], v152 offset:34816
	ds_read_b128 v[198:201], v152 offset:35840
	ds_read_b128 v[202:205], v152 offset:36864
	ds_read_b128 v[206:209], v152 offset:37888
	ds_read_b128 v[210:213], v152 offset:38912
	ds_read_b128 v[214:217], v152 offset:39936
	s_add_u32 s60, s84, 0x100000
	s_addc_u32 s61, s85, 0
	s_mov_b32 m0, s88
	s_nop 0
	global_load_lds_dwordx4 v141, s[60:61]
	s_nop 0
	s_mov_b32 m0, s89
	s_nop 0
	global_load_lds_dwordx4 v143, s[60:61]
	s_waitcnt vmcnt(8)
	s_waitcnt lgkmcnt(0)
	s_barrier
	s_setprio 1
	s_waitcnt lgkmcnt(7)
	v_mfma_f32_16x16x32_bf16 v[126:129], v[154:157], v[186:189], v[126:129]
	v_mfma_f32_16x16x32_bf16 v[122:125], v[162:165], v[186:189], v[122:125]
	s_waitcnt lgkmcnt(5)
	v_mfma_f32_16x16x32_bf16 v[118:121], v[170:173], v[186:189], v[118:121]
	v_mfma_f32_16x16x32_bf16 v[114:117], v[178:181], v[186:189], v[114:117]
	s_waitcnt lgkmcnt(3)
	v_mfma_f32_16x16x32_bf16 v[98:101], v[178:181], v[194:197], v[98:101]
	v_mfma_f32_16x16x32_bf16 v[102:105], v[170:173], v[194:197], v[102:105]
	s_waitcnt lgkmcnt(1)
	v_mfma_f32_16x16x32_bf16 v[106:109], v[162:165], v[194:197], v[106:109]
	v_mfma_f32_16x16x32_bf16 v[110:113], v[154:157], v[194:197], v[110:113]
	v_mfma_f32_16x16x32_bf16 v[94:97], v[154:157], v[202:205], v[94:97]
	v_mfma_f32_16x16x32_bf16 v[90:93], v[162:165], v[202:205], v[90:93]
	v_mfma_f32_16x16x32_bf16 v[86:89], v[170:173], v[202:205], v[86:89]
	v_mfma_f32_16x16x32_bf16 v[82:85], v[178:181], v[202:205], v[82:85]
	v_mfma_f32_16x16x32_bf16 v[66:69], v[178:181], v[210:213], v[66:69]
	v_mfma_f32_16x16x32_bf16 v[70:73], v[170:173], v[210:213], v[70:73]
	s_waitcnt lgkmcnt(0)
	v_mfma_f32_16x16x32_bf16 v[74:77], v[162:165], v[210:213], v[74:77]
	v_mfma_f32_16x16x32_bf16 v[78:81], v[154:157], v[210:213], v[78:81]
	s_setprio 0
	s_setprio 1
	v_mfma_f32_16x16x32_bf16 v[126:129], v[248:251], v[190:193], v[126:129]
	v_mfma_f32_16x16x32_bf16 v[122:125], v[166:169], v[190:193], v[122:125]
	v_mfma_f32_16x16x32_bf16 v[118:121], v[174:177], v[190:193], v[118:121]
	v_mfma_f32_16x16x32_bf16 v[114:117], v[182:185], v[190:193], v[114:117]
	v_mfma_f32_16x16x32_bf16 v[98:101], v[182:185], v[198:201], v[98:101]
	v_mfma_f32_16x16x32_bf16 v[102:105], v[174:177], v[198:201], v[102:105]
	v_mfma_f32_16x16x32_bf16 v[106:109], v[166:169], v[198:201], v[106:109]
	v_mfma_f32_16x16x32_bf16 v[110:113], v[248:251], v[198:201], v[110:113]
	v_mfma_f32_16x16x32_bf16 v[94:97], v[248:251], v[206:209], v[94:97]
	v_mfma_f32_16x16x32_bf16 v[90:93], v[166:169], v[206:209], v[90:93]
	v_mfma_f32_16x16x32_bf16 v[86:89], v[174:177], v[206:209], v[86:89]
	v_mfma_f32_16x16x32_bf16 v[82:85], v[182:185], v[206:209], v[82:85]
	v_mfma_f32_16x16x32_bf16 v[66:69], v[182:185], v[214:217], v[66:69]
	v_mfma_f32_16x16x32_bf16 v[70:73], v[174:177], v[214:217], v[70:73]
	v_mfma_f32_16x16x32_bf16 v[74:77], v[166:169], v[214:217], v[74:77]
	s_setprio 2
	s_barrier
; #define PG8_STAGE(bufoff, gbase, voff) do { _Pragma("unroll") for (int _i = 0; _i < 2; ++_i) \
;         asm volatile("s_mov_b32 m0, %2\n\ts_nop 0\n\tglobal_load_lds_dwordx4 %0, %1" :: "v"((voff)[_i]), "s"((const char*)(gbase)), "s"(ldsbase + (unsigned)(bufoff) + ldsw + (unsigned)_i * 8192u) : "memory", "m0"); } while (0)
; #define PG8_LDA(dst, b, h) do { _Pragma("unroll") for (int m = 0; m < 4; ++m) _Pragma("unroll") for (int k = 0; k < 2; ++k) dst[m][k] = *(const PG8_LAS bf16x8*)(lds + PG8_SA(b, h) + aoff + m * 2048 + k * 1024); } while (0)
; #define PG8_BAR __builtin_amdgcn_s_barrier()
; template <class Epi, class Sched, bool ALIGN_EPI = false, bool SP2 = false>
; __device__ __forceinline__ void gemm_phase(PG8_LAS unsigned char* lds, const Gemm g, const Sched& S, const Epi& E) {
;     ...
;         for (int t = 0; t < nt; t += 2) {
;             const bool last = (t == nt - 2);
;             const char* a1 = cA + (size_t)(t + 1) * kstep;
;             const char* a2 = last ? nA : cA + (size_t)(t + 2) * kstep; const char* b2 = last ? nB : cB + (size_t)(t + 2) * kstep;
;             const char* a3 = a2 + kstep; const char* b3 = b2 + kstep;
;             if (last && has_next) S.a_ready(nxt);
;             if constexpr (epi_has_mid<Epi>::value) { if (t == Epi::MID_T) E.mid(acc, cur, wr, wc, fr, fq); }
;             if constexpr (SP2) {
;             PG8_LDB(B0, 0, 0); PG8_LDB(B1, 0, 1); PG8_SCHED; PG8_LDA(At, 0, 0); PG8_STAGE(PG8_SA(1, 1), a1 + hstep, voffA);
;             PG8_WAIT_V(8); PG8_WAIT_L(0); PG8_BAR; PG8_MMA(0, 0, At, B0); PG8_MMA(0, 1, At, B1); PG8_BAR; PG8_SCHED;
;             PG8_LDA(At, 0, 1); PG8_STAGE(PG8_SB(0, 0), b2, voffB); PG8_STAGE(PG8_SB(0, 1), b2 + hstep, voffB); PG8_STAGE(PG8_SA(0, 0), a2, voffA);
;             PG8_WAIT_V(8); PG8_WAIT_L(0); PG8_BAR; PG8_MMA(1, 0, At, B0); PG8_MMA(1, 1, At, B1); PG8_BAR; PG8_SCHED;
;             PG8_LDB(B0, 1, 0); PG8_LDB(B1, 1, 1); PG8_SCHED; PG8_LDA(At, 1, 0); PG8_STAGE(PG8_SA(0, 1), a2 + hstep, voffA);
;             PG8_WAIT_V(8); PG8_WAIT_L(0); PG8_BAR; PG8_MMA(0, 0, At, B0); PG8_MMA(0, 1, At, B1); PG8_BAR; PG8_SCHED;
;             PG8_LDA(At, 1, 1); PG8_STAGE(PG8_SB(1, 0), b3, voffB); PG8_STAGE(PG8_SB(1, 1), b3 + hstep, voffB); PG8_STAGE(PG8_SA(1, 0), a3, voffA);
;             PG8_WAIT_V(8); PG8_WAIT_L(0); PG8_BAR; PG8_MMA(1, 0, At, B0); PG8_MMA(1, 1, At, B1); PG8_BAR; PG8_SCHED;
	v_mfma_f32_16x16x32_bf16 v[78:81], v[248:251], v[214:217], v[78:81]
	s_setprio 0
	ds_read_b128 v[186:189], v152 offset:49152
	ds_read_b128 v[190:193], v152 offset:50176
	ds_read_b128 v[194:197], v152 offset:51200
	ds_read_b128 v[198:201], v152 offset:52224
	ds_read_b128 v[202:205], v152 offset:53248
	ds_read_b128 v[206:209], v152 offset:54272
	ds_read_b128 v[210:213], v152 offset:55296
	ds_read_b128 v[252:255], v152 offset:56320
	s_mov_b32 m0, s90
	s_nop 0
	global_load_lds_dwordx4 v142, s[76:77]
	s_add_u32 s60, s62, 0x100080
	s_mov_b32 m0, s91
	s_nop 0
	global_load_lds_dwordx4 v144, s[76:77]
	s_addc_u32 s61, s63, 0
	s_mov_b32 m0, s95
	s_nop 0
	global_load_lds_dwordx4 v142, s[60:61]
	s_nop 0
	s_mov_b32 m0, s96
	s_nop 0
	global_load_lds_dwordx4 v144, s[60:61]
	s_nop 0
	s_mov_b32 m0, s92
	s_nop 0
	global_load_lds_dwordx4 v141, s[66:67]
	s_nop 0
	s_mov_b32 m0, s94
	s_nop 0
	global_load_lds_dwordx4 v143, s[66:67]
	s_waitcnt vmcnt(8)
	s_waitcnt lgkmcnt(0)
	s_barrier
	s_setprio 1
	s_waitcnt lgkmcnt(7)
	v_mfma_f32_16x16x32_bf16 v[62:65], v[154:157], v[186:189], v[62:65]
	v_mfma_f32_16x16x32_bf16 v[58:61], v[162:165], v[186:189], v[58:61]
	s_waitcnt lgkmcnt(5)
	v_mfma_f32_16x16x32_bf16 v[54:57], v[170:173], v[186:189], v[54:57]
	v_mfma_f32_16x16x32_bf16 v[50:53], v[178:181], v[186:189], v[50:53]
	s_waitcnt lgkmcnt(3)
	v_mfma_f32_16x16x32_bf16 v[34:37], v[178:181], v[194:197], v[34:37]
	v_mfma_f32_16x16x32_bf16 v[38:41], v[170:173], v[194:197], v[38:41]
	s_waitcnt lgkmcnt(1)
	v_mfma_f32_16x16x32_bf16 v[42:45], v[162:165], v[194:197], v[42:45]
	v_mfma_f32_16x16x32_bf16 v[46:49], v[154:157], v[194:197], v[46:49]
	v_mfma_f32_16x16x32_bf16 v[30:33], v[154:157], v[202:205], v[30:33]
	v_mfma_f32_16x16x32_bf16 v[26:29], v[162:165], v[202:205], v[26:29]
	v_mfma_f32_16x16x32_bf16 v[22:25], v[170:173], v[202:205], v[22:25]
	v_mfma_f32_16x16x32_bf16 v[18:21], v[178:181], v[202:205], v[18:21]
	v_mfma_f32_16x16x32_bf16 v[2:5], v[178:181], v[210:213], v[2:5]
	v_mfma_f32_16x16x32_bf16 v[6:9], v[170:173], v[210:213], v[6:9]
	s_waitcnt lgkmcnt(0)
	v_mfma_f32_16x16x32_bf16 v[10:13], v[162:165], v[210:213], v[10:13]
	v_mfma_f32_16x16x32_bf16 v[14:17], v[154:157], v[210:213], v[14:17]
	s_setprio 0
	s_setprio 1
	v_mfma_f32_16x16x32_bf16 v[62:65], v[248:251], v[190:193], v[62:65]
	v_mfma_f32_16x16x32_bf16 v[58:61], v[166:169], v[190:193], v[58:61]
	v_mfma_f32_16x16x32_bf16 v[54:57], v[174:177], v[190:193], v[54:57]
	v_mfma_f32_16x16x32_bf16 v[50:53], v[182:185], v[190:193], v[50:53]
	v_mfma_f32_16x16x32_bf16 v[34:37], v[182:185], v[198:201], v[34:37]
	v_mfma_f32_16x16x32_bf16 v[38:41], v[174:177], v[198:201], v[38:41]
	v_mfma_f32_16x16x32_bf16 v[42:45], v[166:169], v[198:201], v[42:45]
	v_mfma_f32_16x16x32_bf16 v[46:49], v[248:251], v[198:201], v[46:49]
	v_mfma_f32_16x16x32_bf16 v[30:33], v[248:251], v[206:209], v[30:33]
	v_mfma_f32_16x16x32_bf16 v[26:29], v[166:169], v[206:209], v[26:29]
	v_mfma_f32_16x16x32_bf16 v[22:25], v[174:177], v[206:209], v[22:25]
	v_mfma_f32_16x16x32_bf16 v[18:21], v[182:185], v[206:209], v[18:21]
	v_mfma_f32_16x16x32_bf16 v[2:5], v[182:185], v[252:255], v[2:5]
	v_mfma_f32_16x16x32_bf16 v[6:9], v[174:177], v[252:255], v[6:9]
	v_mfma_f32_16x16x32_bf16 v[10:13], v[166:169], v[252:255], v[10:13]
	s_setprio 2
	s_barrier
	v_mfma_f32_16x16x32_bf16 v[14:17], v[248:251], v[252:255], v[14:17]
	s_setprio 0
	s_add_i32 s58, s58, 2
	s_add_u32 s56, s56, 0x100
	s_addc_u32 s57, s57, 0
	s_cmp_gt_u32 s58, 61
	s_cbranch_scc1 .LBB0_316
	s_mov_b64 s[82:83], s[8:9]
	s_branch .LBB0_320

; #define PG8_STAGE(bufoff, gbase, voff) do { _Pragma("unroll") for (int _i = 0; _i < 2; ++_i) \
;         asm volatile("s_mov_b32 m0, %2\n\ts_nop 0\n\tglobal_load_lds_dwordx4 %0, %1" :: "v"((voff)[_i]), "s"((const char*)(gbase)), "s"(ldsbase + (unsigned)(bufoff) + ldsw + (unsigned)_i * 8192u) : "memory", "m0"); } while (0)
; #define PG8_LDA(dst, b, h) do { _Pragma("unroll") for (int m = 0; m < 4; ++m) _Pragma("unroll") for (int k = 0; k < 2; ++k) dst[m][k] = *(const PG8_LAS bf16x8*)(lds + PG8_SA(b, h) + aoff + m * 2048 + k * 1024); } while (0)
; #define PG8_WAIT_V(n) asm volatile("s_waitcnt vmcnt(" #n ")" ::: "memory")
; template <class Epi, class Sched, bool ALIGN_EPI = false, bool SP2 = false>
; __device__ __forceinline__ void gemm_phase(PG8_LAS unsigned char* lds, const Gemm g, const Sched& S, const Epi& E) {
;     ...
;             const bool last = (t == nt - 2);
;             const char* a1 = cA + (size_t)(t + 1) * kstep;
;             const char* a2 = last ? nA : cA + (size_t)(t + 2) * kstep; const char* b2 = last ? nB : cB + (size_t)(t + 2) * kstep;
;             const char* a3 = a2 + kstep; const char* b3 = b2 + kstep;
;             if (last && has_next) S.a_ready(nxt);
;             if constexpr (epi_has_mid<Epi>::value) { if (t == Epi::MID_T) E.mid(acc, cur, wr, wc, fr, fq); }
;             if constexpr (SP2) {
;             PG8_LDB(B0, 0, 0); PG8_LDB(B1, 0, 1); PG8_SCHED; PG8_LDA(At, 0, 0); PG8_STAGE(PG8_SA(1, 1), a1 + hstep, voffA);
;             PG8_WAIT_V(8); PG8_WAIT_L(0); PG8_BAR; PG8_MMA(0, 0, At, B0); PG8_MMA(0, 1, At, B1); PG8_BAR; PG8_SCHED;
;             PG8_LDA(At, 0, 1); PG8_STAGE(PG8_SB(0, 0), b2, voffB); PG8_STAGE(PG8_SB(0, 1), b2 + hstep, voffB); PG8_STAGE(PG8_SA(0, 0), a2, voffA);
;             PG8_WAIT_V(8); PG8_WAIT_L(0); PG8_BAR; PG8_MMA(1, 0, At, B0); PG8_MMA(1, 1, At, B1); PG8_BAR; PG8_SCHED;
;             PG8_LDB(B0, 1, 0); PG8_LDB(B1, 1, 1); PG8_SCHED; PG8_LDA(At, 1, 0); PG8_STAGE(PG8_SA(0, 1), a2 + hstep, voffA);
;             PG8_WAIT_V(8); PG8_WAIT_L(0); PG8_BAR; PG8_MMA(0, 0, At, B0); PG8_MMA(0, 1, At, B1); PG8_BAR; PG8_SCHED;
;             PG8_LDA(At, 1, 1); PG8_STAGE(PG8_SB(1, 0), b3, voffB); PG8_STAGE(PG8_SB(1, 1), b3 + hstep, voffB); PG8_STAGE(PG8_SA(1, 0), a3, voffA);
;             PG8_WAIT_V(8); PG8_WAIT_L(0); PG8_BAR; PG8_MMA(1, 0, At, B0); PG8_MMA(1, 1, At, B1); PG8_BAR; PG8_SCHED;
.LBB0_698:
	ds_read_b128 v[134:137], v145
	ds_read_b128 v[152:155], v145 offset:1024
	ds_read_b128 v[156:159], v145 offset:2048
	ds_read_b128 v[160:163], v145 offset:3072
	ds_read_b128 v[164:167], v146
	ds_read_b128 v[168:171], v146 offset:1024
	ds_read_b128 v[172:175], v146 offset:2048
	ds_read_b128 v[176:179], v146 offset:3072
	s_cmp_eq_u32 s69, 60
	s_cselect_b32 s48, s41, s53
	s_cselect_b32 s49, s19, s58
	s_cselect_b32 s46, s52, s59
	s_cselect_b32 s47, s17, s68
	s_add_u32 s44, s48, 0x80
	s_addc_u32 s45, s49, 0
	ds_read_b128 v[180:183], v147
	ds_read_b128 v[184:187], v147 offset:1024
	ds_read_b128 v[188:191], v147 offset:2048
	ds_read_b128 v[192:195], v147 offset:3072
	ds_read_b128 v[196:199], v147 offset:4096
	ds_read_b128 v[200:203], v147 offset:5120
	ds_read_b128 v[204:207], v147 offset:6144
	ds_read_b128 v[208:211], v147 offset:7168
	s_mov_b32 m0, s67
	s_nop 0
	global_load_lds_dwordx4 v1, s[42:43]
	s_nop 0
	s_mov_b32 m0, s74
	s_nop 0
	global_load_lds_dwordx4 v141, s[42:43]
	s_waitcnt vmcnt(8)
	s_waitcnt lgkmcnt(0)
	s_barrier
	s_setprio 1
	s_waitcnt lgkmcnt(7)
	v_mfma_f32_16x16x32_bf16 v[126:129], v[134:137], v[180:183], v[126:129]
	v_mfma_f32_16x16x32_bf16 v[122:125], v[156:159], v[180:183], v[122:125]
	s_waitcnt lgkmcnt(5)
	v_mfma_f32_16x16x32_bf16 v[118:121], v[164:167], v[180:183], v[118:121]
	v_mfma_f32_16x16x32_bf16 v[114:117], v[172:175], v[180:183], v[114:117]
	s_waitcnt lgkmcnt(3)
	v_mfma_f32_16x16x32_bf16 v[98:101], v[172:175], v[188:191], v[98:101]
	v_mfma_f32_16x16x32_bf16 v[102:105], v[164:167], v[188:191], v[102:105]
	s_waitcnt lgkmcnt(1)
	v_mfma_f32_16x16x32_bf16 v[106:109], v[156:159], v[188:191], v[106:109]
	v_mfma_f32_16x16x32_bf16 v[110:113], v[134:137], v[188:191], v[110:113]
	v_mfma_f32_16x16x32_bf16 v[94:97], v[134:137], v[196:199], v[94:97]
	v_mfma_f32_16x16x32_bf16 v[90:93], v[156:159], v[196:199], v[90:93]
	v_mfma_f32_16x16x32_bf16 v[86:89], v[164:167], v[196:199], v[86:89]
	v_mfma_f32_16x16x32_bf16 v[82:85], v[172:175], v[196:199], v[82:85]
	v_mfma_f32_16x16x32_bf16 v[66:69], v[172:175], v[204:207], v[66:69]
	v_mfma_f32_16x16x32_bf16 v[70:73], v[164:167], v[204:207], v[70:73]
	s_waitcnt lgkmcnt(0)
	v_mfma_f32_16x16x32_bf16 v[74:77], v[156:159], v[204:207], v[74:77]
	v_mfma_f32_16x16x32_bf16 v[78:81], v[134:137], v[204:207], v[78:81]
	s_setprio 0
	s_setprio 1
	v_mfma_f32_16x16x32_bf16 v[126:129], v[152:155], v[184:187], v[126:129]
	v_mfma_f32_16x16x32_bf16 v[122:125], v[160:163], v[184:187], v[122:125]
	v_mfma_f32_16x16x32_bf16 v[118:121], v[168:171], v[184:187], v[118:121]
	v_mfma_f32_16x16x32_bf16 v[114:117], v[176:179], v[184:187], v[114:117]
	v_mfma_f32_16x16x32_bf16 v[98:101], v[176:179], v[192:195], v[98:101]
	v_mfma_f32_16x16x32_bf16 v[102:105], v[168:171], v[192:195], v[102:105]
	v_mfma_f32_16x16x32_bf16 v[106:109], v[160:163], v[192:195], v[106:109]
	v_mfma_f32_16x16x32_bf16 v[110:113], v[152:155], v[192:195], v[110:113]
	v_mfma_f32_16x16x32_bf16 v[94:97], v[152:155], v[200:203], v[94:97]
	v_mfma_f32_16x16x32_bf16 v[90:93], v[160:163], v[200:203], v[90:93]
	v_mfma_f32_16x16x32_bf16 v[86:89], v[168:171], v[200:203], v[86:89]
	v_mfma_f32_16x16x32_bf16 v[82:85], v[176:179], v[200:203], v[82:85]
	v_mfma_f32_16x16x32_bf16 v[66:69], v[176:179], v[208:211], v[66:69]
	v_mfma_f32_16x16x32_bf16 v[70:73], v[168:171], v[208:211], v[70:73]
	v_mfma_f32_16x16x32_bf16 v[74:77], v[160:163], v[208:211], v[74:77]
	s_setprio 2
	s_barrier
	v_mfma_f32_16x16x32_bf16 v[78:81], v[152:155], v[208:211], v[78:81]
	s_setprio 0
	ds_read_b128 v[180:183], v147 offset:16384
	ds_read_b128 v[184:187], v147 offset:17408
	ds_read_b128 v[188:191], v147 offset:18432
	ds_read_b128 v[192:195], v147 offset:19456
	ds_read_b128 v[196:199], v147 offset:20480
	ds_read_b128 v[200:203], v147 offset:21504
	ds_read_b128 v[204:207], v147 offset:22528
	ds_read_b128 v[252:255], v147 offset:23552
	s_mov_b32 m0, s35
	s_nop 0
	global_load_lds_dwordx4 v140, s[46:47]
	s_add_u32 s70, s46, 0x100000
	s_mov_b32 m0, s50
	s_nop 0
	global_load_lds_dwordx4 v142, s[46:47]
	s_addc_u32 s71, s47, 0
	s_mov_b32 m0, s51
	s_nop 0
	global_load_lds_dwordx4 v140, s[70:71]
	s_nop 0
	s_mov_b32 m0, s54
	s_nop 0
	global_load_lds_dwordx4 v142, s[70:71]
	s_nop 0
	s_mov_b32 m0, s3
	s_nop 0
	global_load_lds_dwordx4 v1, s[48:49]
	s_nop 0
	s_mov_b32 m0, s55
	s_nop 0
	global_load_lds_dwordx4 v141, s[48:49]
	s_waitcnt vmcnt(8)
	s_waitcnt lgkmcnt(0)
	s_barrier
	s_setprio 1
	s_waitcnt lgkmcnt(7)
	v_mfma_f32_16x16x32_bf16 v[62:65], v[134:137], v[180:183], v[62:65]
	v_mfma_f32_16x16x32_bf16 v[58:61], v[156:159], v[180:183], v[58:61]
	s_waitcnt lgkmcnt(5)
	v_mfma_f32_16x16x32_bf16 v[54:57], v[164:167], v[180:183], v[54:57]
	v_mfma_f32_16x16x32_bf16 v[50:53], v[172:175], v[180:183], v[50:53]
	s_waitcnt lgkmcnt(3)
	v_mfma_f32_16x16x32_bf16 v[34:37], v[172:175], v[188:191], v[34:37]
	v_mfma_f32_16x16x32_bf16 v[38:41], v[164:167], v[188:191], v[38:41]
	s_waitcnt lgkmcnt(1)
	v_mfma_f32_16x16x32_bf16 v[42:45], v[156:159], v[188:191], v[42:45]
	v_mfma_f32_16x16x32_bf16 v[46:49], v[134:137], v[188:191], v[46:49]
	v_mfma_f32_16x16x32_bf16 v[30:33], v[134:137], v[196:199], v[30:33]
	v_mfma_f32_16x16x32_bf16 v[26:29], v[156:159], v[196:199], v[26:29]
	v_mfma_f32_16x16x32_bf16 v[22:25], v[164:167], v[196:199], v[22:25]
	v_mfma_f32_16x16x32_bf16 v[18:21], v[172:175], v[196:199], v[18:21]
	v_mfma_f32_16x16x32_bf16 v[2:5], v[172:175], v[204:207], v[2:5]
	v_mfma_f32_16x16x32_bf16 v[6:9], v[164:167], v[204:207], v[6:9]
	s_waitcnt lgkmcnt(0)
	v_mfma_f32_16x16x32_bf16 v[10:13], v[156:159], v[204:207], v[10:13]
	v_mfma_f32_16x16x32_bf16 v[14:17], v[134:137], v[204:207], v[14:17]
	s_setprio 0
	s_setprio 1
	v_mfma_f32_16x16x32_bf16 v[62:65], v[152:155], v[184:187], v[62:65]
	v_mfma_f32_16x16x32_bf16 v[58:61], v[160:163], v[184:187], v[58:61]
	v_mfma_f32_16x16x32_bf16 v[54:57], v[168:171], v[184:187], v[54:57]
	v_mfma_f32_16x16x32_bf16 v[50:53], v[176:179], v[184:187], v[50:53]
	v_mfma_f32_16x16x32_bf16 v[34:37], v[176:179], v[192:195], v[34:37]
	v_mfma_f32_16x16x32_bf16 v[38:41], v[168:171], v[192:195], v[38:41]
	v_mfma_f32_16x16x32_bf16 v[42:45], v[160:163], v[192:195], v[42:45]
	v_mfma_f32_16x16x32_bf16 v[46:49], v[152:155], v[192:195], v[46:49]
	v_mfma_f32_16x16x32_bf16 v[30:33], v[152:155], v[200:203], v[30:33]
	v_mfma_f32_16x16x32_bf16 v[26:29], v[160:163], v[200:203], v[26:29]
	v_mfma_f32_16x16x32_bf16 v[22:25], v[168:171], v[200:203], v[22:25]
	v_mfma_f32_16x16x32_bf16 v[18:21], v[176:179], v[200:203], v[18:21]
	v_mfma_f32_16x16x32_bf16 v[2:5], v[176:179], v[252:255], v[2:5]
	v_mfma_f32_16x16x32_bf16 v[6:9], v[168:171], v[252:255], v[6:9]
	v_mfma_f32_16x16x32_bf16 v[10:13], v[160:163], v[252:255], v[10:13]
	s_setprio 2
	s_barrier
; #define PG8_STAGE(bufoff, gbase, voff) do { _Pragma("unroll") for (int _i = 0; _i < 2; ++_i) \
;         asm volatile("s_mov_b32 m0, %2\n\ts_nop 0\n\tglobal_load_lds_dwordx4 %0, %1" :: "v"((voff)[_i]), "s"((const char*)(gbase)), "s"(ldsbase + (unsigned)(bufoff) + ldsw + (unsigned)_i * 8192u) : "memory", "m0"); } while (0)
; #define PG8_LDA(dst, b, h) do { _Pragma("unroll") for (int m = 0; m < 4; ++m) _Pragma("unroll") for (int k = 0; k < 2; ++k) dst[m][k] = *(const PG8_LAS bf16x8*)(lds + PG8_SA(b, h) + aoff + m * 2048 + k * 1024); } while (0)
; #define PG8_LDB(dst, b, h) do { _Pragma("unroll") for (int n = 0; n < 2; ++n) _Pragma("unroll") for (int k = 0; k < 2; ++k) dst[n][k] = *(const PG8_LAS bf16x8*)(lds + PG8_SB(b, h) + boff + n * 2048 + k * 1024); } while (0)
; #define PG8_MMA(ai, bj, At, Bt) do { __builtin_amdgcn_s_setprio(1); _Pragma("unroll") for (int m = 0; m < 4; ++m) _Pragma("unroll") for (int n = 0; n < 2; ++n) _Pragma("unroll") for (int k = 0; k < 2; ++k) \
;         acc[ai][bj][m][n] = __builtin_amdgcn_mfma_f32_16x16x32_bf16(Bt[n][k], At[m][k], acc[ai][bj][m][n], 0, 0, 0); __builtin_amdgcn_s_setprio(0); } while (0)
; template <class Epi, class Sched, bool ALIGN_EPI = false, bool SP2 = false>
; __device__ __forceinline__ void gemm_phase(PG8_LAS unsigned char* lds, const Gemm g, const Sched& S, const Epi& E) {
;     ...
;             PG8_LDB(B0, 0, 0); PG8_LDB(B1, 0, 1); PG8_SCHED; PG8_LDA(At, 0, 0); PG8_STAGE(PG8_SA(1, 1), a1 + hstep, voffA);
;             PG8_WAIT_V(8); PG8_WAIT_L(0); PG8_BAR; PG8_MMA(0, 0, At, B0); PG8_MMA(0, 1, At, B1); PG8_BAR; PG8_SCHED;
;             PG8_LDA(At, 0, 1); PG8_STAGE(PG8_SB(0, 0), b2, voffB); PG8_STAGE(PG8_SB(0, 1), b2 + hstep, voffB); PG8_STAGE(PG8_SA(0, 0), a2, voffA);
;             PG8_WAIT_V(8); PG8_WAIT_L(0); PG8_BAR; PG8_MMA(1, 0, At, B0); PG8_MMA(1, 1, At, B1); PG8_BAR; PG8_SCHED;
;             PG8_LDB(B0, 1, 0); PG8_LDB(B1, 1, 1); PG8_SCHED; PG8_LDA(At, 1, 0); PG8_STAGE(PG8_SA(0, 1), a2 + hstep, voffA);
;             PG8_WAIT_V(8); PG8_WAIT_L(0); PG8_BAR; PG8_MMA(0, 0, At, B0); PG8_MMA(0, 1, At, B1); PG8_BAR; PG8_SCHED;
;             PG8_LDA(At, 1, 1); PG8_STAGE(PG8_SB(1, 0), b3, voffB); PG8_STAGE(PG8_SB(1, 1), b3 + hstep, voffB); PG8_STAGE(PG8_SA(1, 0), a3, voffA);
;             PG8_WAIT_V(8); PG8_WAIT_L(0); PG8_BAR; PG8_MMA(1, 0, At, B0); PG8_MMA(1, 1, At, B1); PG8_BAR; PG8_SCHED;
	v_mfma_f32_16x16x32_bf16 v[14:17], v[152:155], v[252:255], v[14:17]
	s_setprio 0
	ds_read_b128 v[134:137], v148
	ds_read_b128 v[248:251], v148 offset:1024
	ds_read_b128 v[156:159], v148 offset:2048
	ds_read_b128 v[160:163], v148 offset:3072
	ds_read_b128 v[164:167], v149
	ds_read_b128 v[168:171], v149 offset:1024
	ds_read_b128 v[172:175], v149 offset:2048
	ds_read_b128 v[176:179], v149 offset:3072
	ds_read_b128 v[180:183], v147 offset:32768
	ds_read_b128 v[184:187], v147 offset:33792
	ds_read_b128 v[188:191], v147 offset:34816
	ds_read_b128 v[192:195], v147 offset:35840
	ds_read_b128 v[196:199], v147 offset:36864
	ds_read_b128 v[200:203], v147 offset:37888
	ds_read_b128 v[204:207], v147 offset:38912
	ds_read_b128 v[208:211], v147 offset:39936
	s_add_u32 s48, s48, 0x100000
	s_addc_u32 s49, s49, 0
	s_mov_b32 m0, s56
	s_nop 0
	global_load_lds_dwordx4 v1, s[48:49]
	s_nop 0
	s_mov_b32 m0, s57
	s_nop 0
	global_load_lds_dwordx4 v141, s[48:49]
	s_waitcnt vmcnt(8)
	s_waitcnt lgkmcnt(0)
	s_barrier
	s_setprio 1
	s_waitcnt lgkmcnt(7)
	v_mfma_f32_16x16x32_bf16 v[126:129], v[134:137], v[180:183], v[126:129]
	v_mfma_f32_16x16x32_bf16 v[122:125], v[156:159], v[180:183], v[122:125]
	s_waitcnt lgkmcnt(5)
	v_mfma_f32_16x16x32_bf16 v[118:121], v[164:167], v[180:183], v[118:121]
	v_mfma_f32_16x16x32_bf16 v[114:117], v[172:175], v[180:183], v[114:117]
	s_waitcnt lgkmcnt(3)
	v_mfma_f32_16x16x32_bf16 v[98:101], v[172:175], v[188:191], v[98:101]
	v_mfma_f32_16x16x32_bf16 v[102:105], v[164:167], v[188:191], v[102:105]
	s_waitcnt lgkmcnt(1)
	v_mfma_f32_16x16x32_bf16 v[106:109], v[156:159], v[188:191], v[106:109]
	v_mfma_f32_16x16x32_bf16 v[110:113], v[134:137], v[188:191], v[110:113]
	v_mfma_f32_16x16x32_bf16 v[94:97], v[134:137], v[196:199], v[94:97]
	v_mfma_f32_16x16x32_bf16 v[90:93], v[156:159], v[196:199], v[90:93]
	v_mfma_f32_16x16x32_bf16 v[86:89], v[164:167], v[196:199], v[86:89]
	v_mfma_f32_16x16x32_bf16 v[82:85], v[172:175], v[196:199], v[82:85]
	v_mfma_f32_16x16x32_bf16 v[66:69], v[172:175], v[204:207], v[66:69]
	v_mfma_f32_16x16x32_bf16 v[70:73], v[164:167], v[204:207], v[70:73]
	s_waitcnt lgkmcnt(0)
	v_mfma_f32_16x16x32_bf16 v[74:77], v[156:159], v[204:207], v[74:77]
	v_mfma_f32_16x16x32_bf16 v[78:81], v[134:137], v[204:207], v[78:81]
	s_setprio 0
	s_setprio 1
	v_mfma_f32_16x16x32_bf16 v[126:129], v[248:251], v[184:187], v[126:129]
	v_mfma_f32_16x16x32_bf16 v[122:125], v[160:163], v[184:187], v[122:125]
	v_mfma_f32_16x16x32_bf16 v[118:121], v[168:171], v[184:187], v[118:121]
	v_mfma_f32_16x16x32_bf16 v[114:117], v[176:179], v[184:187], v[114:117]
	v_mfma_f32_16x16x32_bf16 v[98:101], v[176:179], v[192:195], v[98:101]
	v_mfma_f32_16x16x32_bf16 v[102:105], v[168:171], v[192:195], v[102:105]
	v_mfma_f32_16x16x32_bf16 v[106:109], v[160:163], v[192:195], v[106:109]
	v_mfma_f32_16x16x32_bf16 v[110:113], v[248:251], v[192:195], v[110:113]
	v_mfma_f32_16x16x32_bf16 v[94:97], v[248:251], v[200:203], v[94:97]
	v_mfma_f32_16x16x32_bf16 v[90:93], v[160:163], v[200:203], v[90:93]
	v_mfma_f32_16x16x32_bf16 v[86:89], v[168:171], v[200:203], v[86:89]
	v_mfma_f32_16x16x32_bf16 v[82:85], v[176:179], v[200:203], v[82:85]
	v_mfma_f32_16x16x32_bf16 v[66:69], v[176:179], v[208:211], v[66:69]
	v_mfma_f32_16x16x32_bf16 v[70:73], v[168:171], v[208:211], v[70:73]
	v_mfma_f32_16x16x32_bf16 v[74:77], v[160:163], v[208:211], v[74:77]
	s_setprio 2
	s_barrier
; #define PG8_STAGE(bufoff, gbase, voff) do { _Pragma("unroll") for (int _i = 0; _i < 2; ++_i) \
;         asm volatile("s_mov_b32 m0, %2\n\ts_nop 0\n\tglobal_load_lds_dwordx4 %0, %1" :: "v"((voff)[_i]), "s"((const char*)(gbase)), "s"(ldsbase + (unsigned)(bufoff) + ldsw + (unsigned)_i * 8192u) : "memory", "m0"); } while (0)
; #define PG8_LDA(dst, b, h) do { _Pragma("unroll") for (int m = 0; m < 4; ++m) _Pragma("unroll") for (int k = 0; k < 2; ++k) dst[m][k] = *(const PG8_LAS bf16x8*)(lds + PG8_SA(b, h) + aoff + m * 2048 + k * 1024); } while (0)
; #define PG8_BAR __builtin_amdgcn_s_barrier()
; template <class Epi, class Sched, bool ALIGN_EPI = false, bool SP2 = false>
; __device__ __forceinline__ void gemm_phase(PG8_LAS unsigned char* lds, const Gemm g, const Sched& S, const Epi& E) {
;     ...
;         for (int t = 0; t < nt; t += 2) {
;             const bool last = (t == nt - 2);
;             const char* a1 = cA + (size_t)(t + 1) * kstep;
;             const char* a2 = last ? nA : cA + (size_t)(t + 2) * kstep; const char* b2 = last ? nB : cB + (size_t)(t + 2) * kstep;
;             const char* a3 = a2 + kstep; const char* b3 = b2 + kstep;
;             if (last && has_next) S.a_ready(nxt);
;             if constexpr (epi_has_mid<Epi>::value) { if (t == Epi::MID_T) E.mid(acc, cur, wr, wc, fr, fq); }
;             if constexpr (SP2) {
;             PG8_LDB(B0, 0, 0); PG8_LDB(B1, 0, 1); PG8_SCHED; PG8_LDA(At, 0, 0); PG8_STAGE(PG8_SA(1, 1), a1 + hstep, voffA);
;             PG8_WAIT_V(8); PG8_WAIT_L(0); PG8_BAR; PG8_MMA(0, 0, At, B0); PG8_MMA(0, 1, At, B1); PG8_BAR; PG8_SCHED;
;             PG8_LDA(At, 0, 1); PG8_STAGE(PG8_SB(0, 0), b2, voffB); PG8_STAGE(PG8_SB(0, 1), b2 + hstep, voffB); PG8_STAGE(PG8_SA(0, 0), a2, voffA);
;             PG8_WAIT_V(8); PG8_WAIT_L(0); PG8_BAR; PG8_MMA(1, 0, At, B0); PG8_MMA(1, 1, At, B1); PG8_BAR; PG8_SCHED;
;             PG8_LDB(B0, 1, 0); PG8_LDB(B1, 1, 1); PG8_SCHED; PG8_LDA(At, 1, 0); PG8_STAGE(PG8_SA(0, 1), a2 + hstep, voffA);
;             PG8_WAIT_V(8); PG8_WAIT_L(0); PG8_BAR; PG8_MMA(0, 0, At, B0); PG8_MMA(0, 1, At, B1); PG8_BAR; PG8_SCHED;
;             PG8_LDA(At, 1, 1); PG8_STAGE(PG8_SB(1, 0), b3, voffB); PG8_STAGE(PG8_SB(1, 1), b3 + hstep, voffB); PG8_STAGE(PG8_SA(1, 0), a3, voffA);
;             PG8_WAIT_V(8); PG8_WAIT_L(0); PG8_BAR; PG8_MMA(1, 0, At, B0); PG8_MMA(1, 1, At, B1); PG8_BAR; PG8_SCHED;
	v_mfma_f32_16x16x32_bf16 v[78:81], v[248:251], v[208:211], v[78:81]
	s_setprio 0
	ds_read_b128 v[180:183], v147 offset:49152
	ds_read_b128 v[184:187], v147 offset:50176
	ds_read_b128 v[188:191], v147 offset:51200
	ds_read_b128 v[192:195], v147 offset:52224
	ds_read_b128 v[196:199], v147 offset:53248
	ds_read_b128 v[200:203], v147 offset:54272
	ds_read_b128 v[204:207], v147 offset:55296
	ds_read_b128 v[252:255], v147 offset:56320
	s_add_u32 s48, s46, 0x80
	s_addc_u32 s49, s47, 0
	s_mov_b32 m0, s61
	s_nop 0
	global_load_lds_dwordx4 v140, s[48:49]
	s_add_u32 s46, s46, 0x100080
	s_mov_b32 m0, s62
	s_nop 0
	global_load_lds_dwordx4 v142, s[48:49]
	s_addc_u32 s47, s47, 0
	s_mov_b32 m0, s65
	s_nop 0
	global_load_lds_dwordx4 v140, s[46:47]
	s_nop 0
	s_mov_b32 m0, s66
	s_nop 0
	global_load_lds_dwordx4 v142, s[46:47]
	s_nop 0
	s_mov_b32 m0, s63
	s_nop 0
	global_load_lds_dwordx4 v1, s[44:45]
	s_nop 0
	s_mov_b32 m0, s64
	s_nop 0
	global_load_lds_dwordx4 v141, s[44:45]
	s_waitcnt vmcnt(8)
	s_waitcnt lgkmcnt(0)
	s_barrier
	s_setprio 1
	s_waitcnt lgkmcnt(7)
	v_mfma_f32_16x16x32_bf16 v[62:65], v[134:137], v[180:183], v[62:65]
	v_mfma_f32_16x16x32_bf16 v[58:61], v[156:159], v[180:183], v[58:61]
	s_waitcnt lgkmcnt(5)
	v_mfma_f32_16x16x32_bf16 v[54:57], v[164:167], v[180:183], v[54:57]
	v_mfma_f32_16x16x32_bf16 v[50:53], v[172:175], v[180:183], v[50:53]
	s_waitcnt lgkmcnt(3)
	v_mfma_f32_16x16x32_bf16 v[34:37], v[172:175], v[188:191], v[34:37]
	v_mfma_f32_16x16x32_bf16 v[38:41], v[164:167], v[188:191], v[38:41]
	s_waitcnt lgkmcnt(1)
	v_mfma_f32_16x16x32_bf16 v[42:45], v[156:159], v[188:191], v[42:45]
	v_mfma_f32_16x16x32_bf16 v[46:49], v[134:137], v[188:191], v[46:49]
	v_mfma_f32_16x16x32_bf16 v[30:33], v[134:137], v[196:199], v[30:33]
	v_mfma_f32_16x16x32_bf16 v[26:29], v[156:159], v[196:199], v[26:29]
	v_mfma_f32_16x16x32_bf16 v[22:25], v[164:167], v[196:199], v[22:25]
	v_mfma_f32_16x16x32_bf16 v[18:21], v[172:175], v[196:199], v[18:21]
	v_mfma_f32_16x16x32_bf16 v[2:5], v[172:175], v[204:207], v[2:5]
	v_mfma_f32_16x16x32_bf16 v[6:9], v[164:167], v[204:207], v[6:9]
	s_waitcnt lgkmcnt(0)
	v_mfma_f32_16x16x32_bf16 v[10:13], v[156:159], v[204:207], v[10:13]
	v_mfma_f32_16x16x32_bf16 v[14:17], v[134:137], v[204:207], v[14:17]
	s_setprio 0
	s_setprio 1
	v_mfma_f32_16x16x32_bf16 v[62:65], v[248:251], v[184:187], v[62:65]
	v_mfma_f32_16x16x32_bf16 v[58:61], v[160:163], v[184:187], v[58:61]
	v_mfma_f32_16x16x32_bf16 v[54:57], v[168:171], v[184:187], v[54:57]
	v_mfma_f32_16x16x32_bf16 v[50:53], v[176:179], v[184:187], v[50:53]
	v_mfma_f32_16x16x32_bf16 v[34:37], v[176:179], v[192:195], v[34:37]
	v_mfma_f32_16x16x32_bf16 v[38:41], v[168:171], v[192:195], v[38:41]
	v_mfma_f32_16x16x32_bf16 v[42:45], v[160:163], v[192:195], v[42:45]
	v_mfma_f32_16x16x32_bf16 v[46:49], v[248:251], v[192:195], v[46:49]
	v_mfma_f32_16x16x32_bf16 v[30:33], v[248:251], v[200:203], v[30:33]
	v_mfma_f32_16x16x32_bf16 v[26:29], v[160:163], v[200:203], v[26:29]
	v_mfma_f32_16x16x32_bf16 v[22:25], v[168:171], v[200:203], v[22:25]
	v_mfma_f32_16x16x32_bf16 v[18:21], v[176:179], v[200:203], v[18:21]
	v_mfma_f32_16x16x32_bf16 v[2:5], v[176:179], v[252:255], v[2:5]
	v_mfma_f32_16x16x32_bf16 v[6:9], v[168:171], v[252:255], v[6:9]
	v_mfma_f32_16x16x32_bf16 v[10:13], v[160:163], v[252:255], v[10:13]
	s_setprio 2
	s_barrier
	v_mfma_f32_16x16x32_bf16 v[14:17], v[248:251], v[252:255], v[14:17]
	s_setprio 0
	s_add_i32 s69, s69, 2
	s_add_u32 s53, s53, 0x100
	s_addc_u32 s58, s58, 0
	s_add_u32 s59, s59, 0x100
	s_addc_u32 s68, s68, 0
	s_add_u32 s42, s42, 0x100
	s_addc_u32 s43, s43, 0
	s_cmp_gt_u32 s69, 61
	s_cbranch_scc0 .LBB0_698
	s_and_b64 vcc, exec, s[14:15]
	s_cbranch_vccz .LBB0_701
	s_barrier

; #define PG8_STAGE(bufoff, gbase, voff) do { _Pragma("unroll") for (int _i = 0; _i < 2; ++_i) \
;         asm volatile("s_mov_b32 m0, %2\n\ts_nop 0\n\tglobal_load_lds_dwordx4 %0, %1" :: "v"((voff)[_i]), "s"((const char*)(gbase)), "s"(ldsbase + (unsigned)(bufoff) + ldsw + (unsigned)_i * 8192u) : "memory", "m0"); } while (0)
; #define PG8_LDA(dst, b, h) do { _Pragma("unroll") for (int m = 0; m < 4; ++m) _Pragma("unroll") for (int k = 0; k < 2; ++k) dst[m][k] = *(const PG8_LAS bf16x8*)(lds + PG8_SA(b, h) + aoff + m * 2048 + k * 1024); } while (0)
; #define PG8_WAIT_V(n) asm volatile("s_waitcnt vmcnt(" #n ")" ::: "memory")
; template <class Epi, class Sched, bool ALIGN_EPI = false, bool SP2 = false>
; __device__ __forceinline__ void gemm_phase(PG8_LAS unsigned char* lds, const Gemm g, const Sched& S, const Epi& E) {
;     ...
;             const bool last = (t == nt - 2);
;             const char* a1 = cA + (size_t)(t + 1) * kstep;
;             const char* a2 = last ? nA : cA + (size_t)(t + 2) * kstep; const char* b2 = last ? nB : cB + (size_t)(t + 2) * kstep;
;             const char* a3 = a2 + kstep; const char* b3 = b2 + kstep;
;             if (last && has_next) S.a_ready(nxt);
;             if constexpr (epi_has_mid<Epi>::value) { if (t == Epi::MID_T) E.mid(acc, cur, wr, wc, fr, fq); }
;             if constexpr (SP2) {
;             PG8_LDB(B0, 0, 0); PG8_LDB(B1, 0, 1); PG8_SCHED; PG8_LDA(At, 0, 0); PG8_STAGE(PG8_SA(1, 1), a1 + hstep, voffA);
;             PG8_WAIT_V(8); PG8_WAIT_L(0); PG8_BAR; PG8_MMA(0, 0, At, B0); PG8_MMA(0, 1, At, B1); PG8_BAR; PG8_SCHED;
;             PG8_LDA(At, 0, 1); PG8_STAGE(PG8_SB(0, 0), b2, voffB); PG8_STAGE(PG8_SB(0, 1), b2 + hstep, voffB); PG8_STAGE(PG8_SA(0, 0), a2, voffA);
;             PG8_WAIT_V(8); PG8_WAIT_L(0); PG8_BAR; PG8_MMA(1, 0, At, B0); PG8_MMA(1, 1, At, B1); PG8_BAR; PG8_SCHED;
;             PG8_LDB(B0, 1, 0); PG8_LDB(B1, 1, 1); PG8_SCHED; PG8_LDA(At, 1, 0); PG8_STAGE(PG8_SA(0, 1), a2 + hstep, voffA);
;             PG8_WAIT_V(8); PG8_WAIT_L(0); PG8_BAR; PG8_MMA(0, 0, At, B0); PG8_MMA(0, 1, At, B1); PG8_BAR; PG8_SCHED;
;             PG8_LDA(At, 1, 1); PG8_STAGE(PG8_SB(1, 0), b3, voffB); PG8_STAGE(PG8_SB(1, 1), b3 + hstep, voffB); PG8_STAGE(PG8_SA(1, 0), a3, voffA);
;             PG8_WAIT_V(8); PG8_WAIT_L(0); PG8_BAR; PG8_MMA(1, 0, At, B0); PG8_MMA(1, 1, At, B1); PG8_BAR; PG8_SCHED;
.LBB0_789:
	v_add_u32_e32 v164, 0x10000, v149
	v_add_u32_e32 v180, 0x14000, v149
	s_add_u32 s8, s40, 0x100
	s_waitcnt lgkmcnt(0)
	ds_read_b128 v[152:155], v164
	ds_read_b128 v[156:159], v164 offset:1024
	ds_read_b128 v[160:163], v164 offset:2048
	ds_read_b128 v[164:167], v164 offset:3072
	ds_read_b128 v[168:171], v180
	ds_read_b128 v[172:175], v180 offset:1024
	ds_read_b128 v[176:179], v180 offset:2048
	ds_read_b128 v[180:183], v180 offset:3072
	s_addc_u32 s9, s41, 0
	s_and_b64 s[38:39], s[38:39], exec
	s_cselect_b32 s46, s59, s8
	s_cselect_b32 s47, s17, s9
	s_cselect_b32 s39, s15, s75
	s_cselect_b32 s38, s71, s74
	s_add_u32 s42, s46, 0x80
	s_addc_u32 s43, s47, 0
	s_add_u32 s44, s38, 0x80
	s_addc_u32 s45, s39, 0
	ds_read_b128 v[184:187], v150
	ds_read_b128 v[188:191], v150 offset:1024
	ds_read_b128 v[192:195], v150 offset:2048
	ds_read_b128 v[196:199], v150 offset:3072
	ds_read_b128 v[200:203], v150 offset:4096
	ds_read_b128 v[204:207], v150 offset:5120
	ds_read_b128 v[208:211], v150 offset:6144
	ds_read_b128 v[212:215], v150 offset:7168
	s_add_u32 s40, s40, 0x100080
	s_addc_u32 s41, s41, 0
	s_mov_b32 m0, s64
	s_nop 0
	global_load_lds_dwordx4 v139, s[40:41]
	s_nop 0
	s_mov_b32 m0, s65
	s_nop 0
	global_load_lds_dwordx4 v141, s[40:41]
	s_waitcnt vmcnt(8)
	s_waitcnt lgkmcnt(0)
	s_barrier
	s_setprio 1
	s_waitcnt lgkmcnt(7)
	v_mfma_f32_16x16x32_bf16 v[126:129], v[152:155], v[184:187], v[126:129]
	v_mfma_f32_16x16x32_bf16 v[122:125], v[160:163], v[184:187], v[122:125]
	s_waitcnt lgkmcnt(5)
	v_mfma_f32_16x16x32_bf16 v[118:121], v[168:171], v[184:187], v[118:121]
	v_mfma_f32_16x16x32_bf16 v[114:117], v[176:179], v[184:187], v[114:117]
	s_waitcnt lgkmcnt(3)
	v_mfma_f32_16x16x32_bf16 v[98:101], v[176:179], v[192:195], v[98:101]
	v_mfma_f32_16x16x32_bf16 v[102:105], v[168:171], v[192:195], v[102:105]
	s_waitcnt lgkmcnt(1)
	v_mfma_f32_16x16x32_bf16 v[106:109], v[160:163], v[192:195], v[106:109]
	v_mfma_f32_16x16x32_bf16 v[110:113], v[152:155], v[192:195], v[110:113]
	v_mfma_f32_16x16x32_bf16 v[94:97], v[152:155], v[200:203], v[94:97]
	v_mfma_f32_16x16x32_bf16 v[90:93], v[160:163], v[200:203], v[90:93]
	v_mfma_f32_16x16x32_bf16 v[86:89], v[168:171], v[200:203], v[86:89]
	v_mfma_f32_16x16x32_bf16 v[82:85], v[176:179], v[200:203], v[82:85]
	v_mfma_f32_16x16x32_bf16 v[66:69], v[176:179], v[208:211], v[66:69]
	v_mfma_f32_16x16x32_bf16 v[70:73], v[168:171], v[208:211], v[70:73]
	s_waitcnt lgkmcnt(0)
	v_mfma_f32_16x16x32_bf16 v[74:77], v[160:163], v[208:211], v[74:77]
	v_mfma_f32_16x16x32_bf16 v[78:81], v[152:155], v[208:211], v[78:81]
	s_setprio 0
	s_setprio 1
	v_mfma_f32_16x16x32_bf16 v[126:129], v[156:159], v[188:191], v[126:129]
	v_mfma_f32_16x16x32_bf16 v[122:125], v[164:167], v[188:191], v[122:125]
	v_mfma_f32_16x16x32_bf16 v[118:121], v[172:175], v[188:191], v[118:121]
	v_mfma_f32_16x16x32_bf16 v[114:117], v[180:183], v[188:191], v[114:117]
	v_mfma_f32_16x16x32_bf16 v[98:101], v[180:183], v[196:199], v[98:101]
	v_mfma_f32_16x16x32_bf16 v[102:105], v[172:175], v[196:199], v[102:105]
	v_mfma_f32_16x16x32_bf16 v[106:109], v[164:167], v[196:199], v[106:109]
	v_mfma_f32_16x16x32_bf16 v[110:113], v[156:159], v[196:199], v[110:113]
	v_mfma_f32_16x16x32_bf16 v[94:97], v[156:159], v[204:207], v[94:97]
	v_mfma_f32_16x16x32_bf16 v[90:93], v[164:167], v[204:207], v[90:93]
	v_mfma_f32_16x16x32_bf16 v[86:89], v[172:175], v[204:207], v[86:89]
	v_mfma_f32_16x16x32_bf16 v[82:85], v[180:183], v[204:207], v[82:85]
	v_mfma_f32_16x16x32_bf16 v[66:69], v[180:183], v[212:215], v[66:69]
	v_mfma_f32_16x16x32_bf16 v[70:73], v[172:175], v[212:215], v[70:73]
	v_mfma_f32_16x16x32_bf16 v[74:77], v[164:167], v[212:215], v[74:77]
	s_setprio 2
	s_barrier
	v_mfma_f32_16x16x32_bf16 v[78:81], v[156:159], v[212:215], v[78:81]
	s_setprio 0
	ds_read_b128 v[184:187], v150 offset:16384
	ds_read_b128 v[188:191], v150 offset:17408
	ds_read_b128 v[192:195], v150 offset:18432
	ds_read_b128 v[196:199], v150 offset:19456
	ds_read_b128 v[200:203], v150 offset:20480
	ds_read_b128 v[204:207], v150 offset:21504
	ds_read_b128 v[208:211], v150 offset:22528
	ds_read_b128 v[252:255], v150 offset:23552
	s_mov_b32 m0, s49
	s_nop 0
	global_load_lds_dwordx4 v140, s[38:39]
	s_add_u32 s40, s38, 0x100000
	s_mov_b32 m0, s50
	s_nop 0
	global_load_lds_dwordx4 v142, s[38:39]
	s_addc_u32 s41, s39, 0
	s_mov_b32 m0, s51
	s_nop 0
	global_load_lds_dwordx4 v140, s[40:41]
	s_nop 0
	s_mov_b32 m0, s52
	s_nop 0
	global_load_lds_dwordx4 v142, s[40:41]
	s_nop 0
	s_mov_b32 m0, s37
	s_nop 0
	global_load_lds_dwordx4 v139, s[46:47]
	s_nop 0
	s_mov_b32 m0, s53
	s_nop 0
	global_load_lds_dwordx4 v141, s[46:47]
	s_waitcnt vmcnt(8)
	s_waitcnt lgkmcnt(0)
	s_barrier
; #define PG8_STAGE(bufoff, gbase, voff) do { _Pragma("unroll") for (int _i = 0; _i < 2; ++_i) \
;         asm volatile("s_mov_b32 m0, %2\n\ts_nop 0\n\tglobal_load_lds_dwordx4 %0, %1" :: "v"((voff)[_i]), "s"((const char*)(gbase)), "s"(ldsbase + (unsigned)(bufoff) + ldsw + (unsigned)_i * 8192u) : "memory", "m0"); } while (0)
; #define PG8_LDA(dst, b, h) do { _Pragma("unroll") for (int m = 0; m < 4; ++m) _Pragma("unroll") for (int k = 0; k < 2; ++k) dst[m][k] = *(const PG8_LAS bf16x8*)(lds + PG8_SA(b, h) + aoff + m * 2048 + k * 1024); } while (0)
; #define PG8_LDB(dst, b, h) do { _Pragma("unroll") for (int n = 0; n < 2; ++n) _Pragma("unroll") for (int k = 0; k < 2; ++k) dst[n][k] = *(const PG8_LAS bf16x8*)(lds + PG8_SB(b, h) + boff + n * 2048 + k * 1024); } while (0)
; #define PG8_MMA(ai, bj, At, Bt) do { __builtin_amdgcn_s_setprio(1); _Pragma("unroll") for (int m = 0; m < 4; ++m) _Pragma("unroll") for (int n = 0; n < 2; ++n) _Pragma("unroll") for (int k = 0; k < 2; ++k) \
;         acc[ai][bj][m][n] = __builtin_amdgcn_mfma_f32_16x16x32_bf16(Bt[n][k], At[m][k], acc[ai][bj][m][n], 0, 0, 0); __builtin_amdgcn_s_setprio(0); } while (0)
; template <class Epi, class Sched, bool ALIGN_EPI = false, bool SP2 = false>
; __device__ __forceinline__ void gemm_phase(PG8_LAS unsigned char* lds, const Gemm g, const Sched& S, const Epi& E) {
;     ...
;             PG8_LDB(B0, 0, 0); PG8_LDB(B1, 0, 1); PG8_SCHED; PG8_LDA(At, 0, 0); PG8_STAGE(PG8_SA(1, 1), a1 + hstep, voffA);
;             PG8_WAIT_V(8); PG8_WAIT_L(0); PG8_BAR; PG8_MMA(0, 0, At, B0); PG8_MMA(0, 1, At, B1); PG8_BAR; PG8_SCHED;
;             PG8_LDA(At, 0, 1); PG8_STAGE(PG8_SB(0, 0), b2, voffB); PG8_STAGE(PG8_SB(0, 1), b2 + hstep, voffB); PG8_STAGE(PG8_SA(0, 0), a2, voffA);
;             PG8_WAIT_V(8); PG8_WAIT_L(0); PG8_BAR; PG8_MMA(1, 0, At, B0); PG8_MMA(1, 1, At, B1); PG8_BAR; PG8_SCHED;
;             PG8_LDB(B0, 1, 0); PG8_LDB(B1, 1, 1); PG8_SCHED; PG8_LDA(At, 1, 0); PG8_STAGE(PG8_SA(0, 1), a2 + hstep, voffA);
;             PG8_WAIT_V(8); PG8_WAIT_L(0); PG8_BAR; PG8_MMA(0, 0, At, B0); PG8_MMA(0, 1, At, B1); PG8_BAR; PG8_SCHED;
;             PG8_LDA(At, 1, 1); PG8_STAGE(PG8_SB(1, 0), b3, voffB); PG8_STAGE(PG8_SB(1, 1), b3 + hstep, voffB); PG8_STAGE(PG8_SA(1, 0), a3, voffA);
;             PG8_WAIT_V(8); PG8_WAIT_L(0); PG8_BAR; PG8_MMA(1, 0, At, B0); PG8_MMA(1, 1, At, B1); PG8_BAR; PG8_SCHED;
	s_setprio 1
	s_waitcnt lgkmcnt(7)
	v_mfma_f32_16x16x32_bf16 v[62:65], v[152:155], v[184:187], v[62:65]
	v_mfma_f32_16x16x32_bf16 v[58:61], v[160:163], v[184:187], v[58:61]
	s_waitcnt lgkmcnt(5)
	v_mfma_f32_16x16x32_bf16 v[54:57], v[168:171], v[184:187], v[54:57]
	v_mfma_f32_16x16x32_bf16 v[50:53], v[176:179], v[184:187], v[50:53]
	s_waitcnt lgkmcnt(3)
	v_mfma_f32_16x16x32_bf16 v[34:37], v[176:179], v[192:195], v[34:37]
	v_mfma_f32_16x16x32_bf16 v[38:41], v[168:171], v[192:195], v[38:41]
	s_waitcnt lgkmcnt(1)
	v_mfma_f32_16x16x32_bf16 v[42:45], v[160:163], v[192:195], v[42:45]
	v_mfma_f32_16x16x32_bf16 v[46:49], v[152:155], v[192:195], v[46:49]
	v_mfma_f32_16x16x32_bf16 v[30:33], v[152:155], v[200:203], v[30:33]
	v_mfma_f32_16x16x32_bf16 v[26:29], v[160:163], v[200:203], v[26:29]
	v_mfma_f32_16x16x32_bf16 v[22:25], v[168:171], v[200:203], v[22:25]
	v_mfma_f32_16x16x32_bf16 v[18:21], v[176:179], v[200:203], v[18:21]
	v_mfma_f32_16x16x32_bf16 v[2:5], v[176:179], v[208:211], v[2:5]
	v_mfma_f32_16x16x32_bf16 v[6:9], v[168:171], v[208:211], v[6:9]
	s_waitcnt lgkmcnt(0)
	v_mfma_f32_16x16x32_bf16 v[10:13], v[160:163], v[208:211], v[10:13]
	v_mfma_f32_16x16x32_bf16 v[14:17], v[152:155], v[208:211], v[14:17]
	s_setprio 0
	s_setprio 1
	v_mfma_f32_16x16x32_bf16 v[62:65], v[156:159], v[188:191], v[62:65]
	v_mfma_f32_16x16x32_bf16 v[58:61], v[164:167], v[188:191], v[58:61]
	v_mfma_f32_16x16x32_bf16 v[54:57], v[172:175], v[188:191], v[54:57]
	v_mfma_f32_16x16x32_bf16 v[50:53], v[180:183], v[188:191], v[50:53]
	v_mfma_f32_16x16x32_bf16 v[34:37], v[180:183], v[196:199], v[34:37]
	v_mfma_f32_16x16x32_bf16 v[38:41], v[172:175], v[196:199], v[38:41]
	v_mfma_f32_16x16x32_bf16 v[42:45], v[164:167], v[196:199], v[42:45]
	v_mfma_f32_16x16x32_bf16 v[46:49], v[156:159], v[196:199], v[46:49]
	v_mfma_f32_16x16x32_bf16 v[30:33], v[156:159], v[204:207], v[30:33]
	v_mfma_f32_16x16x32_bf16 v[26:29], v[164:167], v[204:207], v[26:29]
	v_mfma_f32_16x16x32_bf16 v[22:25], v[172:175], v[204:207], v[22:25]
	v_mfma_f32_16x16x32_bf16 v[18:21], v[180:183], v[204:207], v[18:21]
	v_mfma_f32_16x16x32_bf16 v[2:5], v[180:183], v[252:255], v[2:5]
	v_mfma_f32_16x16x32_bf16 v[6:9], v[172:175], v[252:255], v[6:9]
	v_mfma_f32_16x16x32_bf16 v[10:13], v[164:167], v[252:255], v[10:13]
	s_setprio 2
	s_barrier
	v_mfma_f32_16x16x32_bf16 v[14:17], v[156:159], v[252:255], v[14:17]
	s_setprio 0
	v_add_u32_e32 v164, 0x18000, v149
	v_add_u32_e32 v180, 0x1c000, v149
	ds_read_b128 v[152:155], v164
	ds_read_b128 v[248:251], v164 offset:1024
	ds_read_b128 v[160:163], v164 offset:2048
	ds_read_b128 v[164:167], v164 offset:3072
	ds_read_b128 v[168:171], v180
	ds_read_b128 v[172:175], v180 offset:1024
	ds_read_b128 v[176:179], v180 offset:2048
	ds_read_b128 v[180:183], v180 offset:3072
	ds_read_b128 v[184:187], v150 offset:32768
	ds_read_b128 v[188:191], v150 offset:33792
	ds_read_b128 v[192:195], v150 offset:34816
	ds_read_b128 v[196:199], v150 offset:35840
	ds_read_b128 v[200:203], v150 offset:36864
	ds_read_b128 v[204:207], v150 offset:37888
	ds_read_b128 v[208:211], v150 offset:38912
	ds_read_b128 v[212:215], v150 offset:39936
	s_add_u32 s40, s46, 0x100000
	s_addc_u32 s41, s47, 0
	s_mov_b32 m0, s54
	s_nop 0
	global_load_lds_dwordx4 v139, s[40:41]
	s_nop 0
	s_mov_b32 m0, s55
	s_nop 0
	global_load_lds_dwordx4 v141, s[40:41]
	s_waitcnt vmcnt(8)
	s_waitcnt lgkmcnt(0)
	s_barrier
	s_setprio 1
	s_waitcnt lgkmcnt(7)
	v_mfma_f32_16x16x32_bf16 v[126:129], v[152:155], v[184:187], v[126:129]
	v_mfma_f32_16x16x32_bf16 v[122:125], v[160:163], v[184:187], v[122:125]
	s_waitcnt lgkmcnt(5)
	v_mfma_f32_16x16x32_bf16 v[118:121], v[168:171], v[184:187], v[118:121]
	v_mfma_f32_16x16x32_bf16 v[114:117], v[176:179], v[184:187], v[114:117]
	s_waitcnt lgkmcnt(3)
	v_mfma_f32_16x16x32_bf16 v[98:101], v[176:179], v[192:195], v[98:101]
	v_mfma_f32_16x16x32_bf16 v[102:105], v[168:171], v[192:195], v[102:105]
	s_waitcnt lgkmcnt(1)
	v_mfma_f32_16x16x32_bf16 v[106:109], v[160:163], v[192:195], v[106:109]
	v_mfma_f32_16x16x32_bf16 v[110:113], v[152:155], v[192:195], v[110:113]
	v_mfma_f32_16x16x32_bf16 v[94:97], v[152:155], v[200:203], v[94:97]
	v_mfma_f32_16x16x32_bf16 v[90:93], v[160:163], v[200:203], v[90:93]
	v_mfma_f32_16x16x32_bf16 v[86:89], v[168:171], v[200:203], v[86:89]
	v_mfma_f32_16x16x32_bf16 v[82:85], v[176:179], v[200:203], v[82:85]
	v_mfma_f32_16x16x32_bf16 v[66:69], v[176:179], v[208:211], v[66:69]
	v_mfma_f32_16x16x32_bf16 v[70:73], v[168:171], v[208:211], v[70:73]
	s_waitcnt lgkmcnt(0)
	v_mfma_f32_16x16x32_bf16 v[74:77], v[160:163], v[208:211], v[74:77]
	v_mfma_f32_16x16x32_bf16 v[78:81], v[152:155], v[208:211], v[78:81]
	s_setprio 0
	s_setprio 1
	v_mfma_f32_16x16x32_bf16 v[126:129], v[248:251], v[188:191], v[126:129]
	v_mfma_f32_16x16x32_bf16 v[122:125], v[164:167], v[188:191], v[122:125]
	v_mfma_f32_16x16x32_bf16 v[118:121], v[172:175], v[188:191], v[118:121]
	v_mfma_f32_16x16x32_bf16 v[114:117], v[180:183], v[188:191], v[114:117]
	v_mfma_f32_16x16x32_bf16 v[98:101], v[180:183], v[196:199], v[98:101]
	v_mfma_f32_16x16x32_bf16 v[102:105], v[172:175], v[196:199], v[102:105]
	v_mfma_f32_16x16x32_bf16 v[106:109], v[164:167], v[196:199], v[106:109]
	v_mfma_f32_16x16x32_bf16 v[110:113], v[248:251], v[196:199], v[110:113]
	v_mfma_f32_16x16x32_bf16 v[94:97], v[248:251], v[204:207], v[94:97]
	v_mfma_f32_16x16x32_bf16 v[90:93], v[164:167], v[204:207], v[90:93]
	v_mfma_f32_16x16x32_bf16 v[86:89], v[172:175], v[204:207], v[86:89]
	v_mfma_f32_16x16x32_bf16 v[82:85], v[180:183], v[204:207], v[82:85]
	v_mfma_f32_16x16x32_bf16 v[66:69], v[180:183], v[212:215], v[66:69]
	v_mfma_f32_16x16x32_bf16 v[70:73], v[172:175], v[212:215], v[70:73]
	v_mfma_f32_16x16x32_bf16 v[74:77], v[164:167], v[212:215], v[74:77]
	s_setprio 2
	s_barrier
; #define PG8_STAGE(bufoff, gbase, voff) do { _Pragma("unroll") for (int _i = 0; _i < 2; ++_i) \
;         asm volatile("s_mov_b32 m0, %2\n\ts_nop 0\n\tglobal_load_lds_dwordx4 %0, %1" :: "v"((voff)[_i]), "s"((const char*)(gbase)), "s"(ldsbase + (unsigned)(bufoff) + ldsw + (unsigned)_i * 8192u) : "memory", "m0"); } while (0)
; #define PG8_LDA(dst, b, h) do { _Pragma("unroll") for (int m = 0; m < 4; ++m) _Pragma("unroll") for (int k = 0; k < 2; ++k) dst[m][k] = *(const PG8_LAS bf16x8*)(lds + PG8_SA(b, h) + aoff + m * 2048 + k * 1024); } while (0)
; #define PG8_BAR __builtin_amdgcn_s_barrier()
; template <class Epi, class Sched, bool ALIGN_EPI = false, bool SP2 = false>
; __device__ __forceinline__ void gemm_phase(PG8_LAS unsigned char* lds, const Gemm g, const Sched& S, const Epi& E) {
;     ...
;         for (int t = 0; t < nt; t += 2) {
;             const bool last = (t == nt - 2);
;             const char* a1 = cA + (size_t)(t + 1) * kstep;
;             const char* a2 = last ? nA : cA + (size_t)(t + 2) * kstep; const char* b2 = last ? nB : cB + (size_t)(t + 2) * kstep;
;             const char* a3 = a2 + kstep; const char* b3 = b2 + kstep;
;             if (last && has_next) S.a_ready(nxt);
;             if constexpr (epi_has_mid<Epi>::value) { if (t == Epi::MID_T) E.mid(acc, cur, wr, wc, fr, fq); }
;             if constexpr (SP2) {
;             PG8_LDB(B0, 0, 0); PG8_LDB(B1, 0, 1); PG8_SCHED; PG8_LDA(At, 0, 0); PG8_STAGE(PG8_SA(1, 1), a1 + hstep, voffA);
;             PG8_WAIT_V(8); PG8_WAIT_L(0); PG8_BAR; PG8_MMA(0, 0, At, B0); PG8_MMA(0, 1, At, B1); PG8_BAR; PG8_SCHED;
;             PG8_LDA(At, 0, 1); PG8_STAGE(PG8_SB(0, 0), b2, voffB); PG8_STAGE(PG8_SB(0, 1), b2 + hstep, voffB); PG8_STAGE(PG8_SA(0, 0), a2, voffA);
;             PG8_WAIT_V(8); PG8_WAIT_L(0); PG8_BAR; PG8_MMA(1, 0, At, B0); PG8_MMA(1, 1, At, B1); PG8_BAR; PG8_SCHED;
;             PG8_LDB(B0, 1, 0); PG8_LDB(B1, 1, 1); PG8_SCHED; PG8_LDA(At, 1, 0); PG8_STAGE(PG8_SA(0, 1), a2 + hstep, voffA);
;             PG8_WAIT_V(8); PG8_WAIT_L(0); PG8_BAR; PG8_MMA(0, 0, At, B0); PG8_MMA(0, 1, At, B1); PG8_BAR; PG8_SCHED;
;             PG8_LDA(At, 1, 1); PG8_STAGE(PG8_SB(1, 0), b3, voffB); PG8_STAGE(PG8_SB(1, 1), b3 + hstep, voffB); PG8_STAGE(PG8_SA(1, 0), a3, voffA);
;             PG8_WAIT_V(8); PG8_WAIT_L(0); PG8_BAR; PG8_MMA(1, 0, At, B0); PG8_MMA(1, 1, At, B1); PG8_BAR; PG8_SCHED;
	v_mfma_f32_16x16x32_bf16 v[78:81], v[248:251], v[212:215], v[78:81]
	s_setprio 0
	ds_read_b128 v[184:187], v150 offset:49152
	ds_read_b128 v[188:191], v150 offset:50176
	ds_read_b128 v[192:195], v150 offset:51200
	ds_read_b128 v[196:199], v150 offset:52224
	ds_read_b128 v[200:203], v150 offset:53248
	ds_read_b128 v[204:207], v150 offset:54272
	ds_read_b128 v[208:211], v150 offset:55296
	ds_read_b128 v[252:255], v150 offset:56320
	s_mov_b32 m0, s56
	s_nop 0
	global_load_lds_dwordx4 v140, s[44:45]
	s_add_u32 s38, s38, 0x100080
	s_mov_b32 m0, s57
	s_nop 0
	global_load_lds_dwordx4 v142, s[44:45]
	s_addc_u32 s39, s39, 0
	s_mov_b32 m0, s62
	s_nop 0
	global_load_lds_dwordx4 v140, s[38:39]
	s_nop 0
	s_mov_b32 m0, s63
	s_nop 0
	global_load_lds_dwordx4 v142, s[38:39]
	s_nop 0
	s_mov_b32 m0, s60
	s_nop 0
	global_load_lds_dwordx4 v139, s[42:43]
	s_nop 0
	s_mov_b32 m0, s61
	s_nop 0
	global_load_lds_dwordx4 v141, s[42:43]
	s_waitcnt vmcnt(8)
	s_waitcnt lgkmcnt(0)
	s_barrier
	s_setprio 1
	s_waitcnt lgkmcnt(7)
	v_mfma_f32_16x16x32_bf16 v[62:65], v[152:155], v[184:187], v[62:65]
	v_mfma_f32_16x16x32_bf16 v[58:61], v[160:163], v[184:187], v[58:61]
	s_waitcnt lgkmcnt(5)
	v_mfma_f32_16x16x32_bf16 v[54:57], v[168:171], v[184:187], v[54:57]
	v_mfma_f32_16x16x32_bf16 v[50:53], v[176:179], v[184:187], v[50:53]
	s_waitcnt lgkmcnt(3)
	v_mfma_f32_16x16x32_bf16 v[34:37], v[176:179], v[192:195], v[34:37]
	v_mfma_f32_16x16x32_bf16 v[38:41], v[168:171], v[192:195], v[38:41]
	s_waitcnt lgkmcnt(1)
	v_mfma_f32_16x16x32_bf16 v[42:45], v[160:163], v[192:195], v[42:45]
	v_mfma_f32_16x16x32_bf16 v[46:49], v[152:155], v[192:195], v[46:49]
	v_mfma_f32_16x16x32_bf16 v[30:33], v[152:155], v[200:203], v[30:33]
	v_mfma_f32_16x16x32_bf16 v[26:29], v[160:163], v[200:203], v[26:29]
	v_mfma_f32_16x16x32_bf16 v[22:25], v[168:171], v[200:203], v[22:25]
	v_mfma_f32_16x16x32_bf16 v[18:21], v[176:179], v[200:203], v[18:21]
	v_mfma_f32_16x16x32_bf16 v[2:5], v[176:179], v[208:211], v[2:5]
	v_mfma_f32_16x16x32_bf16 v[6:9], v[168:171], v[208:211], v[6:9]
	s_waitcnt lgkmcnt(0)
	v_mfma_f32_16x16x32_bf16 v[10:13], v[160:163], v[208:211], v[10:13]
	v_mfma_f32_16x16x32_bf16 v[14:17], v[152:155], v[208:211], v[14:17]
	s_setprio 0
	s_setprio 1
	v_mfma_f32_16x16x32_bf16 v[62:65], v[248:251], v[188:191], v[62:65]
	v_mfma_f32_16x16x32_bf16 v[58:61], v[164:167], v[188:191], v[58:61]
	v_mfma_f32_16x16x32_bf16 v[54:57], v[172:175], v[188:191], v[54:57]
	v_mfma_f32_16x16x32_bf16 v[50:53], v[180:183], v[188:191], v[50:53]
	v_mfma_f32_16x16x32_bf16 v[34:37], v[180:183], v[196:199], v[34:37]
	v_mfma_f32_16x16x32_bf16 v[38:41], v[172:175], v[196:199], v[38:41]
	v_mfma_f32_16x16x32_bf16 v[42:45], v[164:167], v[196:199], v[42:45]
	v_mfma_f32_16x16x32_bf16 v[46:49], v[248:251], v[196:199], v[46:49]
	v_mfma_f32_16x16x32_bf16 v[30:33], v[248:251], v[204:207], v[30:33]
	v_mfma_f32_16x16x32_bf16 v[26:29], v[164:167], v[204:207], v[26:29]
	v_mfma_f32_16x16x32_bf16 v[22:25], v[172:175], v[204:207], v[22:25]
	v_mfma_f32_16x16x32_bf16 v[18:21], v[180:183], v[204:207], v[18:21]
	v_mfma_f32_16x16x32_bf16 v[2:5], v[180:183], v[252:255], v[2:5]
	v_mfma_f32_16x16x32_bf16 v[6:9], v[172:175], v[252:255], v[6:9]
	v_mfma_f32_16x16x32_bf16 v[10:13], v[164:167], v[252:255], v[10:13]
	s_setprio 2
	s_barrier
	v_mfma_f32_16x16x32_bf16 v[14:17], v[248:251], v[252:255], v[14:17]
	s_setprio 0
	s_add_i32 s76, s76, 2
	s_add_u32 s74, s74, 0x100
	s_addc_u32 s75, s75, 0
	s_cmp_gt_u32 s76, 61
	s_cbranch_scc1 .LBB0_780
	s_mov_b64 s[40:41], s[8:9]
	s_branch .LBB0_784

; #define PG8_STAGE(bufoff, gbase, voff) do { _Pragma("unroll") for (int _i = 0; _i < 2; ++_i) \
;         asm volatile("s_mov_b32 m0, %2\n\ts_nop 0\n\tglobal_load_lds_dwordx4 %0, %1" :: "v"((voff)[_i]), "s"((const char*)(gbase)), "s"(ldsbase + (unsigned)(bufoff) + ldsw + (unsigned)_i * 8192u) : "memory", "m0"); } while (0)
; #define PG8_LDA(dst, b, h) do { _Pragma("unroll") for (int m = 0; m < 4; ++m) _Pragma("unroll") for (int k = 0; k < 2; ++k) dst[m][k] = *(const PG8_LAS bf16x8*)(lds + PG8_SA(b, h) + aoff + m * 2048 + k * 1024); } while (0)
; #define PG8_WAIT_V(n) asm volatile("s_waitcnt vmcnt(" #n ")" ::: "memory")
; template <class Epi, class Sched, bool ALIGN_EPI = false, bool SP2 = false>
; __device__ __forceinline__ void gemm_phase(PG8_LAS unsigned char* lds, const Gemm g, const Sched& S, const Epi& E) {
;     ...
;             const bool last = (t == nt - 2);
;             const char* a1 = cA + (size_t)(t + 1) * kstep;
;             const char* a2 = last ? nA : cA + (size_t)(t + 2) * kstep; const char* b2 = last ? nB : cB + (size_t)(t + 2) * kstep;
;             const char* a3 = a2 + kstep; const char* b3 = b2 + kstep;
;             if (last && has_next) S.a_ready(nxt);
;             if constexpr (epi_has_mid<Epi>::value) { if (t == Epi::MID_T) E.mid(acc, cur, wr, wc, fr, fq); }
;             if constexpr (SP2) {
;             PG8_LDB(B0, 0, 0); PG8_LDB(B1, 0, 1); PG8_SCHED; PG8_LDA(At, 0, 0); PG8_STAGE(PG8_SA(1, 1), a1 + hstep, voffA);
;             PG8_WAIT_V(8); PG8_WAIT_L(0); PG8_BAR; PG8_MMA(0, 0, At, B0); PG8_MMA(0, 1, At, B1); PG8_BAR; PG8_SCHED;
;             PG8_LDA(At, 0, 1); PG8_STAGE(PG8_SB(0, 0), b2, voffB); PG8_STAGE(PG8_SB(0, 1), b2 + hstep, voffB); PG8_STAGE(PG8_SA(0, 0), a2, voffA);
;             PG8_WAIT_V(8); PG8_WAIT_L(0); PG8_BAR; PG8_MMA(1, 0, At, B0); PG8_MMA(1, 1, At, B1); PG8_BAR; PG8_SCHED;
;             PG8_LDB(B0, 1, 0); PG8_LDB(B1, 1, 1); PG8_SCHED; PG8_LDA(At, 1, 0); PG8_STAGE(PG8_SA(0, 1), a2 + hstep, voffA);
;             PG8_WAIT_V(8); PG8_WAIT_L(0); PG8_BAR; PG8_MMA(0, 0, At, B0); PG8_MMA(0, 1, At, B1); PG8_BAR; PG8_SCHED;
;             PG8_LDA(At, 1, 1); PG8_STAGE(PG8_SB(1, 0), b3, voffB); PG8_STAGE(PG8_SB(1, 1), b3 + hstep, voffB); PG8_STAGE(PG8_SA(1, 0), a3, voffA);
;             PG8_WAIT_V(8); PG8_WAIT_L(0); PG8_BAR; PG8_MMA(1, 0, At, B0); PG8_MMA(1, 1, At, B1); PG8_BAR; PG8_SCHED;
.LBB0_873:
	ds_read_b128 v[134:137], v145
	ds_read_b128 v[150:153], v145 offset:1024
	ds_read_b128 v[154:157], v145 offset:2048
	ds_read_b128 v[158:161], v145 offset:3072
	ds_read_b128 v[162:165], v146
	ds_read_b128 v[166:169], v146 offset:1024
	ds_read_b128 v[170:173], v146 offset:2048
	ds_read_b128 v[174:177], v146 offset:3072
	s_add_u32 s38, s36, 0x100
	s_addc_u32 s39, s37, 0
	s_cmpk_eq_i32 s69, 0xa8
	s_cselect_b32 s44, s4, s38
	s_cselect_b32 s45, s5, s39
	s_cselect_b32 s42, s22, s67
	s_cselect_b32 s43, s23, s68
	s_add_u32 s40, s44, 0x80
	s_addc_u32 s41, s45, 0
	ds_read_b128 v[178:181], v147
	ds_read_b128 v[182:185], v147 offset:1024
	ds_read_b128 v[186:189], v147 offset:2048
	ds_read_b128 v[190:193], v147 offset:3072
	ds_read_b128 v[194:197], v147 offset:4096
	ds_read_b128 v[198:201], v147 offset:5120
	ds_read_b128 v[202:205], v147 offset:6144
	ds_read_b128 v[206:209], v147 offset:7168
	s_add_u32 s36, s36, 0x2b0080
	s_addc_u32 s37, s37, 0
	s_mov_b32 m0, s60
	s_nop 0
	global_load_lds_dwordx4 v1, s[36:37]
	s_nop 0
	s_mov_b32 m0, s61
	s_nop 0
	global_load_lds_dwordx4 v141, s[36:37]
	s_waitcnt vmcnt(8)
	s_waitcnt lgkmcnt(0)
	s_barrier
	s_setprio 1
	s_waitcnt lgkmcnt(7)
	v_mfma_f32_16x16x32_bf16 v[126:129], v[134:137], v[178:181], v[126:129]
	v_mfma_f32_16x16x32_bf16 v[122:125], v[154:157], v[178:181], v[122:125]
	s_waitcnt lgkmcnt(5)
	v_mfma_f32_16x16x32_bf16 v[118:121], v[162:165], v[178:181], v[118:121]
	v_mfma_f32_16x16x32_bf16 v[114:117], v[170:173], v[178:181], v[114:117]
	s_waitcnt lgkmcnt(3)
	v_mfma_f32_16x16x32_bf16 v[98:101], v[170:173], v[186:189], v[98:101]
	v_mfma_f32_16x16x32_bf16 v[102:105], v[162:165], v[186:189], v[102:105]
	s_waitcnt lgkmcnt(1)
	v_mfma_f32_16x16x32_bf16 v[106:109], v[154:157], v[186:189], v[106:109]
	v_mfma_f32_16x16x32_bf16 v[110:113], v[134:137], v[186:189], v[110:113]
	v_mfma_f32_16x16x32_bf16 v[94:97], v[134:137], v[194:197], v[94:97]
	v_mfma_f32_16x16x32_bf16 v[90:93], v[154:157], v[194:197], v[90:93]
	v_mfma_f32_16x16x32_bf16 v[86:89], v[162:165], v[194:197], v[86:89]
	v_mfma_f32_16x16x32_bf16 v[82:85], v[170:173], v[194:197], v[82:85]
	v_mfma_f32_16x16x32_bf16 v[66:69], v[170:173], v[202:205], v[66:69]
	v_mfma_f32_16x16x32_bf16 v[70:73], v[162:165], v[202:205], v[70:73]
	s_waitcnt lgkmcnt(0)
	v_mfma_f32_16x16x32_bf16 v[74:77], v[154:157], v[202:205], v[74:77]
	v_mfma_f32_16x16x32_bf16 v[78:81], v[134:137], v[202:205], v[78:81]
	s_setprio 0
	s_setprio 1
	v_mfma_f32_16x16x32_bf16 v[126:129], v[150:153], v[182:185], v[126:129]
	v_mfma_f32_16x16x32_bf16 v[122:125], v[158:161], v[182:185], v[122:125]
	v_mfma_f32_16x16x32_bf16 v[118:121], v[166:169], v[182:185], v[118:121]
	v_mfma_f32_16x16x32_bf16 v[114:117], v[174:177], v[182:185], v[114:117]
	v_mfma_f32_16x16x32_bf16 v[98:101], v[174:177], v[190:193], v[98:101]
	v_mfma_f32_16x16x32_bf16 v[102:105], v[166:169], v[190:193], v[102:105]
	v_mfma_f32_16x16x32_bf16 v[106:109], v[158:161], v[190:193], v[106:109]
	v_mfma_f32_16x16x32_bf16 v[110:113], v[150:153], v[190:193], v[110:113]
	v_mfma_f32_16x16x32_bf16 v[94:97], v[150:153], v[198:201], v[94:97]
	v_mfma_f32_16x16x32_bf16 v[90:93], v[158:161], v[198:201], v[90:93]
	v_mfma_f32_16x16x32_bf16 v[86:89], v[166:169], v[198:201], v[86:89]
	v_mfma_f32_16x16x32_bf16 v[82:85], v[174:177], v[198:201], v[82:85]
	v_mfma_f32_16x16x32_bf16 v[66:69], v[174:177], v[206:209], v[66:69]
	v_mfma_f32_16x16x32_bf16 v[70:73], v[166:169], v[206:209], v[70:73]
	v_mfma_f32_16x16x32_bf16 v[74:77], v[158:161], v[206:209], v[74:77]
	s_setprio 2
	s_barrier
	v_mfma_f32_16x16x32_bf16 v[78:81], v[150:153], v[206:209], v[78:81]
	s_setprio 0
	ds_read_b128 v[178:181], v147 offset:16384
	ds_read_b128 v[182:185], v147 offset:17408
	ds_read_b128 v[186:189], v147 offset:18432
	ds_read_b128 v[190:193], v147 offset:19456
	ds_read_b128 v[194:197], v147 offset:20480
	ds_read_b128 v[198:201], v147 offset:21504
	ds_read_b128 v[202:205], v147 offset:22528
	ds_read_b128 v[252:255], v147 offset:23552
	s_mov_b32 m0, s47
	s_nop 0
	global_load_lds_dwordx4 v140, s[42:43]
	s_add_u32 s36, s42, 0x2b0000
	s_mov_b32 m0, s48
	s_nop 0
	global_load_lds_dwordx4 v142, s[42:43]
	s_addc_u32 s37, s43, 0
	s_mov_b32 m0, s49
	s_nop 0
	global_load_lds_dwordx4 v140, s[36:37]
	s_nop 0
	s_mov_b32 m0, s50
	s_nop 0
	global_load_lds_dwordx4 v142, s[36:37]
	s_nop 0
	s_mov_b32 m0, s46
	s_nop 0
	global_load_lds_dwordx4 v1, s[44:45]
	s_nop 0
	s_mov_b32 m0, s51
	s_nop 0
	global_load_lds_dwordx4 v141, s[44:45]
	s_waitcnt vmcnt(8)
	s_waitcnt lgkmcnt(0)
	s_barrier
; #define PG8_STAGE(bufoff, gbase, voff) do { _Pragma("unroll") for (int _i = 0; _i < 2; ++_i) \
;         asm volatile("s_mov_b32 m0, %2\n\ts_nop 0\n\tglobal_load_lds_dwordx4 %0, %1" :: "v"((voff)[_i]), "s"((const char*)(gbase)), "s"(ldsbase + (unsigned)(bufoff) + ldsw + (unsigned)_i * 8192u) : "memory", "m0"); } while (0)
; #define PG8_LDA(dst, b, h) do { _Pragma("unroll") for (int m = 0; m < 4; ++m) _Pragma("unroll") for (int k = 0; k < 2; ++k) dst[m][k] = *(const PG8_LAS bf16x8*)(lds + PG8_SA(b, h) + aoff + m * 2048 + k * 1024); } while (0)
; #define PG8_LDB(dst, b, h) do { _Pragma("unroll") for (int n = 0; n < 2; ++n) _Pragma("unroll") for (int k = 0; k < 2; ++k) dst[n][k] = *(const PG8_LAS bf16x8*)(lds + PG8_SB(b, h) + boff + n * 2048 + k * 1024); } while (0)
; #define PG8_MMA(ai, bj, At, Bt) do { __builtin_amdgcn_s_setprio(1); _Pragma("unroll") for (int m = 0; m < 4; ++m) _Pragma("unroll") for (int n = 0; n < 2; ++n) _Pragma("unroll") for (int k = 0; k < 2; ++k) \
;         acc[ai][bj][m][n] = __builtin_amdgcn_mfma_f32_16x16x32_bf16(Bt[n][k], At[m][k], acc[ai][bj][m][n], 0, 0, 0); __builtin_amdgcn_s_setprio(0); } while (0)
; template <class Epi, class Sched, bool ALIGN_EPI = false, bool SP2 = false>
; __device__ __forceinline__ void gemm_phase(PG8_LAS unsigned char* lds, const Gemm g, const Sched& S, const Epi& E) {
;     ...
;             PG8_LDB(B0, 0, 0); PG8_LDB(B1, 0, 1); PG8_SCHED; PG8_LDA(At, 0, 0); PG8_STAGE(PG8_SA(1, 1), a1 + hstep, voffA);
;             PG8_WAIT_V(8); PG8_WAIT_L(0); PG8_BAR; PG8_MMA(0, 0, At, B0); PG8_MMA(0, 1, At, B1); PG8_BAR; PG8_SCHED;
;             PG8_LDA(At, 0, 1); PG8_STAGE(PG8_SB(0, 0), b2, voffB); PG8_STAGE(PG8_SB(0, 1), b2 + hstep, voffB); PG8_STAGE(PG8_SA(0, 0), a2, voffA);
;             PG8_WAIT_V(8); PG8_WAIT_L(0); PG8_BAR; PG8_MMA(1, 0, At, B0); PG8_MMA(1, 1, At, B1); PG8_BAR; PG8_SCHED;
;             PG8_LDB(B0, 1, 0); PG8_LDB(B1, 1, 1); PG8_SCHED; PG8_LDA(At, 1, 0); PG8_STAGE(PG8_SA(0, 1), a2 + hstep, voffA);
;             PG8_WAIT_V(8); PG8_WAIT_L(0); PG8_BAR; PG8_MMA(0, 0, At, B0); PG8_MMA(0, 1, At, B1); PG8_BAR; PG8_SCHED;
;             PG8_LDA(At, 1, 1); PG8_STAGE(PG8_SB(1, 0), b3, voffB); PG8_STAGE(PG8_SB(1, 1), b3 + hstep, voffB); PG8_STAGE(PG8_SA(1, 0), a3, voffA);
;             PG8_WAIT_V(8); PG8_WAIT_L(0); PG8_BAR; PG8_MMA(1, 0, At, B0); PG8_MMA(1, 1, At, B1); PG8_BAR; PG8_SCHED;
	s_setprio 1
	s_waitcnt lgkmcnt(7)
	v_mfma_f32_16x16x32_bf16 v[62:65], v[134:137], v[178:181], v[62:65]
	v_mfma_f32_16x16x32_bf16 v[58:61], v[154:157], v[178:181], v[58:61]
	s_waitcnt lgkmcnt(5)
	v_mfma_f32_16x16x32_bf16 v[54:57], v[162:165], v[178:181], v[54:57]
	v_mfma_f32_16x16x32_bf16 v[50:53], v[170:173], v[178:181], v[50:53]
	s_waitcnt lgkmcnt(3)
	v_mfma_f32_16x16x32_bf16 v[34:37], v[170:173], v[186:189], v[34:37]
	v_mfma_f32_16x16x32_bf16 v[38:41], v[162:165], v[186:189], v[38:41]
	s_waitcnt lgkmcnt(1)
	v_mfma_f32_16x16x32_bf16 v[42:45], v[154:157], v[186:189], v[42:45]
	v_mfma_f32_16x16x32_bf16 v[46:49], v[134:137], v[186:189], v[46:49]
	v_mfma_f32_16x16x32_bf16 v[30:33], v[134:137], v[194:197], v[30:33]
	v_mfma_f32_16x16x32_bf16 v[26:29], v[154:157], v[194:197], v[26:29]
	v_mfma_f32_16x16x32_bf16 v[22:25], v[162:165], v[194:197], v[22:25]
	v_mfma_f32_16x16x32_bf16 v[18:21], v[170:173], v[194:197], v[18:21]
	v_mfma_f32_16x16x32_bf16 v[2:5], v[170:173], v[202:205], v[2:5]
	v_mfma_f32_16x16x32_bf16 v[6:9], v[162:165], v[202:205], v[6:9]
	s_waitcnt lgkmcnt(0)
	v_mfma_f32_16x16x32_bf16 v[10:13], v[154:157], v[202:205], v[10:13]
	v_mfma_f32_16x16x32_bf16 v[14:17], v[134:137], v[202:205], v[14:17]
	s_setprio 0
	s_setprio 1
	v_mfma_f32_16x16x32_bf16 v[62:65], v[150:153], v[182:185], v[62:65]
	v_mfma_f32_16x16x32_bf16 v[58:61], v[158:161], v[182:185], v[58:61]
	v_mfma_f32_16x16x32_bf16 v[54:57], v[166:169], v[182:185], v[54:57]
	v_mfma_f32_16x16x32_bf16 v[50:53], v[174:177], v[182:185], v[50:53]
	v_mfma_f32_16x16x32_bf16 v[34:37], v[174:177], v[190:193], v[34:37]
	v_mfma_f32_16x16x32_bf16 v[38:41], v[166:169], v[190:193], v[38:41]
	v_mfma_f32_16x16x32_bf16 v[42:45], v[158:161], v[190:193], v[42:45]
	v_mfma_f32_16x16x32_bf16 v[46:49], v[150:153], v[190:193], v[46:49]
	v_mfma_f32_16x16x32_bf16 v[30:33], v[150:153], v[198:201], v[30:33]
	v_mfma_f32_16x16x32_bf16 v[26:29], v[158:161], v[198:201], v[26:29]
	v_mfma_f32_16x16x32_bf16 v[22:25], v[166:169], v[198:201], v[22:25]
	v_mfma_f32_16x16x32_bf16 v[18:21], v[174:177], v[198:201], v[18:21]
	v_mfma_f32_16x16x32_bf16 v[2:5], v[174:177], v[252:255], v[2:5]
	v_mfma_f32_16x16x32_bf16 v[6:9], v[166:169], v[252:255], v[6:9]
	v_mfma_f32_16x16x32_bf16 v[10:13], v[158:161], v[252:255], v[10:13]
	s_setprio 2
	s_barrier
	v_mfma_f32_16x16x32_bf16 v[14:17], v[150:153], v[252:255], v[14:17]
	s_setprio 0
	ds_read_b128 v[134:137], v148
	ds_read_b128 v[248:251], v148 offset:1024
	ds_read_b128 v[154:157], v148 offset:2048
	ds_read_b128 v[158:161], v148 offset:3072
	ds_read_b128 v[162:165], v149
	ds_read_b128 v[166:169], v149 offset:1024
	ds_read_b128 v[170:173], v149 offset:2048
	ds_read_b128 v[174:177], v149 offset:3072
	ds_read_b128 v[178:181], v147 offset:32768
	ds_read_b128 v[182:185], v147 offset:33792
	ds_read_b128 v[186:189], v147 offset:34816
	ds_read_b128 v[190:193], v147 offset:35840
	ds_read_b128 v[194:197], v147 offset:36864
	ds_read_b128 v[198:201], v147 offset:37888
	ds_read_b128 v[202:205], v147 offset:38912
	ds_read_b128 v[206:209], v147 offset:39936
	s_add_u32 s36, s44, 0x2b0000
	s_addc_u32 s37, s45, 0
	s_mov_b32 m0, s52
	s_nop 0
	global_load_lds_dwordx4 v1, s[36:37]
	s_nop 0
	s_mov_b32 m0, s53
	s_nop 0
	global_load_lds_dwordx4 v141, s[36:37]
	s_waitcnt vmcnt(8)
	s_waitcnt lgkmcnt(0)
	s_barrier
	s_setprio 1
	s_waitcnt lgkmcnt(7)
	v_mfma_f32_16x16x32_bf16 v[126:129], v[134:137], v[178:181], v[126:129]
	v_mfma_f32_16x16x32_bf16 v[122:125], v[154:157], v[178:181], v[122:125]
	s_waitcnt lgkmcnt(5)
	v_mfma_f32_16x16x32_bf16 v[118:121], v[162:165], v[178:181], v[118:121]
	v_mfma_f32_16x16x32_bf16 v[114:117], v[170:173], v[178:181], v[114:117]
	s_waitcnt lgkmcnt(3)
	v_mfma_f32_16x16x32_bf16 v[98:101], v[170:173], v[186:189], v[98:101]
	v_mfma_f32_16x16x32_bf16 v[102:105], v[162:165], v[186:189], v[102:105]
	s_waitcnt lgkmcnt(1)
	v_mfma_f32_16x16x32_bf16 v[106:109], v[154:157], v[186:189], v[106:109]
	v_mfma_f32_16x16x32_bf16 v[110:113], v[134:137], v[186:189], v[110:113]
	v_mfma_f32_16x16x32_bf16 v[94:97], v[134:137], v[194:197], v[94:97]
	v_mfma_f32_16x16x32_bf16 v[90:93], v[154:157], v[194:197], v[90:93]
	v_mfma_f32_16x16x32_bf16 v[86:89], v[162:165], v[194:197], v[86:89]
	v_mfma_f32_16x16x32_bf16 v[82:85], v[170:173], v[194:197], v[82:85]
	v_mfma_f32_16x16x32_bf16 v[66:69], v[170:173], v[202:205], v[66:69]
	v_mfma_f32_16x16x32_bf16 v[70:73], v[162:165], v[202:205], v[70:73]
	s_waitcnt lgkmcnt(0)
	v_mfma_f32_16x16x32_bf16 v[74:77], v[154:157], v[202:205], v[74:77]
	v_mfma_f32_16x16x32_bf16 v[78:81], v[134:137], v[202:205], v[78:81]
	s_setprio 0
	s_setprio 1
	v_mfma_f32_16x16x32_bf16 v[126:129], v[248:251], v[182:185], v[126:129]
	v_mfma_f32_16x16x32_bf16 v[122:125], v[158:161], v[182:185], v[122:125]
	v_mfma_f32_16x16x32_bf16 v[118:121], v[166:169], v[182:185], v[118:121]
	v_mfma_f32_16x16x32_bf16 v[114:117], v[174:177], v[182:185], v[114:117]
	v_mfma_f32_16x16x32_bf16 v[98:101], v[174:177], v[190:193], v[98:101]
	v_mfma_f32_16x16x32_bf16 v[102:105], v[166:169], v[190:193], v[102:105]
	v_mfma_f32_16x16x32_bf16 v[106:109], v[158:161], v[190:193], v[106:109]
	v_mfma_f32_16x16x32_bf16 v[110:113], v[248:251], v[190:193], v[110:113]
	v_mfma_f32_16x16x32_bf16 v[94:97], v[248:251], v[198:201], v[94:97]
	v_mfma_f32_16x16x32_bf16 v[90:93], v[158:161], v[198:201], v[90:93]
	v_mfma_f32_16x16x32_bf16 v[86:89], v[166:169], v[198:201], v[86:89]
	v_mfma_f32_16x16x32_bf16 v[82:85], v[174:177], v[198:201], v[82:85]
	v_mfma_f32_16x16x32_bf16 v[66:69], v[174:177], v[206:209], v[66:69]
	v_mfma_f32_16x16x32_bf16 v[70:73], v[166:169], v[206:209], v[70:73]
	v_mfma_f32_16x16x32_bf16 v[74:77], v[158:161], v[206:209], v[74:77]
	s_setprio 2
	s_barrier
; #define PG8_STAGE(bufoff, gbase, voff) do { _Pragma("unroll") for (int _i = 0; _i < 2; ++_i) \
;         asm volatile("s_mov_b32 m0, %2\n\ts_nop 0\n\tglobal_load_lds_dwordx4 %0, %1" :: "v"((voff)[_i]), "s"((const char*)(gbase)), "s"(ldsbase + (unsigned)(bufoff) + ldsw + (unsigned)_i * 8192u) : "memory", "m0"); } while (0)
; #define PG8_LDA(dst, b, h) do { _Pragma("unroll") for (int m = 0; m < 4; ++m) _Pragma("unroll") for (int k = 0; k < 2; ++k) dst[m][k] = *(const PG8_LAS bf16x8*)(lds + PG8_SA(b, h) + aoff + m * 2048 + k * 1024); } while (0)
; #define PG8_BAR __builtin_amdgcn_s_barrier()
; template <class Epi, class Sched, bool ALIGN_EPI = false, bool SP2 = false>
; __device__ __forceinline__ void gemm_phase(PG8_LAS unsigned char* lds, const Gemm g, const Sched& S, const Epi& E) {
;     ...
;         for (int t = 0; t < nt; t += 2) {
;             const bool last = (t == nt - 2);
;             const char* a1 = cA + (size_t)(t + 1) * kstep;
;             const char* a2 = last ? nA : cA + (size_t)(t + 2) * kstep; const char* b2 = last ? nB : cB + (size_t)(t + 2) * kstep;
;             const char* a3 = a2 + kstep; const char* b3 = b2 + kstep;
;             if (last && has_next) S.a_ready(nxt);
;             if constexpr (epi_has_mid<Epi>::value) { if (t == Epi::MID_T) E.mid(acc, cur, wr, wc, fr, fq); }
;             if constexpr (SP2) {
;             PG8_LDB(B0, 0, 0); PG8_LDB(B1, 0, 1); PG8_SCHED; PG8_LDA(At, 0, 0); PG8_STAGE(PG8_SA(1, 1), a1 + hstep, voffA);
;             PG8_WAIT_V(8); PG8_WAIT_L(0); PG8_BAR; PG8_MMA(0, 0, At, B0); PG8_MMA(0, 1, At, B1); PG8_BAR; PG8_SCHED;
;             PG8_LDA(At, 0, 1); PG8_STAGE(PG8_SB(0, 0), b2, voffB); PG8_STAGE(PG8_SB(0, 1), b2 + hstep, voffB); PG8_STAGE(PG8_SA(0, 0), a2, voffA);
;             PG8_WAIT_V(8); PG8_WAIT_L(0); PG8_BAR; PG8_MMA(1, 0, At, B0); PG8_MMA(1, 1, At, B1); PG8_BAR; PG8_SCHED;
;             PG8_LDB(B0, 1, 0); PG8_LDB(B1, 1, 1); PG8_SCHED; PG8_LDA(At, 1, 0); PG8_STAGE(PG8_SA(0, 1), a2 + hstep, voffA);
;             PG8_WAIT_V(8); PG8_WAIT_L(0); PG8_BAR; PG8_MMA(0, 0, At, B0); PG8_MMA(0, 1, At, B1); PG8_BAR; PG8_SCHED;
;             PG8_LDA(At, 1, 1); PG8_STAGE(PG8_SB(1, 0), b3, voffB); PG8_STAGE(PG8_SB(1, 1), b3 + hstep, voffB); PG8_STAGE(PG8_SA(1, 0), a3, voffA);
;             PG8_WAIT_V(8); PG8_WAIT_L(0); PG8_BAR; PG8_MMA(1, 0, At, B0); PG8_MMA(1, 1, At, B1); PG8_BAR; PG8_SCHED;
	v_mfma_f32_16x16x32_bf16 v[78:81], v[248:251], v[206:209], v[78:81]
	s_setprio 0
	ds_read_b128 v[178:181], v147 offset:49152
	ds_read_b128 v[182:185], v147 offset:50176
	ds_read_b128 v[186:189], v147 offset:51200
	ds_read_b128 v[190:193], v147 offset:52224
	ds_read_b128 v[194:197], v147 offset:53248
	ds_read_b128 v[198:201], v147 offset:54272
	ds_read_b128 v[202:205], v147 offset:55296
	ds_read_b128 v[252:255], v147 offset:56320
	s_add_u32 s36, s42, 0x80
	s_addc_u32 s37, s43, 0
	s_mov_b32 m0, s54
	s_nop 0
	global_load_lds_dwordx4 v140, s[36:37]
	s_nop 0
	s_mov_b32 m0, s55
	s_nop 0
	global_load_lds_dwordx4 v142, s[36:37]
	s_add_u32 s36, s42, 0x2b0080
	s_addc_u32 s37, s43, 0
	s_mov_b32 m0, s58
	s_nop 0
	global_load_lds_dwordx4 v140, s[36:37]
	s_nop 0
	s_mov_b32 m0, s59
	s_nop 0
	global_load_lds_dwordx4 v142, s[36:37]
	s_nop 0
	s_mov_b32 m0, s56
	s_nop 0
	global_load_lds_dwordx4 v1, s[40:41]
	s_nop 0
	s_mov_b32 m0, s57
	s_nop 0
	global_load_lds_dwordx4 v141, s[40:41]
	s_waitcnt vmcnt(8)
	s_waitcnt lgkmcnt(0)
	s_barrier
	s_setprio 1
	s_waitcnt lgkmcnt(7)
	v_mfma_f32_16x16x32_bf16 v[62:65], v[134:137], v[178:181], v[62:65]
	v_mfma_f32_16x16x32_bf16 v[58:61], v[154:157], v[178:181], v[58:61]
	s_waitcnt lgkmcnt(5)
	v_mfma_f32_16x16x32_bf16 v[54:57], v[162:165], v[178:181], v[54:57]
	v_mfma_f32_16x16x32_bf16 v[50:53], v[170:173], v[178:181], v[50:53]
	s_waitcnt lgkmcnt(3)
	v_mfma_f32_16x16x32_bf16 v[34:37], v[170:173], v[186:189], v[34:37]
	v_mfma_f32_16x16x32_bf16 v[38:41], v[162:165], v[186:189], v[38:41]
	s_waitcnt lgkmcnt(1)
	v_mfma_f32_16x16x32_bf16 v[42:45], v[154:157], v[186:189], v[42:45]
	v_mfma_f32_16x16x32_bf16 v[46:49], v[134:137], v[186:189], v[46:49]
	v_mfma_f32_16x16x32_bf16 v[30:33], v[134:137], v[194:197], v[30:33]
	v_mfma_f32_16x16x32_bf16 v[26:29], v[154:157], v[194:197], v[26:29]
	v_mfma_f32_16x16x32_bf16 v[22:25], v[162:165], v[194:197], v[22:25]
	v_mfma_f32_16x16x32_bf16 v[18:21], v[170:173], v[194:197], v[18:21]
	v_mfma_f32_16x16x32_bf16 v[2:5], v[170:173], v[202:205], v[2:5]
	v_mfma_f32_16x16x32_bf16 v[6:9], v[162:165], v[202:205], v[6:9]
	s_waitcnt lgkmcnt(0)
	v_mfma_f32_16x16x32_bf16 v[10:13], v[154:157], v[202:205], v[10:13]
	v_mfma_f32_16x16x32_bf16 v[14:17], v[134:137], v[202:205], v[14:17]
	s_setprio 0
	s_setprio 1
	v_mfma_f32_16x16x32_bf16 v[62:65], v[248:251], v[182:185], v[62:65]
	v_mfma_f32_16x16x32_bf16 v[58:61], v[158:161], v[182:185], v[58:61]
	v_mfma_f32_16x16x32_bf16 v[54:57], v[166:169], v[182:185], v[54:57]
	v_mfma_f32_16x16x32_bf16 v[50:53], v[174:177], v[182:185], v[50:53]
	v_mfma_f32_16x16x32_bf16 v[34:37], v[174:177], v[190:193], v[34:37]
	v_mfma_f32_16x16x32_bf16 v[38:41], v[166:169], v[190:193], v[38:41]
	v_mfma_f32_16x16x32_bf16 v[42:45], v[158:161], v[190:193], v[42:45]
	v_mfma_f32_16x16x32_bf16 v[46:49], v[248:251], v[190:193], v[46:49]
	v_mfma_f32_16x16x32_bf16 v[30:33], v[248:251], v[198:201], v[30:33]
	v_mfma_f32_16x16x32_bf16 v[26:29], v[158:161], v[198:201], v[26:29]
	v_mfma_f32_16x16x32_bf16 v[22:25], v[166:169], v[198:201], v[22:25]
	v_mfma_f32_16x16x32_bf16 v[18:21], v[174:177], v[198:201], v[18:21]
	v_mfma_f32_16x16x32_bf16 v[2:5], v[174:177], v[252:255], v[2:5]
	v_mfma_f32_16x16x32_bf16 v[6:9], v[166:169], v[252:255], v[6:9]
	v_mfma_f32_16x16x32_bf16 v[10:13], v[158:161], v[252:255], v[10:13]
	s_setprio 2
	s_barrier
	v_mfma_f32_16x16x32_bf16 v[14:17], v[248:251], v[252:255], v[14:17]
	s_setprio 0
	s_add_i32 s69, s69, 2
	s_add_u32 s67, s67, 0x100
	s_addc_u32 s68, s68, 0
	s_cmpk_gt_u32 s69, 0xa9
	s_mov_b64 s[36:37], s[38:39]
	s_cbranch_scc0 .LBB0_873
	s_and_b64 vcc, exec, s[10:11]
	s_cbranch_vccz .LBB0_876
	s_barrier
